# GEMM MFMA order: accumulate chains plus one shared operand between consecutive MFMAs (K-half order alternates per accumulator)
# speedup vs baseline: 1.0136x; 1.0097x over previous
; #define PG8_STAGE(bufoff, gbase, voff) do { _Pragma("unroll") for (int _i = 0; _i < 2; ++_i) \
;         __builtin_amdgcn_global_load_lds((const unsigned*)((const char*)(gbase) + (voff)[_i]), (LAS unsigned*)(lds + (bufoff) + ldsw + _i * 8192), 16, 0, 0); } while (0)
; #define PG8_LDA(dst, b, h) do { _Pragma("unroll") for (int m = 0; m < 4; ++m) _Pragma("unroll") for (int k = 0; k < 2; ++k) dst[m][k] = *(const LAS bf16x8*)(lds + PG8_SA(b, h) + aoff + m * 2048 + k * 1024); } while (0)
; #define PG8_LDB(dst, b, h) do { _Pragma("unroll") for (int n = 0; n < 2; ++n) _Pragma("unroll") for (int k = 0; k < 2; ++k) dst[n][k] = *(const LAS bf16x8*)(lds + PG8_SB(b, h) + boff + n * 2048 + k * 1024); } while (0)
; #define PG8_MMA(ai, bj, At, Bt) do { __builtin_amdgcn_s_setprio(1); _Pragma("unroll") for (int m = 0; m < 4; ++m) _Pragma("unroll") for (int n = 0; n < 2; ++n) _Pragma("unroll") for (int k = 0; k < 2; ++k) \
;         acc[ai][bj][m][n] = __builtin_amdgcn_mfma_f32_16x16x32_bf16(Bt[n][k], At[m][k], acc[ai][bj][m][n], 0, 0, 0); __builtin_amdgcn_s_setprio(0); } while (0)
; #define PG8_WAIT_V(n) asm volatile("s_waitcnt vmcnt(" #n ")" ::: "memory")
; #define PG8_WAIT_L(n) asm volatile("s_waitcnt lgkmcnt(" #n ")" ::: "memory")
; #define PG8_BAR __builtin_amdgcn_s_barrier()
; #define PG8_SCHED __builtin_amdgcn_sched_barrier(0)
;     ...
;             const bool last = (t == nt - 2);
;             const char* a1 = PG8_ATILE(cA, cA2, t + 1);
;             const char* a2 = last ? nA : PG8_ATILE(cA, cA2, t + 2); const char* b2 = last ? nB : cB + (size_t)(t + 2) * 128;
;             const char* a3 = last ? nA + kA1 : PG8_ATILE(cA, cA2, t + 3); const char* b3 = b2 + kB1;
;             if constexpr (SP2) {
;             PG8_LDB(B0, 0, 0); PG8_LDB(B1, 0, 1); PG8_SCHED; PG8_LDA(At, 0, 0); PG8_STAGE(PG8_SA(1, 1), a1 + hA, voffA);
;             PG8_WAIT_V(8); PG8_WAIT_L(0); PG8_BAR; PG8_MMA(0, 0, At, B0); PG8_MMA(0, 1, At, B1); PG8_BAR; PG8_SCHED;
;             PG8_LDA(At, 0, 1); PG8_STAGE(PG8_SB(0, 0), b2, voffB); PG8_STAGE(PG8_SB(0, 1), b2 + hB, voffB); PG8_STAGE(PG8_SA(0, 0), a2, voffA);
;             PG8_WAIT_V(8); PG8_WAIT_L(0); PG8_BAR; PG8_MMA(1, 0, At, B0); PG8_MMA(1, 1, At, B1); PG8_BAR; PG8_SCHED;
.LBB0_96:
	s_and_b64 s[2:3], exec, s[80:81]
	s_cselect_b32 s73, s27, s13
	s_cselect_b32 s72, s26, s9
	s_add_i32 s17, 0, 0x10000
	s_add_i32 s36, 0, 0x14000
	v_add_u32_e32 v132, s17, v182
	v_add_u32_e32 v180, s36, v182
	ds_read_b128 v[16:19], v132
	ds_read_b128 v[24:27], v132 offset:1024
	ds_read_b128 v[120:123], v132 offset:2048
	ds_read_b128 v[132:135], v132 offset:3072
	ds_read_b128 v[140:143], v180
	ds_read_b128 v[148:151], v180 offset:1024
	ds_read_b128 v[176:179], v180 offset:2048
	ds_read_b128 v[184:187], v180 offset:3072
	s_add_u32 s2, s78, 0x10000
	s_addc_u32 s3, s79, 0
	v_lshl_add_u64 v[180:181], s[2:3], 0, v[152:153]
	s_add_i32 m0, s94, 0xc000
	ds_read_b128 v[188:191], v183
	ds_read_b128 v[192:195], v183 offset:1024
	ds_read_b128 v[196:199], v183 offset:2048
	ds_read_b128 v[200:203], v183 offset:3072
	ds_read_b128 v[208:211], v183 offset:4096
	ds_read_b128 v[214:217], v183 offset:5120
	ds_read_b128 v[230:233], v183 offset:6144
	ds_read_b128 v[234:237], v183 offset:7168
	global_load_lds_dwordx4 v[180:181], off
	v_lshl_add_u64 v[180:181], s[2:3], 0, v[154:155]
	s_add_i32 m0, s94, 0xe000
	s_nop 0
	global_load_lds_dwordx4 v[180:181], off
	s_waitcnt vmcnt(8)
	s_waitcnt lgkmcnt(0)
	s_barrier
	s_setprio 1
	s_waitcnt lgkmcnt(0)
	v_mfma_f32_16x16x32_bf16 v[144:147], v[16:19], v[188:191], v[144:147]
	v_mfma_f32_16x16x32_bf16 v[144:147], v[24:27], v[192:195], v[144:147]
	v_mfma_f32_16x16x32_bf16 v[136:139], v[132:135], v[192:195], v[136:139]
	v_mfma_f32_16x16x32_bf16 v[136:139], v[120:123], v[188:191], v[136:139]
	v_mfma_f32_16x16x32_bf16 v[112:115], v[120:123], v[196:199], v[112:115]
	v_mfma_f32_16x16x32_bf16 v[112:115], v[132:135], v[200:203], v[112:115]
	v_mfma_f32_16x16x32_bf16 v[116:119], v[24:27], v[200:203], v[116:119]
	v_mfma_f32_16x16x32_bf16 v[116:119], v[16:19], v[196:199], v[116:119]
	v_mfma_f32_16x16x32_bf16 v[100:103], v[16:19], v[208:211], v[100:103]
	v_mfma_f32_16x16x32_bf16 v[100:103], v[24:27], v[214:217], v[100:103]
	v_mfma_f32_16x16x32_bf16 v[96:99], v[132:135], v[214:217], v[96:99]
	v_mfma_f32_16x16x32_bf16 v[96:99], v[120:123], v[208:211], v[96:99]
	v_mfma_f32_16x16x32_bf16 v[80:83], v[120:123], v[230:233], v[80:83]
	v_mfma_f32_16x16x32_bf16 v[80:83], v[132:135], v[234:237], v[80:83]
	v_mfma_f32_16x16x32_bf16 v[84:87], v[24:27], v[234:237], v[84:87]
	v_mfma_f32_16x16x32_bf16 v[84:87], v[16:19], v[230:233], v[84:87]
	s_setprio 0
	s_setprio 1
	v_mfma_f32_16x16x32_bf16 v[128:131], v[140:143], v[188:191], v[128:131]
	v_mfma_f32_16x16x32_bf16 v[128:131], v[148:151], v[192:195], v[128:131]
	v_mfma_f32_16x16x32_bf16 v[124:127], v[184:187], v[192:195], v[124:127]
	v_mfma_f32_16x16x32_bf16 v[124:127], v[176:179], v[188:191], v[124:127]
	v_mfma_f32_16x16x32_bf16 v[104:107], v[176:179], v[196:199], v[104:107]
	v_mfma_f32_16x16x32_bf16 v[104:107], v[184:187], v[200:203], v[104:107]
	v_mfma_f32_16x16x32_bf16 v[108:111], v[148:151], v[200:203], v[108:111]
	v_mfma_f32_16x16x32_bf16 v[108:111], v[140:143], v[196:199], v[108:111]
	v_mfma_f32_16x16x32_bf16 v[92:95], v[140:143], v[208:211], v[92:95]
	v_mfma_f32_16x16x32_bf16 v[92:95], v[148:151], v[214:217], v[92:95]
	v_mfma_f32_16x16x32_bf16 v[88:91], v[184:187], v[214:217], v[88:91]
	v_mfma_f32_16x16x32_bf16 v[88:91], v[176:179], v[208:211], v[88:91]
	v_mfma_f32_16x16x32_bf16 v[72:75], v[176:179], v[230:233], v[72:75]
	v_mfma_f32_16x16x32_bf16 v[72:75], v[184:187], v[234:237], v[72:75]
	v_mfma_f32_16x16x32_bf16 v[76:79], v[148:151], v[234:237], v[76:79]
	v_mfma_f32_16x16x32_bf16 v[76:79], v[140:143], v[230:233], v[76:79]
	s_setprio 0
	s_barrier
	s_add_i32 s2, s17, s93
	v_lshl_add_u64 v[180:181], s[72:73], 0, v[156:157]
	s_mov_b32 m0, s2
	ds_read_b128 v[188:191], v183 offset:16384
	ds_read_b128 v[192:195], v183 offset:17408
	ds_read_b128 v[196:199], v183 offset:18432
	ds_read_b128 v[200:203], v183 offset:19456
	ds_read_b128 v[208:211], v183 offset:20480
	ds_read_b128 v[214:217], v183 offset:21504
	ds_read_b128 v[230:233], v183 offset:22528
	ds_read_b128 v[234:237], v183 offset:23552
	global_load_lds_dwordx4 v[180:181], off
	s_add_i32 m0, s2, 0x2000
	s_add_u32 s2, s72, 0x18000
	v_lshl_add_u64 v[204:205], s[72:73], 0, v[168:169]
	s_addc_u32 s3, s73, 0
	s_add_i32 s17, s36, s93
	global_load_lds_dwordx4 v[204:205], off
	v_lshl_add_u64 v[206:207], s[2:3], 0, v[156:157]
	s_mov_b32 m0, s17
	s_nop 0
	global_load_lds_dwordx4 v[206:207], off
	v_lshl_add_u64 v[206:207], s[2:3], 0, v[168:169]
	s_add_i32 m0, s17, 0x2000
	s_nop 0
	global_load_lds_dwordx4 v[206:207], off
	v_lshl_add_u64 v[206:207], s[76:77], 0, v[152:153]
	s_mov_b32 m0, s94
	s_nop 0
	global_load_lds_dwordx4 v[206:207], off
	v_lshl_add_u64 v[206:207], s[76:77], 0, v[154:155]
	s_mov_b32 m0, s95
	s_nop 0
	global_load_lds_dwordx4 v[206:207], off
	s_waitcnt vmcnt(8)
	s_waitcnt lgkmcnt(0)
	s_barrier
; #define PG8_STAGE(bufoff, gbase, voff) do { _Pragma("unroll") for (int _i = 0; _i < 2; ++_i) \
;         __builtin_amdgcn_global_load_lds((const unsigned*)((const char*)(gbase) + (voff)[_i]), (LAS unsigned*)(lds + (bufoff) + ldsw + _i * 8192), 16, 0, 0); } while (0)
; #define PG8_LDA(dst, b, h) do { _Pragma("unroll") for (int m = 0; m < 4; ++m) _Pragma("unroll") for (int k = 0; k < 2; ++k) dst[m][k] = *(const LAS bf16x8*)(lds + PG8_SA(b, h) + aoff + m * 2048 + k * 1024); } while (0)
; #define PG8_LDB(dst, b, h) do { _Pragma("unroll") for (int n = 0; n < 2; ++n) _Pragma("unroll") for (int k = 0; k < 2; ++k) dst[n][k] = *(const LAS bf16x8*)(lds + PG8_SB(b, h) + boff + n * 2048 + k * 1024); } while (0)
; #define PG8_MMA(ai, bj, At, Bt) do { __builtin_amdgcn_s_setprio(1); _Pragma("unroll") for (int m = 0; m < 4; ++m) _Pragma("unroll") for (int n = 0; n < 2; ++n) _Pragma("unroll") for (int k = 0; k < 2; ++k) \
;         acc[ai][bj][m][n] = __builtin_amdgcn_mfma_f32_16x16x32_bf16(Bt[n][k], At[m][k], acc[ai][bj][m][n], 0, 0, 0); __builtin_amdgcn_s_setprio(0); } while (0)
; #define PG8_WAIT_V(n) asm volatile("s_waitcnt vmcnt(" #n ")" ::: "memory")
; #define PG8_WAIT_L(n) asm volatile("s_waitcnt lgkmcnt(" #n ")" ::: "memory")
; #define PG8_BAR __builtin_amdgcn_s_barrier()
; #define PG8_SCHED __builtin_amdgcn_sched_barrier(0)
;     ...
;             PG8_WAIT_V(8); PG8_WAIT_L(0); PG8_BAR; PG8_MMA(1, 0, At, B0); PG8_MMA(1, 1, At, B1); PG8_BAR; PG8_SCHED;
;             PG8_LDB(B0, 1, 0); PG8_LDB(B1, 1, 1); PG8_SCHED; PG8_LDA(At, 1, 0); PG8_STAGE(PG8_SA(0, 1), a2 + hA, voffA);
;             PG8_WAIT_V(8); PG8_WAIT_L(0); PG8_BAR; PG8_MMA(0, 0, At, B0); PG8_MMA(0, 1, At, B1); PG8_BAR; PG8_SCHED;
	s_setprio 1
	s_waitcnt lgkmcnt(0)
	v_mfma_f32_16x16x32_bf16 v[68:71], v[16:19], v[188:191], v[68:71]
	v_mfma_f32_16x16x32_bf16 v[68:71], v[24:27], v[192:195], v[68:71]
	v_mfma_f32_16x16x32_bf16 v[64:67], v[132:135], v[192:195], v[64:67]
	v_mfma_f32_16x16x32_bf16 v[64:67], v[120:123], v[188:191], v[64:67]
	v_mfma_f32_16x16x32_bf16 v[48:51], v[120:123], v[196:199], v[48:51]
	v_mfma_f32_16x16x32_bf16 v[48:51], v[132:135], v[200:203], v[48:51]
	v_mfma_f32_16x16x32_bf16 v[52:55], v[24:27], v[200:203], v[52:55]
	v_mfma_f32_16x16x32_bf16 v[52:55], v[16:19], v[196:199], v[52:55]
	v_mfma_f32_16x16x32_bf16 v[36:39], v[16:19], v[208:211], v[36:39]
	v_mfma_f32_16x16x32_bf16 v[36:39], v[24:27], v[214:217], v[36:39]
	v_mfma_f32_16x16x32_bf16 v[32:35], v[132:135], v[214:217], v[32:35]
	v_mfma_f32_16x16x32_bf16 v[32:35], v[120:123], v[208:211], v[32:35]
	v_mfma_f32_16x16x32_bf16 v[8:11], v[120:123], v[230:233], v[8:11]
	v_mfma_f32_16x16x32_bf16 v[8:11], v[132:135], v[234:237], v[8:11]
	v_mfma_f32_16x16x32_bf16 v[12:15], v[24:27], v[234:237], v[12:15]
	v_mfma_f32_16x16x32_bf16 v[12:15], v[16:19], v[230:233], v[12:15]
	s_setprio 0
	s_setprio 1
	v_mfma_f32_16x16x32_bf16 v[44:47], v[140:143], v[196:199], v[44:47]
	v_mfma_f32_16x16x32_bf16 v[44:47], v[148:151], v[200:203], v[44:47]
	v_mfma_f32_16x16x32_bf16 v[40:43], v[176:179], v[196:199], v[40:43]
	v_mfma_f32_16x16x32_bf16 v[40:43], v[184:187], v[200:203], v[40:43]
	v_mfma_f32_16x16x32_bf16 v[28:31], v[140:143], v[208:211], v[28:31]
	v_mfma_f32_16x16x32_bf16 v[28:31], v[148:151], v[214:217], v[28:31]
	v_mfma_f32_16x16x32_bf16 v[20:23], v[176:179], v[208:211], v[20:23]
	v_mfma_f32_16x16x32_bf16 v[20:23], v[184:187], v[214:217], v[20:23]
	v_mfma_f32_16x16x32_bf16 v[4:7], v[140:143], v[230:233], v[4:7]
	v_mfma_f32_16x16x32_bf16 v[4:7], v[148:151], v[234:237], v[4:7]
	v_mfma_f32_16x16x32_bf16 v[0:3], v[176:179], v[230:233], v[0:3]
	v_mfma_f32_16x16x32_bf16 v[0:3], v[184:187], v[234:237], v[0:3]
	v_mfma_f32_16x16x32_bf16 v[16:19], v[140:143], v[188:191], v[60:63]
	v_mfma_f32_16x16x32_bf16 v[16:19], v[148:151], v[192:195], v[16:19]
	v_mfma_f32_16x16x32_bf16 v[24:27], v[176:179], v[188:191], v[56:59]
	v_mfma_f32_16x16x32_bf16 v[24:27], v[184:187], v[192:195], v[24:27]
	s_setprio 0
	s_barrier
	s_add_i32 s17, 0, 0x18000
	s_add_i32 s36, 0, 0x1c000
	v_add_u32_e32 v132, s17, v182
	v_add_u32_e32 v184, s36, v182
	ds_read_b128 v[56:59], v132
	ds_read_b128 v[60:63], v132 offset:1024
	ds_read_b128 v[120:123], v132 offset:2048
	ds_read_b128 v[132:135], v132 offset:3072
	ds_read_b128 v[140:143], v184
	ds_read_b128 v[148:151], v184 offset:1024
	ds_read_b128 v[176:179], v184 offset:2048
	ds_read_b128 v[184:187], v184 offset:3072
	s_add_u32 s2, s76, 0x10000
	s_addc_u32 s3, s77, 0
	s_mov_b32 m0, s44
	v_lshl_add_u64 v[206:207], s[2:3], 0, v[152:153]
	ds_read_b128 v[188:191], v183 offset:32768
	ds_read_b128 v[192:195], v183 offset:33792
	ds_read_b128 v[196:199], v183 offset:34816
	ds_read_b128 v[200:203], v183 offset:35840
	ds_read_b128 v[208:211], v183 offset:36864
	ds_read_b128 v[214:217], v183 offset:37888
	ds_read_b128 v[230:233], v183 offset:38912
	ds_read_b128 v[234:237], v183 offset:39936
	global_load_lds_dwordx4 v[206:207], off
	v_lshl_add_u64 v[206:207], s[2:3], 0, v[154:155]
	s_mov_b32 m0, s45
	s_nop 0
	global_load_lds_dwordx4 v[206:207], off
	s_waitcnt vmcnt(8)
	s_waitcnt lgkmcnt(0)
	s_barrier
	s_setprio 1
	s_waitcnt lgkmcnt(0)
	v_mfma_f32_16x16x32_bf16 v[144:147], v[56:59], v[188:191], v[144:147]
	v_mfma_f32_16x16x32_bf16 v[144:147], v[60:63], v[192:195], v[144:147]
	v_mfma_f32_16x16x32_bf16 v[136:139], v[132:135], v[192:195], v[136:139]
	v_mfma_f32_16x16x32_bf16 v[136:139], v[120:123], v[188:191], v[136:139]
	v_mfma_f32_16x16x32_bf16 v[112:115], v[120:123], v[196:199], v[112:115]
	v_mfma_f32_16x16x32_bf16 v[112:115], v[132:135], v[200:203], v[112:115]
	v_mfma_f32_16x16x32_bf16 v[116:119], v[60:63], v[200:203], v[116:119]
	v_mfma_f32_16x16x32_bf16 v[116:119], v[56:59], v[196:199], v[116:119]
	v_mfma_f32_16x16x32_bf16 v[100:103], v[56:59], v[208:211], v[100:103]
	v_mfma_f32_16x16x32_bf16 v[100:103], v[60:63], v[214:217], v[100:103]
	v_mfma_f32_16x16x32_bf16 v[96:99], v[132:135], v[214:217], v[96:99]
	v_mfma_f32_16x16x32_bf16 v[96:99], v[120:123], v[208:211], v[96:99]
	v_mfma_f32_16x16x32_bf16 v[80:83], v[120:123], v[230:233], v[80:83]
	v_mfma_f32_16x16x32_bf16 v[80:83], v[132:135], v[234:237], v[80:83]
	v_mfma_f32_16x16x32_bf16 v[84:87], v[60:63], v[234:237], v[84:87]
	v_mfma_f32_16x16x32_bf16 v[84:87], v[56:59], v[230:233], v[84:87]
	s_setprio 0
	s_setprio 1
	v_mfma_f32_16x16x32_bf16 v[128:131], v[140:143], v[188:191], v[128:131]
	v_mfma_f32_16x16x32_bf16 v[128:131], v[148:151], v[192:195], v[128:131]
	v_mfma_f32_16x16x32_bf16 v[124:127], v[184:187], v[192:195], v[124:127]
	v_mfma_f32_16x16x32_bf16 v[124:127], v[176:179], v[188:191], v[124:127]
	v_mfma_f32_16x16x32_bf16 v[104:107], v[176:179], v[196:199], v[104:107]
	v_mfma_f32_16x16x32_bf16 v[104:107], v[184:187], v[200:203], v[104:107]
	v_mfma_f32_16x16x32_bf16 v[108:111], v[148:151], v[200:203], v[108:111]
	v_mfma_f32_16x16x32_bf16 v[108:111], v[140:143], v[196:199], v[108:111]
	v_mfma_f32_16x16x32_bf16 v[92:95], v[140:143], v[208:211], v[92:95]
	v_mfma_f32_16x16x32_bf16 v[92:95], v[148:151], v[214:217], v[92:95]
	v_mfma_f32_16x16x32_bf16 v[88:91], v[184:187], v[214:217], v[88:91]
	v_mfma_f32_16x16x32_bf16 v[88:91], v[176:179], v[208:211], v[88:91]
	v_mfma_f32_16x16x32_bf16 v[72:75], v[176:179], v[230:233], v[72:75]
	v_mfma_f32_16x16x32_bf16 v[72:75], v[184:187], v[234:237], v[72:75]
	v_mfma_f32_16x16x32_bf16 v[76:79], v[148:151], v[234:237], v[76:79]
	v_mfma_f32_16x16x32_bf16 v[76:79], v[140:143], v[230:233], v[76:79]
	s_setprio 0
	s_barrier
; #define PG8_STAGE(bufoff, gbase, voff) do { _Pragma("unroll") for (int _i = 0; _i < 2; ++_i) \
;         __builtin_amdgcn_global_load_lds((const unsigned*)((const char*)(gbase) + (voff)[_i]), (LAS unsigned*)(lds + (bufoff) + ldsw + _i * 8192), 16, 0, 0); } while (0)
; #define PG8_LDA(dst, b, h) do { _Pragma("unroll") for (int m = 0; m < 4; ++m) _Pragma("unroll") for (int k = 0; k < 2; ++k) dst[m][k] = *(const LAS bf16x8*)(lds + PG8_SA(b, h) + aoff + m * 2048 + k * 1024); } while (0)
; #define PG8_MMA(ai, bj, At, Bt) do { __builtin_amdgcn_s_setprio(1); _Pragma("unroll") for (int m = 0; m < 4; ++m) _Pragma("unroll") for (int n = 0; n < 2; ++n) _Pragma("unroll") for (int k = 0; k < 2; ++k) \
;         acc[ai][bj][m][n] = __builtin_amdgcn_mfma_f32_16x16x32_bf16(Bt[n][k], At[m][k], acc[ai][bj][m][n], 0, 0, 0); __builtin_amdgcn_s_setprio(0); } while (0)
; #define PG8_WAIT_V(n) asm volatile("s_waitcnt vmcnt(" #n ")" ::: "memory")
; #define PG8_WAIT_L(n) asm volatile("s_waitcnt lgkmcnt(" #n ")" ::: "memory")
; #define PG8_BAR __builtin_amdgcn_s_barrier()
; #define PG8_SCHED __builtin_amdgcn_sched_barrier(0)
;     ...
;             PG8_LDA(At, 1, 1); PG8_STAGE(PG8_SB(1, 0), b3, voffB); PG8_STAGE(PG8_SB(1, 1), b3 + hB, voffB); PG8_STAGE(PG8_SA(1, 0), a3, voffA);
;             PG8_WAIT_V(8); PG8_WAIT_L(0); PG8_BAR; PG8_MMA(1, 0, At, B0); PG8_MMA(1, 1, At, B1); PG8_BAR; PG8_SCHED;
	s_add_i32 s2, s17, s93
	v_lshl_add_u64 v[180:181], v[180:181], 0, s[38:39]
	s_mov_b32 m0, s2
	ds_read_b128 v[188:191], v183 offset:49152
	ds_read_b128 v[192:195], v183 offset:50176
	ds_read_b128 v[196:199], v183 offset:51200
	ds_read_b128 v[200:203], v183 offset:52224
	ds_read_b128 v[208:211], v183 offset:53248
	ds_read_b128 v[214:217], v183 offset:54272
	ds_read_b128 v[230:233], v183 offset:55296
	ds_read_b128 v[234:237], v183 offset:56320
	global_load_lds_dwordx4 v[180:181], off
	s_add_i32 m0, s2, 0x2000
	s_add_u32 s2, s72, 0x18080
	v_lshl_add_u64 v[180:181], v[204:205], 0, s[38:39]
	s_addc_u32 s3, s73, 0
	s_add_i32 s17, s36, s93
	global_load_lds_dwordx4 v[180:181], off
	v_lshl_add_u64 v[180:181], s[2:3], 0, v[156:157]
	s_mov_b32 m0, s17
	s_nop 0
	global_load_lds_dwordx4 v[180:181], off
	v_lshl_add_u64 v[180:181], s[2:3], 0, v[168:169]
	s_add_i32 m0, s17, 0x2000
	s_nop 0
	global_load_lds_dwordx4 v[180:181], off
	v_lshl_add_u64 v[180:181], s[74:75], 0, v[152:153]
	s_mov_b32 m0, s51
	s_nop 0
	global_load_lds_dwordx4 v[180:181], off
	v_lshl_add_u64 v[180:181], s[74:75], 0, v[154:155]
	s_mov_b32 m0, s50
	s_nop 0
	global_load_lds_dwordx4 v[180:181], off
	s_waitcnt vmcnt(8)
	s_waitcnt lgkmcnt(0)
	s_barrier
	s_setprio 1
	s_waitcnt lgkmcnt(0)
	v_mfma_f32_16x16x32_bf16 v[68:71], v[56:59], v[188:191], v[68:71]
	v_mfma_f32_16x16x32_bf16 v[68:71], v[60:63], v[192:195], v[68:71]
	v_mfma_f32_16x16x32_bf16 v[64:67], v[132:135], v[192:195], v[64:67]
	v_mfma_f32_16x16x32_bf16 v[64:67], v[120:123], v[188:191], v[64:67]
	v_mfma_f32_16x16x32_bf16 v[48:51], v[120:123], v[196:199], v[48:51]
	v_mfma_f32_16x16x32_bf16 v[48:51], v[132:135], v[200:203], v[48:51]
	v_mfma_f32_16x16x32_bf16 v[52:55], v[60:63], v[200:203], v[52:55]
	v_mfma_f32_16x16x32_bf16 v[52:55], v[56:59], v[196:199], v[52:55]
	v_mfma_f32_16x16x32_bf16 v[36:39], v[56:59], v[208:211], v[36:39]
	v_mfma_f32_16x16x32_bf16 v[36:39], v[60:63], v[214:217], v[36:39]
	v_mfma_f32_16x16x32_bf16 v[32:35], v[132:135], v[214:217], v[32:35]
	v_mfma_f32_16x16x32_bf16 v[32:35], v[120:123], v[208:211], v[32:35]
	v_mfma_f32_16x16x32_bf16 v[8:11], v[120:123], v[230:233], v[8:11]
	v_mfma_f32_16x16x32_bf16 v[8:11], v[132:135], v[234:237], v[8:11]
	v_mfma_f32_16x16x32_bf16 v[12:15], v[60:63], v[234:237], v[12:15]
	v_mfma_f32_16x16x32_bf16 v[12:15], v[56:59], v[230:233], v[12:15]
	s_setprio 0
	s_setprio 1
	v_mfma_f32_16x16x32_bf16 v[16:19], v[140:143], v[188:191], v[16:19]
	v_mfma_f32_16x16x32_bf16 v[60:63], v[148:151], v[192:195], v[16:19]
	v_mfma_f32_16x16x32_bf16 v[16:19], v[176:179], v[188:191], v[24:27]
	v_mfma_f32_16x16x32_bf16 v[56:59], v[184:187], v[192:195], v[16:19]
	v_mfma_f32_16x16x32_bf16 v[16:19], v[140:143], v[196:199], v[44:47]
	v_mfma_f32_16x16x32_bf16 v[44:47], v[148:151], v[200:203], v[16:19]
	v_mfma_f32_16x16x32_bf16 v[16:19], v[176:179], v[196:199], v[40:43]
	v_mfma_f32_16x16x32_bf16 v[40:43], v[184:187], v[200:203], v[16:19]
	v_mfma_f32_16x16x32_bf16 v[16:19], v[140:143], v[208:211], v[28:31]
	v_mfma_f32_16x16x32_bf16 v[28:31], v[148:151], v[214:217], v[16:19]
	v_mfma_f32_16x16x32_bf16 v[16:19], v[176:179], v[208:211], v[20:23]
	v_mfma_f32_16x16x32_bf16 v[4:7], v[140:143], v[230:233], v[4:7]
	v_mfma_f32_16x16x32_bf16 v[0:3], v[176:179], v[230:233], v[0:3]
	v_mfma_f32_16x16x32_bf16 v[20:23], v[184:187], v[214:217], v[16:19]
	v_mfma_f32_16x16x32_bf16 v[4:7], v[148:151], v[234:237], v[4:7]
	v_mfma_f32_16x16x32_bf16 v[0:3], v[184:187], v[234:237], v[0:3]
	s_setprio 0
	s_barrier
	s_add_u32 s90, s90, 0x100
	s_addc_u32 s91, s91, 0
	s_add_u32 s9, s9, 0x100
	s_addc_u32 s13, s13, 0
	s_cmp_gt_u32 s15, 3
	s_mov_b32 s72, s15
	s_cbranch_scc1 .LBB0_103

; #define PG8_STAGE(bufoff, gbase, voff) do { _Pragma("unroll") for (int _i = 0; _i < 2; ++_i) \
;         __builtin_amdgcn_global_load_lds((const unsigned*)((const char*)(gbase) + (voff)[_i]), (LAS unsigned*)(lds + (bufoff) + ldsw + _i * 8192), 16, 0, 0); } while (0)
; #define PG8_LDA(dst, b, h) do { _Pragma("unroll") for (int m = 0; m < 4; ++m) _Pragma("unroll") for (int k = 0; k < 2; ++k) dst[m][k] = *(const LAS bf16x8*)(lds + PG8_SA(b, h) + aoff + m * 2048 + k * 1024); } while (0)
; #define PG8_LDB(dst, b, h) do { _Pragma("unroll") for (int n = 0; n < 2; ++n) _Pragma("unroll") for (int k = 0; k < 2; ++k) dst[n][k] = *(const LAS bf16x8*)(lds + PG8_SB(b, h) + boff + n * 2048 + k * 1024); } while (0)
; #define PG8_MMA(ai, bj, At, Bt) do { __builtin_amdgcn_s_setprio(1); _Pragma("unroll") for (int m = 0; m < 4; ++m) _Pragma("unroll") for (int n = 0; n < 2; ++n) _Pragma("unroll") for (int k = 0; k < 2; ++k) \
;         acc[ai][bj][m][n] = __builtin_amdgcn_mfma_f32_16x16x32_bf16(Bt[n][k], At[m][k], acc[ai][bj][m][n], 0, 0, 0); __builtin_amdgcn_s_setprio(0); } while (0)
; #define PG8_WAIT_V(n) asm volatile("s_waitcnt vmcnt(" #n ")" ::: "memory")
; #define PG8_WAIT_L(n) asm volatile("s_waitcnt lgkmcnt(" #n ")" ::: "memory")
; #define PG8_BAR __builtin_amdgcn_s_barrier()
; #define PG8_SCHED __builtin_amdgcn_sched_barrier(0)
;     ...
;             const bool last = (t == nt - 2);
;             const char* a1 = PG8_ATILE(cA, cA2, t + 1);
;             const char* a2 = last ? nA : PG8_ATILE(cA, cA2, t + 2); const char* b2 = last ? nB : cB + (size_t)(t + 2) * 128;
;             const char* a3 = last ? nA + kA1 : PG8_ATILE(cA, cA2, t + 3); const char* b3 = b2 + kB1;
;             if constexpr (SP2) {
;             PG8_LDB(B0, 0, 0); PG8_LDB(B1, 0, 1); PG8_SCHED; PG8_LDA(At, 0, 0); PG8_STAGE(PG8_SA(1, 1), a1 + hA, voffA);
;             PG8_WAIT_V(8); PG8_WAIT_L(0); PG8_BAR; PG8_MMA(0, 0, At, B0); PG8_MMA(0, 1, At, B1); PG8_BAR; PG8_SCHED;
;             PG8_LDA(At, 0, 1); PG8_STAGE(PG8_SB(0, 0), b2, voffB); PG8_STAGE(PG8_SB(0, 1), b2 + hB, voffB); PG8_STAGE(PG8_SA(0, 0), a2, voffA);
;             PG8_WAIT_V(8); PG8_WAIT_L(0); PG8_BAR; PG8_MMA(1, 0, At, B0); PG8_MMA(1, 1, At, B1); PG8_BAR; PG8_SCHED;
.LBB0_119:
	s_add_u32 s2, s52, s94
	s_addc_u32 s3, s53, s95
	s_add_u32 s76, s2, 0x100
	s_addc_u32 s77, s3, 0
	s_add_u32 s74, s80, s94
	s_addc_u32 s75, s81, s95
	s_add_u32 s2, s2, 0x180
	s_addc_u32 s3, s3, 0
	s_add_i32 vcc_hi, 0, 0x10000
	s_add_i32 s12, 0, 0x14000
	v_add_u32_e32 v155, vcc_hi, v153
	ds_read_b128 v[168:171], v155
	ds_read_b128 v[172:175], v155 offset:1024
	ds_read_b128 v[176:179], v155 offset:2048
	ds_read_b128 v[180:183], v155 offset:3072
	v_add_u32_e32 v155, s12, v153
	ds_read_b128 v[184:187], v155
	ds_read_b128 v[188:191], v155 offset:1024
	ds_read_b128 v[192:195], v155 offset:2048
	ds_read_b128 v[196:199], v155 offset:3072
	s_cmpk_eq_i32 s94, 0x300
	s_cselect_b32 s73, s97, s3
	s_cselect_b32 s72, s96, s2
	s_cselect_b32 s75, s82, s75
	s_cselect_b32 s74, s91, s74
	s_cselect_b32 s77, s83, s77
	s_cselect_b32 s76, s89, s76
	v_lshl_add_u64 v[204:205], v[142:143], 0, s[94:95]
	s_add_i32 m0, s1, 0xc000
	ds_read_b128 v[208:211], v154
	ds_read_b128 v[214:217], v154 offset:1024
	ds_read_b128 v[230:233], v154 offset:2048
	ds_read_b128 v[234:237], v154 offset:3072
	ds_read_b128 v[238:241], v154 offset:4096
	ds_read_b128 v[242:245], v154 offset:5120
	ds_read_b128 v[246:249], v154 offset:6144
	ds_read_b128 v[200:203], v154 offset:7168
	global_load_lds_dwordx4 v[204:205], off
	v_lshl_add_u64 v[204:205], v[144:145], 0, s[94:95]
	s_add_i32 m0, s1, 0xe000
	s_nop 0
	global_load_lds_dwordx4 v[204:205], off
	s_waitcnt vmcnt(8)
	s_waitcnt lgkmcnt(0)
	s_barrier
	s_setprio 1
	s_waitcnt lgkmcnt(0)
	v_mfma_f32_16x16x32_bf16 v[124:127], v[168:171], v[208:211], v[124:127]
	v_mfma_f32_16x16x32_bf16 v[124:127], v[172:175], v[214:217], v[124:127]
	v_mfma_f32_16x16x32_bf16 v[120:123], v[180:183], v[214:217], v[120:123]
	v_mfma_f32_16x16x32_bf16 v[120:123], v[176:179], v[208:211], v[120:123]
	v_mfma_f32_16x16x32_bf16 v[112:115], v[176:179], v[230:233], v[112:115]
	v_mfma_f32_16x16x32_bf16 v[112:115], v[180:183], v[234:237], v[112:115]
	v_mfma_f32_16x16x32_bf16 v[116:119], v[172:175], v[234:237], v[116:119]
	v_mfma_f32_16x16x32_bf16 v[116:119], v[168:171], v[230:233], v[116:119]
	v_mfma_f32_16x16x32_bf16 v[108:111], v[168:171], v[238:241], v[108:111]
	v_mfma_f32_16x16x32_bf16 v[108:111], v[172:175], v[242:245], v[108:111]
	v_mfma_f32_16x16x32_bf16 v[100:103], v[180:183], v[242:245], v[100:103]
	v_mfma_f32_16x16x32_bf16 v[100:103], v[176:179], v[238:241], v[100:103]
	v_mfma_f32_16x16x32_bf16 v[84:87], v[176:179], v[246:249], v[84:87]
	v_mfma_f32_16x16x32_bf16 v[84:87], v[180:183], v[200:203], v[84:87]
	v_mfma_f32_16x16x32_bf16 v[92:95], v[172:175], v[200:203], v[92:95]
	v_mfma_f32_16x16x32_bf16 v[92:95], v[168:171], v[246:249], v[92:95]
	s_setprio 0
	s_setprio 1
	v_mfma_f32_16x16x32_bf16 v[104:107], v[184:187], v[208:211], v[104:107]
	v_mfma_f32_16x16x32_bf16 v[104:107], v[188:191], v[214:217], v[104:107]
	v_mfma_f32_16x16x32_bf16 v[96:99], v[196:199], v[214:217], v[96:99]
	v_mfma_f32_16x16x32_bf16 v[96:99], v[192:195], v[208:211], v[96:99]
	v_mfma_f32_16x16x32_bf16 v[80:83], v[192:195], v[230:233], v[80:83]
	v_mfma_f32_16x16x32_bf16 v[80:83], v[196:199], v[234:237], v[80:83]
	v_mfma_f32_16x16x32_bf16 v[88:91], v[188:191], v[234:237], v[88:91]
	v_mfma_f32_16x16x32_bf16 v[88:91], v[184:187], v[230:233], v[88:91]
	v_mfma_f32_16x16x32_bf16 v[76:79], v[184:187], v[238:241], v[76:79]
	v_mfma_f32_16x16x32_bf16 v[76:79], v[188:191], v[242:245], v[76:79]
	v_mfma_f32_16x16x32_bf16 v[72:75], v[196:199], v[242:245], v[72:75]
	v_mfma_f32_16x16x32_bf16 v[72:75], v[192:195], v[238:241], v[72:75]
	v_mfma_f32_16x16x32_bf16 v[64:67], v[192:195], v[246:249], v[64:67]
	v_mfma_f32_16x16x32_bf16 v[64:67], v[196:199], v[200:203], v[64:67]
	v_mfma_f32_16x16x32_bf16 v[68:71], v[188:191], v[200:203], v[68:71]
	v_mfma_f32_16x16x32_bf16 v[68:71], v[184:187], v[246:249], v[68:71]
	s_setprio 0
	s_barrier
	s_add_i32 s2, vcc_hi, s0
	v_lshl_add_u64 v[204:205], s[74:75], 0, v[130:131]
	s_mov_b32 m0, s2
	ds_read_b128 v[200:203], v154 offset:16384
	ds_read_b128 v[208:211], v154 offset:17408
	ds_read_b128 v[214:217], v154 offset:18432
	ds_read_b128 v[230:233], v154 offset:19456
	ds_read_b128 v[234:237], v154 offset:20480
	ds_read_b128 v[238:241], v154 offset:21504
	ds_read_b128 v[242:245], v154 offset:22528
	ds_read_b128 v[246:249], v154 offset:23552
	global_load_lds_dwordx4 v[204:205], off
	s_add_i32 m0, s2, 0x2000
	s_add_u32 s2, s74, 0x20000
	v_lshl_add_u64 v[206:207], s[74:75], 0, v[134:135]
	s_addc_u32 s3, s75, 0
	s_add_i32 s12, s12, s0
	global_load_lds_dwordx4 v[206:207], off
	v_lshl_add_u64 v[250:251], s[2:3], 0, v[130:131]
	s_mov_b32 m0, s12
	s_nop 0
	global_load_lds_dwordx4 v[250:251], off
	v_lshl_add_u64 v[250:251], s[2:3], 0, v[134:135]
	s_add_i32 m0, s12, 0x2000
	s_nop 0
	global_load_lds_dwordx4 v[250:251], off
	v_lshl_add_u64 v[250:251], s[76:77], 0, v[128:129]
	s_mov_b32 m0, s1
	s_nop 0
	global_load_lds_dwordx4 v[250:251], off
	v_lshl_add_u64 v[250:251], s[76:77], 0, v[132:133]
	s_mov_b32 m0, s4
	s_nop 0
	global_load_lds_dwordx4 v[250:251], off
	s_waitcnt vmcnt(8)
	s_waitcnt lgkmcnt(0)
	s_barrier
; #define PG8_STAGE(bufoff, gbase, voff) do { _Pragma("unroll") for (int _i = 0; _i < 2; ++_i) \
;         __builtin_amdgcn_global_load_lds((const unsigned*)((const char*)(gbase) + (voff)[_i]), (LAS unsigned*)(lds + (bufoff) + ldsw + _i * 8192), 16, 0, 0); } while (0)
; #define PG8_LDA(dst, b, h) do { _Pragma("unroll") for (int m = 0; m < 4; ++m) _Pragma("unroll") for (int k = 0; k < 2; ++k) dst[m][k] = *(const LAS bf16x8*)(lds + PG8_SA(b, h) + aoff + m * 2048 + k * 1024); } while (0)
; #define PG8_LDB(dst, b, h) do { _Pragma("unroll") for (int n = 0; n < 2; ++n) _Pragma("unroll") for (int k = 0; k < 2; ++k) dst[n][k] = *(const LAS bf16x8*)(lds + PG8_SB(b, h) + boff + n * 2048 + k * 1024); } while (0)
; #define PG8_MMA(ai, bj, At, Bt) do { __builtin_amdgcn_s_setprio(1); _Pragma("unroll") for (int m = 0; m < 4; ++m) _Pragma("unroll") for (int n = 0; n < 2; ++n) _Pragma("unroll") for (int k = 0; k < 2; ++k) \
;         acc[ai][bj][m][n] = __builtin_amdgcn_mfma_f32_16x16x32_bf16(Bt[n][k], At[m][k], acc[ai][bj][m][n], 0, 0, 0); __builtin_amdgcn_s_setprio(0); } while (0)
; #define PG8_WAIT_V(n) asm volatile("s_waitcnt vmcnt(" #n ")" ::: "memory")
; #define PG8_WAIT_L(n) asm volatile("s_waitcnt lgkmcnt(" #n ")" ::: "memory")
; #define PG8_BAR __builtin_amdgcn_s_barrier()
; #define PG8_SCHED __builtin_amdgcn_sched_barrier(0)
;     ...
;             PG8_WAIT_V(8); PG8_WAIT_L(0); PG8_BAR; PG8_MMA(1, 0, At, B0); PG8_MMA(1, 1, At, B1); PG8_BAR; PG8_SCHED;
;             PG8_LDB(B0, 1, 0); PG8_LDB(B1, 1, 1); PG8_SCHED; PG8_LDA(At, 1, 0); PG8_STAGE(PG8_SA(0, 1), a2 + hA, voffA);
;             PG8_WAIT_V(8); PG8_WAIT_L(0); PG8_BAR; PG8_MMA(0, 0, At, B0); PG8_MMA(0, 1, At, B1); PG8_BAR; PG8_SCHED;
	s_setprio 1
	s_waitcnt lgkmcnt(0)
	v_mfma_f32_16x16x32_bf16 v[60:63], v[168:171], v[200:203], v[60:63]
	v_mfma_f32_16x16x32_bf16 v[60:63], v[172:175], v[208:211], v[60:63]
	v_mfma_f32_16x16x32_bf16 v[56:59], v[180:183], v[208:211], v[56:59]
	v_mfma_f32_16x16x32_bf16 v[56:59], v[176:179], v[200:203], v[56:59]
	v_mfma_f32_16x16x32_bf16 v[48:51], v[176:179], v[214:217], v[48:51]
	v_mfma_f32_16x16x32_bf16 v[48:51], v[180:183], v[230:233], v[48:51]
	v_mfma_f32_16x16x32_bf16 v[52:55], v[172:175], v[230:233], v[52:55]
	v_mfma_f32_16x16x32_bf16 v[52:55], v[168:171], v[214:217], v[52:55]
	v_mfma_f32_16x16x32_bf16 v[44:47], v[168:171], v[234:237], v[44:47]
	v_mfma_f32_16x16x32_bf16 v[44:47], v[172:175], v[238:241], v[44:47]
	v_mfma_f32_16x16x32_bf16 v[36:39], v[180:183], v[238:241], v[36:39]
	v_mfma_f32_16x16x32_bf16 v[36:39], v[176:179], v[234:237], v[36:39]
	v_mfma_f32_16x16x32_bf16 v[20:23], v[176:179], v[242:245], v[20:23]
	v_mfma_f32_16x16x32_bf16 v[20:23], v[180:183], v[246:249], v[20:23]
	v_mfma_f32_16x16x32_bf16 v[28:31], v[172:175], v[246:249], v[28:31]
	v_mfma_f32_16x16x32_bf16 v[28:31], v[168:171], v[242:245], v[28:31]
	s_setprio 0
	s_setprio 1
	v_mfma_f32_16x16x32_bf16 v[40:43], v[184:187], v[200:203], v[40:43]
	v_mfma_f32_16x16x32_bf16 v[40:43], v[188:191], v[208:211], v[40:43]
	v_mfma_f32_16x16x32_bf16 v[32:35], v[196:199], v[208:211], v[32:35]
	v_mfma_f32_16x16x32_bf16 v[32:35], v[192:195], v[200:203], v[32:35]
	v_mfma_f32_16x16x32_bf16 v[16:19], v[192:195], v[214:217], v[16:19]
	v_mfma_f32_16x16x32_bf16 v[16:19], v[196:199], v[230:233], v[16:19]
	v_mfma_f32_16x16x32_bf16 v[24:27], v[188:191], v[230:233], v[24:27]
	v_mfma_f32_16x16x32_bf16 v[24:27], v[184:187], v[214:217], v[24:27]
	v_mfma_f32_16x16x32_bf16 v[12:15], v[184:187], v[234:237], v[12:15]
	v_mfma_f32_16x16x32_bf16 v[12:15], v[188:191], v[238:241], v[12:15]
	v_mfma_f32_16x16x32_bf16 v[8:11], v[196:199], v[238:241], v[8:11]
	v_mfma_f32_16x16x32_bf16 v[8:11], v[192:195], v[234:237], v[8:11]
	v_mfma_f32_16x16x32_bf16 v[0:3], v[192:195], v[242:245], v[0:3]
	v_mfma_f32_16x16x32_bf16 v[0:3], v[196:199], v[246:249], v[0:3]
	v_mfma_f32_16x16x32_bf16 v[4:7], v[188:191], v[246:249], v[4:7]
	v_mfma_f32_16x16x32_bf16 v[4:7], v[184:187], v[242:245], v[4:7]
	s_setprio 0
	s_barrier
	s_add_i32 s12, 0, 0x18000
	v_add_u32_e32 v155, s12, v153
	s_add_i32 s13, 0, 0x1c000
	ds_read_b128 v[168:171], v155
	ds_read_b128 v[172:175], v155 offset:1024
	ds_read_b128 v[176:179], v155 offset:2048
	ds_read_b128 v[180:183], v155 offset:3072
	v_add_u32_e32 v155, s13, v153
	ds_read_b128 v[184:187], v155
	ds_read_b128 v[188:191], v155 offset:1024
	ds_read_b128 v[192:195], v155 offset:2048
	ds_read_b128 v[196:199], v155 offset:3072
	s_add_u32 s2, s76, 0x20000
	s_addc_u32 s3, s77, 0
	s_mov_b32 m0, s5
	v_lshl_add_u64 v[250:251], s[2:3], 0, v[128:129]
	ds_read_b128 v[200:203], v154 offset:32768
	ds_read_b128 v[208:211], v154 offset:33792
	ds_read_b128 v[214:217], v154 offset:34816
	ds_read_b128 v[230:233], v154 offset:35840
	ds_read_b128 v[234:237], v154 offset:36864
	ds_read_b128 v[238:241], v154 offset:37888
	ds_read_b128 v[242:245], v154 offset:38912
	ds_read_b128 v[246:249], v154 offset:39936
	global_load_lds_dwordx4 v[250:251], off
	v_lshl_add_u64 v[250:251], s[2:3], 0, v[132:133]
	s_mov_b32 m0, s6
	s_nop 0
	global_load_lds_dwordx4 v[250:251], off
	s_waitcnt vmcnt(8)
	s_waitcnt lgkmcnt(0)
	s_barrier
	s_setprio 1
	s_waitcnt lgkmcnt(0)
	v_mfma_f32_16x16x32_bf16 v[124:127], v[168:171], v[200:203], v[124:127]
	v_mfma_f32_16x16x32_bf16 v[124:127], v[172:175], v[208:211], v[124:127]
	v_mfma_f32_16x16x32_bf16 v[120:123], v[180:183], v[208:211], v[120:123]
	v_mfma_f32_16x16x32_bf16 v[120:123], v[176:179], v[200:203], v[120:123]
	v_mfma_f32_16x16x32_bf16 v[112:115], v[176:179], v[214:217], v[112:115]
	v_mfma_f32_16x16x32_bf16 v[112:115], v[180:183], v[230:233], v[112:115]
	v_mfma_f32_16x16x32_bf16 v[116:119], v[172:175], v[230:233], v[116:119]
	v_mfma_f32_16x16x32_bf16 v[116:119], v[168:171], v[214:217], v[116:119]
	v_mfma_f32_16x16x32_bf16 v[108:111], v[168:171], v[234:237], v[108:111]
	v_mfma_f32_16x16x32_bf16 v[108:111], v[172:175], v[238:241], v[108:111]
	v_mfma_f32_16x16x32_bf16 v[100:103], v[180:183], v[238:241], v[100:103]
	v_mfma_f32_16x16x32_bf16 v[100:103], v[176:179], v[234:237], v[100:103]
	v_mfma_f32_16x16x32_bf16 v[84:87], v[176:179], v[242:245], v[84:87]
	v_mfma_f32_16x16x32_bf16 v[84:87], v[180:183], v[246:249], v[84:87]
	v_mfma_f32_16x16x32_bf16 v[92:95], v[172:175], v[246:249], v[92:95]
	v_mfma_f32_16x16x32_bf16 v[92:95], v[168:171], v[242:245], v[92:95]
	s_setprio 0
	s_setprio 1
	v_mfma_f32_16x16x32_bf16 v[104:107], v[184:187], v[200:203], v[104:107]
	v_mfma_f32_16x16x32_bf16 v[104:107], v[188:191], v[208:211], v[104:107]
	v_mfma_f32_16x16x32_bf16 v[96:99], v[196:199], v[208:211], v[96:99]
	v_mfma_f32_16x16x32_bf16 v[96:99], v[192:195], v[200:203], v[96:99]
	v_mfma_f32_16x16x32_bf16 v[80:83], v[192:195], v[214:217], v[80:83]
	v_mfma_f32_16x16x32_bf16 v[80:83], v[196:199], v[230:233], v[80:83]
	v_mfma_f32_16x16x32_bf16 v[88:91], v[188:191], v[230:233], v[88:91]
	v_mfma_f32_16x16x32_bf16 v[88:91], v[184:187], v[214:217], v[88:91]
	v_mfma_f32_16x16x32_bf16 v[76:79], v[184:187], v[234:237], v[76:79]
	v_mfma_f32_16x16x32_bf16 v[76:79], v[188:191], v[238:241], v[76:79]
	v_mfma_f32_16x16x32_bf16 v[72:75], v[196:199], v[238:241], v[72:75]
	v_mfma_f32_16x16x32_bf16 v[72:75], v[192:195], v[234:237], v[72:75]
	v_mfma_f32_16x16x32_bf16 v[64:67], v[192:195], v[242:245], v[64:67]
	v_mfma_f32_16x16x32_bf16 v[64:67], v[196:199], v[246:249], v[64:67]
	v_mfma_f32_16x16x32_bf16 v[68:71], v[188:191], v[246:249], v[68:71]
	v_mfma_f32_16x16x32_bf16 v[68:71], v[184:187], v[242:245], v[68:71]
	s_setprio 0
	s_barrier
; #define PG8_STAGE(bufoff, gbase, voff) do { _Pragma("unroll") for (int _i = 0; _i < 2; ++_i) \
;         __builtin_amdgcn_global_load_lds((const unsigned*)((const char*)(gbase) + (voff)[_i]), (LAS unsigned*)(lds + (bufoff) + ldsw + _i * 8192), 16, 0, 0); } while (0)
; #define PG8_LDA(dst, b, h) do { _Pragma("unroll") for (int m = 0; m < 4; ++m) _Pragma("unroll") for (int k = 0; k < 2; ++k) dst[m][k] = *(const LAS bf16x8*)(lds + PG8_SA(b, h) + aoff + m * 2048 + k * 1024); } while (0)
; #define PG8_MMA(ai, bj, At, Bt) do { __builtin_amdgcn_s_setprio(1); _Pragma("unroll") for (int m = 0; m < 4; ++m) _Pragma("unroll") for (int n = 0; n < 2; ++n) _Pragma("unroll") for (int k = 0; k < 2; ++k) \
;         acc[ai][bj][m][n] = __builtin_amdgcn_mfma_f32_16x16x32_bf16(Bt[n][k], At[m][k], acc[ai][bj][m][n], 0, 0, 0); __builtin_amdgcn_s_setprio(0); } while (0)
; #define PG8_WAIT_V(n) asm volatile("s_waitcnt vmcnt(" #n ")" ::: "memory")
; #define PG8_WAIT_L(n) asm volatile("s_waitcnt lgkmcnt(" #n ")" ::: "memory")
; #define PG8_BAR __builtin_amdgcn_s_barrier()
; #define PG8_SCHED __builtin_amdgcn_sched_barrier(0)
;     ...
;             PG8_LDA(At, 1, 1); PG8_STAGE(PG8_SB(1, 0), b3, voffB); PG8_STAGE(PG8_SB(1, 1), b3 + hB, voffB); PG8_STAGE(PG8_SA(1, 0), a3, voffA);
;             PG8_WAIT_V(8); PG8_WAIT_L(0); PG8_BAR; PG8_MMA(1, 0, At, B0); PG8_MMA(1, 1, At, B1); PG8_BAR; PG8_SCHED;
;     ...
;         }
;         if constexpr (ALIGN_EPI) { if (wr == 0) PG8_BAR; }
	s_add_i32 s2, s12, s0
	v_lshl_add_u64 v[204:205], v[204:205], 0, s[38:39]
	s_mov_b32 m0, s2
	ds_read_b128 v[200:203], v154 offset:49152
	ds_read_b128 v[208:211], v154 offset:50176
	ds_read_b128 v[214:217], v154 offset:51200
	ds_read_b128 v[230:233], v154 offset:52224
	ds_read_b128 v[234:237], v154 offset:53248
	ds_read_b128 v[238:241], v154 offset:54272
	ds_read_b128 v[242:245], v154 offset:55296
	ds_read_b128 v[246:249], v154 offset:56320
	global_load_lds_dwordx4 v[204:205], off
	s_add_i32 m0, s2, 0x2000
	s_add_u32 s2, s74, 0x20080
	v_lshl_add_u64 v[204:205], v[206:207], 0, s[38:39]
	s_addc_u32 s3, s75, 0
	s_add_i32 s12, s13, s0
	global_load_lds_dwordx4 v[204:205], off
	v_lshl_add_u64 v[204:205], s[2:3], 0, v[130:131]
	s_mov_b32 m0, s12
	s_nop 0
	global_load_lds_dwordx4 v[204:205], off
	v_lshl_add_u64 v[204:205], s[2:3], 0, v[134:135]
	s_add_i32 m0, s12, 0x2000
	s_nop 0
	global_load_lds_dwordx4 v[204:205], off
	v_lshl_add_u64 v[204:205], s[72:73], 0, v[128:129]
	s_mov_b32 m0, s8
	s_nop 0
	global_load_lds_dwordx4 v[204:205], off
	v_lshl_add_u64 v[204:205], s[72:73], 0, v[132:133]
	s_mov_b32 m0, s9
	s_nop 0
	global_load_lds_dwordx4 v[204:205], off
	s_waitcnt vmcnt(8)
	s_waitcnt lgkmcnt(0)
	s_barrier
	s_setprio 1
	s_waitcnt lgkmcnt(0)
	v_mfma_f32_16x16x32_bf16 v[60:63], v[168:171], v[200:203], v[60:63]
	v_mfma_f32_16x16x32_bf16 v[60:63], v[172:175], v[208:211], v[60:63]
	v_mfma_f32_16x16x32_bf16 v[56:59], v[180:183], v[208:211], v[56:59]
	v_mfma_f32_16x16x32_bf16 v[56:59], v[176:179], v[200:203], v[56:59]
	v_mfma_f32_16x16x32_bf16 v[48:51], v[176:179], v[214:217], v[48:51]
	v_mfma_f32_16x16x32_bf16 v[48:51], v[180:183], v[230:233], v[48:51]
	v_mfma_f32_16x16x32_bf16 v[52:55], v[172:175], v[230:233], v[52:55]
	v_mfma_f32_16x16x32_bf16 v[52:55], v[168:171], v[214:217], v[52:55]
	v_mfma_f32_16x16x32_bf16 v[44:47], v[168:171], v[234:237], v[44:47]
	v_mfma_f32_16x16x32_bf16 v[44:47], v[172:175], v[238:241], v[44:47]
	v_mfma_f32_16x16x32_bf16 v[36:39], v[180:183], v[238:241], v[36:39]
	v_mfma_f32_16x16x32_bf16 v[36:39], v[176:179], v[234:237], v[36:39]
	v_mfma_f32_16x16x32_bf16 v[20:23], v[176:179], v[242:245], v[20:23]
	v_mfma_f32_16x16x32_bf16 v[20:23], v[180:183], v[246:249], v[20:23]
	v_mfma_f32_16x16x32_bf16 v[28:31], v[172:175], v[246:249], v[28:31]
	v_mfma_f32_16x16x32_bf16 v[28:31], v[168:171], v[242:245], v[28:31]
	s_setprio 0
	s_setprio 1
	v_mfma_f32_16x16x32_bf16 v[40:43], v[184:187], v[200:203], v[40:43]
	v_mfma_f32_16x16x32_bf16 v[40:43], v[188:191], v[208:211], v[40:43]
	v_mfma_f32_16x16x32_bf16 v[32:35], v[196:199], v[208:211], v[32:35]
	v_mfma_f32_16x16x32_bf16 v[32:35], v[192:195], v[200:203], v[32:35]
	v_mfma_f32_16x16x32_bf16 v[16:19], v[192:195], v[214:217], v[16:19]
	v_mfma_f32_16x16x32_bf16 v[16:19], v[196:199], v[230:233], v[16:19]
	v_mfma_f32_16x16x32_bf16 v[24:27], v[188:191], v[230:233], v[24:27]
	v_mfma_f32_16x16x32_bf16 v[24:27], v[184:187], v[214:217], v[24:27]
	v_mfma_f32_16x16x32_bf16 v[12:15], v[184:187], v[234:237], v[12:15]
	v_mfma_f32_16x16x32_bf16 v[12:15], v[188:191], v[238:241], v[12:15]
	v_mfma_f32_16x16x32_bf16 v[8:11], v[196:199], v[238:241], v[8:11]
	v_mfma_f32_16x16x32_bf16 v[8:11], v[192:195], v[234:237], v[8:11]
	v_mfma_f32_16x16x32_bf16 v[0:3], v[192:195], v[242:245], v[0:3]
	v_mfma_f32_16x16x32_bf16 v[0:3], v[196:199], v[246:249], v[0:3]
	v_mfma_f32_16x16x32_bf16 v[4:7], v[188:191], v[246:249], v[4:7]
	v_mfma_f32_16x16x32_bf16 v[4:7], v[184:187], v[242:245], v[4:7]
	s_setprio 0
	s_barrier
	s_add_i32 vcc_lo, vcc_lo, 2
	s_add_u32 s94, s94, 0x100
	s_addc_u32 s95, s95, 0
	s_cmp_gt_u32 vcc_lo, 5
	s_cbranch_scc0 .LBB0_119
	s_and_b64 vcc, exec, s[30:31]
	s_cbranch_vccz .LBB0_122
	s_barrier

; #define PG8_STAGE(bufoff, gbase, voff) do { _Pragma("unroll") for (int _i = 0; _i < 2; ++_i) \
;         __builtin_amdgcn_global_load_lds((const unsigned*)((const char*)(gbase) + (voff)[_i]), (LAS unsigned*)(lds + (bufoff) + ldsw + _i * 8192), 16, 0, 0); } while (0)
; #define PG8_LDA(dst, b, h) do { _Pragma("unroll") for (int m = 0; m < 4; ++m) _Pragma("unroll") for (int k = 0; k < 2; ++k) dst[m][k] = *(const LAS bf16x8*)(lds + PG8_SA(b, h) + aoff + m * 2048 + k * 1024); } while (0)
; #define PG8_LDB(dst, b, h) do { _Pragma("unroll") for (int n = 0; n < 2; ++n) _Pragma("unroll") for (int k = 0; k < 2; ++k) dst[n][k] = *(const LAS bf16x8*)(lds + PG8_SB(b, h) + boff + n * 2048 + k * 1024); } while (0)
; #define PG8_MMA(ai, bj, At, Bt) do { __builtin_amdgcn_s_setprio(1); _Pragma("unroll") for (int m = 0; m < 4; ++m) _Pragma("unroll") for (int n = 0; n < 2; ++n) _Pragma("unroll") for (int k = 0; k < 2; ++k) \
;         acc[ai][bj][m][n] = __builtin_amdgcn_mfma_f32_16x16x32_bf16(Bt[n][k], At[m][k], acc[ai][bj][m][n], 0, 0, 0); __builtin_amdgcn_s_setprio(0); } while (0)
; #define PG8_WAIT_V(n) asm volatile("s_waitcnt vmcnt(" #n ")" ::: "memory")
; #define PG8_WAIT_L(n) asm volatile("s_waitcnt lgkmcnt(" #n ")" ::: "memory")
; #define PG8_BAR __builtin_amdgcn_s_barrier()
; #define PG8_SCHED __builtin_amdgcn_sched_barrier(0)
;     ...
;             const bool last = (t == nt - 2);
;             const char* a1 = PG8_ATILE(cA, cA2, t + 1);
;             const char* a2 = last ? nA : PG8_ATILE(cA, cA2, t + 2); const char* b2 = last ? nB : cB + (size_t)(t + 2) * 128;
;             const char* a3 = last ? nA + kA1 : PG8_ATILE(cA, cA2, t + 3); const char* b3 = b2 + kB1;
;             if constexpr (SP2) {
;             PG8_LDB(B0, 0, 0); PG8_LDB(B1, 0, 1); PG8_SCHED; PG8_LDA(At, 0, 0); PG8_STAGE(PG8_SA(1, 1), a1 + hA, voffA);
;             PG8_WAIT_V(8); PG8_WAIT_L(0); PG8_BAR; PG8_MMA(0, 0, At, B0); PG8_MMA(0, 1, At, B1); PG8_BAR; PG8_SCHED;
;             PG8_LDA(At, 0, 1); PG8_STAGE(PG8_SB(0, 0), b2, voffB); PG8_STAGE(PG8_SB(0, 1), b2 + hB, voffB); PG8_STAGE(PG8_SA(0, 0), a2, voffA);
;             PG8_WAIT_V(8); PG8_WAIT_L(0); PG8_BAR; PG8_MMA(1, 0, At, B0); PG8_MMA(1, 1, At, B1); PG8_BAR; PG8_SCHED;
.LBB0_155:
	s_add_u32 s29, s34, s44
	s_addc_u32 s36, s35, s45
	s_add_u32 s54, s29, 0x800000
	s_addc_u32 s55, s36, 0
	s_add_u32 s29, s29, 0xc00000
	s_addc_u32 s36, s36, 0
	s_add_i32 s82, 0, 0x10000
	s_add_i32 s83, 0, 0x14000
	v_add_u32_e32 v168, s82, v180
	v_add_u32_e32 v183, s83, v180
	ds_read_b128 v[120:123], v168
	ds_read_b128 v[132:135], v168 offset:1024
	ds_read_b128 v[140:143], v168 offset:2048
	ds_read_b128 v[168:171], v168 offset:3072
	ds_read_b128 v[172:175], v183
	ds_read_b128 v[176:179], v183 offset:1024
	ds_read_b128 v[184:187], v183 offset:2048
	ds_read_b128 v[188:191], v183 offset:3072
	s_cmp_eq_u32 s44, 0x3800000
	s_cselect_b32 s53, s8, s36
	s_cselect_b32 s52, s7, s29
	s_cselect_b32 s73, s5, s17
	s_cselect_b32 s72, s6, s9
	s_cselect_b32 s75, s1, s55
	s_cselect_b32 s74, s4, s54
	v_lshl_add_u64 v[204:205], v[110:111], 0, s[44:45]
	s_add_i32 m0, s78, 0xc000
	ds_read_b128 v[192:195], v182
	ds_read_b128 v[196:199], v182 offset:1024
	ds_read_b128 v[200:203], v182 offset:2048
	ds_read_b128 v[208:211], v182 offset:3072
	ds_read_b128 v[214:217], v182 offset:4096
	ds_read_b128 v[230:233], v182 offset:5120
	ds_read_b128 v[234:237], v182 offset:6144
	ds_read_b128 v[238:241], v182 offset:7168
	global_load_lds_dwordx4 v[204:205], off
	v_lshl_add_u64 v[204:205], v[108:109], 0, s[44:45]
	s_add_i32 m0, s78, 0xe000
	s_nop 0
	global_load_lds_dwordx4 v[204:205], off
	s_waitcnt vmcnt(8)
	s_waitcnt lgkmcnt(0)
	s_barrier
	s_setprio 1
	s_waitcnt lgkmcnt(0)
	v_mfma_f32_16x16x32_bf16 v[136:139], v[120:123], v[192:195], v[136:139]
	v_mfma_f32_16x16x32_bf16 v[136:139], v[132:135], v[196:199], v[136:139]
	v_mfma_f32_16x16x32_bf16 v[128:131], v[168:171], v[196:199], v[128:131]
	v_mfma_f32_16x16x32_bf16 v[128:131], v[140:143], v[192:195], v[128:131]
	v_mfma_f32_16x16x32_bf16 v[104:107], v[140:143], v[200:203], v[104:107]
	v_mfma_f32_16x16x32_bf16 v[104:107], v[168:171], v[208:211], v[104:107]
	v_mfma_f32_16x16x32_bf16 v[112:115], v[132:135], v[208:211], v[112:115]
	v_mfma_f32_16x16x32_bf16 v[112:115], v[120:123], v[200:203], v[112:115]
	v_mfma_f32_16x16x32_bf16 v[92:95], v[120:123], v[214:217], v[92:95]
	v_mfma_f32_16x16x32_bf16 v[92:95], v[132:135], v[230:233], v[92:95]
	v_mfma_f32_16x16x32_bf16 v[88:91], v[168:171], v[230:233], v[88:91]
	v_mfma_f32_16x16x32_bf16 v[88:91], v[140:143], v[214:217], v[88:91]
	v_mfma_f32_16x16x32_bf16 v[72:75], v[140:143], v[234:237], v[72:75]
	v_mfma_f32_16x16x32_bf16 v[72:75], v[168:171], v[238:241], v[72:75]
	v_mfma_f32_16x16x32_bf16 v[76:79], v[132:135], v[238:241], v[76:79]
	v_mfma_f32_16x16x32_bf16 v[76:79], v[120:123], v[234:237], v[76:79]
	s_setprio 0
	s_setprio 1
	v_mfma_f32_16x16x32_bf16 v[124:127], v[172:175], v[192:195], v[124:127]
	v_mfma_f32_16x16x32_bf16 v[124:127], v[176:179], v[196:199], v[124:127]
	v_mfma_f32_16x16x32_bf16 v[116:119], v[188:191], v[196:199], v[116:119]
	v_mfma_f32_16x16x32_bf16 v[116:119], v[184:187], v[192:195], v[116:119]
	v_mfma_f32_16x16x32_bf16 v[96:99], v[184:187], v[200:203], v[96:99]
	v_mfma_f32_16x16x32_bf16 v[96:99], v[188:191], v[208:211], v[96:99]
	v_mfma_f32_16x16x32_bf16 v[100:103], v[176:179], v[208:211], v[100:103]
	v_mfma_f32_16x16x32_bf16 v[100:103], v[172:175], v[200:203], v[100:103]
	v_mfma_f32_16x16x32_bf16 v[84:87], v[172:175], v[214:217], v[84:87]
	v_mfma_f32_16x16x32_bf16 v[84:87], v[176:179], v[230:233], v[84:87]
	v_mfma_f32_16x16x32_bf16 v[80:83], v[188:191], v[230:233], v[80:83]
	v_mfma_f32_16x16x32_bf16 v[80:83], v[184:187], v[214:217], v[80:83]
	v_mfma_f32_16x16x32_bf16 v[64:67], v[184:187], v[234:237], v[64:67]
	v_mfma_f32_16x16x32_bf16 v[64:67], v[188:191], v[238:241], v[64:67]
	v_mfma_f32_16x16x32_bf16 v[68:71], v[176:179], v[238:241], v[68:71]
	v_mfma_f32_16x16x32_bf16 v[68:71], v[172:175], v[234:237], v[68:71]
	s_setprio 0
	s_barrier
	s_add_i32 s29, s82, s77
	v_lshl_add_u64 v[204:205], s[72:73], 0, v[146:147]
	s_mov_b32 m0, s29
	ds_read_b128 v[192:195], v182 offset:16384
	ds_read_b128 v[196:199], v182 offset:17408
	ds_read_b128 v[200:203], v182 offset:18432
	ds_read_b128 v[208:211], v182 offset:19456
	ds_read_b128 v[214:217], v182 offset:20480
	ds_read_b128 v[230:233], v182 offset:21504
	ds_read_b128 v[234:237], v182 offset:22528
	ds_read_b128 v[238:241], v182 offset:23552
	global_load_lds_dwordx4 v[204:205], off
	s_add_i32 m0, s29, 0x2000
	s_add_u32 s54, s72, 0x40000
	v_lshl_add_u64 v[206:207], s[72:73], 0, v[150:151]
	s_addc_u32 s55, s73, 0
	s_add_i32 s29, s83, s77
	global_load_lds_dwordx4 v[206:207], off
	v_lshl_add_u64 v[242:243], s[54:55], 0, v[146:147]
	s_mov_b32 m0, s29
	s_nop 0
	global_load_lds_dwordx4 v[242:243], off
	v_lshl_add_u64 v[242:243], s[54:55], 0, v[150:151]
	s_add_i32 m0, s29, 0x2000
	s_nop 0
	global_load_lds_dwordx4 v[242:243], off
	v_lshl_add_u64 v[242:243], s[74:75], 0, v[144:145]
	s_mov_b32 m0, s78
	s_nop 0
	global_load_lds_dwordx4 v[242:243], off
	v_lshl_add_u64 v[242:243], s[74:75], 0, v[148:149]
	s_mov_b32 m0, s79
	s_nop 0
	global_load_lds_dwordx4 v[242:243], off
	s_waitcnt vmcnt(8)
	s_waitcnt lgkmcnt(0)
	s_barrier
; #define PG8_STAGE(bufoff, gbase, voff) do { _Pragma("unroll") for (int _i = 0; _i < 2; ++_i) \
;         __builtin_amdgcn_global_load_lds((const unsigned*)((const char*)(gbase) + (voff)[_i]), (LAS unsigned*)(lds + (bufoff) + ldsw + _i * 8192), 16, 0, 0); } while (0)
; #define PG8_LDA(dst, b, h) do { _Pragma("unroll") for (int m = 0; m < 4; ++m) _Pragma("unroll") for (int k = 0; k < 2; ++k) dst[m][k] = *(const LAS bf16x8*)(lds + PG8_SA(b, h) + aoff + m * 2048 + k * 1024); } while (0)
; #define PG8_LDB(dst, b, h) do { _Pragma("unroll") for (int n = 0; n < 2; ++n) _Pragma("unroll") for (int k = 0; k < 2; ++k) dst[n][k] = *(const LAS bf16x8*)(lds + PG8_SB(b, h) + boff + n * 2048 + k * 1024); } while (0)
; #define PG8_MMA(ai, bj, At, Bt) do { __builtin_amdgcn_s_setprio(1); _Pragma("unroll") for (int m = 0; m < 4; ++m) _Pragma("unroll") for (int n = 0; n < 2; ++n) _Pragma("unroll") for (int k = 0; k < 2; ++k) \
;         acc[ai][bj][m][n] = __builtin_amdgcn_mfma_f32_16x16x32_bf16(Bt[n][k], At[m][k], acc[ai][bj][m][n], 0, 0, 0); __builtin_amdgcn_s_setprio(0); } while (0)
; #define PG8_WAIT_V(n) asm volatile("s_waitcnt vmcnt(" #n ")" ::: "memory")
; #define PG8_WAIT_L(n) asm volatile("s_waitcnt lgkmcnt(" #n ")" ::: "memory")
; #define PG8_BAR __builtin_amdgcn_s_barrier()
; #define PG8_SCHED __builtin_amdgcn_sched_barrier(0)
;     ...
;             PG8_WAIT_V(8); PG8_WAIT_L(0); PG8_BAR; PG8_MMA(1, 0, At, B0); PG8_MMA(1, 1, At, B1); PG8_BAR; PG8_SCHED;
;             PG8_LDB(B0, 1, 0); PG8_LDB(B1, 1, 1); PG8_SCHED; PG8_LDA(At, 1, 0); PG8_STAGE(PG8_SA(0, 1), a2 + hA, voffA);
;             PG8_WAIT_V(8); PG8_WAIT_L(0); PG8_BAR; PG8_MMA(0, 0, At, B0); PG8_MMA(0, 1, At, B1); PG8_BAR; PG8_SCHED;
	s_setprio 1
	s_waitcnt lgkmcnt(0)
	v_mfma_f32_16x16x32_bf16 v[60:63], v[120:123], v[192:195], v[60:63]
	v_mfma_f32_16x16x32_bf16 v[60:63], v[132:135], v[196:199], v[60:63]
	v_mfma_f32_16x16x32_bf16 v[56:59], v[168:171], v[196:199], v[56:59]
	v_mfma_f32_16x16x32_bf16 v[56:59], v[140:143], v[192:195], v[56:59]
	v_mfma_f32_16x16x32_bf16 v[40:43], v[140:143], v[200:203], v[40:43]
	v_mfma_f32_16x16x32_bf16 v[40:43], v[168:171], v[208:211], v[40:43]
	v_mfma_f32_16x16x32_bf16 v[44:47], v[132:135], v[208:211], v[44:47]
	v_mfma_f32_16x16x32_bf16 v[44:47], v[120:123], v[200:203], v[44:47]
	v_mfma_f32_16x16x32_bf16 v[28:31], v[120:123], v[214:217], v[28:31]
	v_mfma_f32_16x16x32_bf16 v[28:31], v[132:135], v[230:233], v[28:31]
	v_mfma_f32_16x16x32_bf16 v[24:27], v[168:171], v[230:233], v[24:27]
	v_mfma_f32_16x16x32_bf16 v[24:27], v[140:143], v[214:217], v[24:27]
	v_mfma_f32_16x16x32_bf16 v[8:11], v[140:143], v[234:237], v[8:11]
	v_mfma_f32_16x16x32_bf16 v[8:11], v[168:171], v[238:241], v[8:11]
	v_mfma_f32_16x16x32_bf16 v[12:15], v[132:135], v[238:241], v[12:15]
	v_mfma_f32_16x16x32_bf16 v[12:15], v[120:123], v[234:237], v[12:15]
	s_setprio 0
	s_setprio 1
	v_mfma_f32_16x16x32_bf16 v[52:55], v[172:175], v[192:195], v[52:55]
	v_mfma_f32_16x16x32_bf16 v[52:55], v[176:179], v[196:199], v[52:55]
	v_mfma_f32_16x16x32_bf16 v[48:51], v[188:191], v[196:199], v[48:51]
	v_mfma_f32_16x16x32_bf16 v[48:51], v[184:187], v[192:195], v[48:51]
	v_mfma_f32_16x16x32_bf16 v[32:35], v[184:187], v[200:203], v[32:35]
	v_mfma_f32_16x16x32_bf16 v[32:35], v[188:191], v[208:211], v[32:35]
	v_mfma_f32_16x16x32_bf16 v[36:39], v[176:179], v[208:211], v[36:39]
	v_mfma_f32_16x16x32_bf16 v[36:39], v[172:175], v[200:203], v[36:39]
	v_mfma_f32_16x16x32_bf16 v[20:23], v[172:175], v[214:217], v[20:23]
	v_mfma_f32_16x16x32_bf16 v[20:23], v[176:179], v[230:233], v[20:23]
	v_mfma_f32_16x16x32_bf16 v[16:19], v[188:191], v[230:233], v[16:19]
	v_mfma_f32_16x16x32_bf16 v[16:19], v[184:187], v[214:217], v[16:19]
	v_mfma_f32_16x16x32_bf16 v[0:3], v[184:187], v[234:237], v[0:3]
	v_mfma_f32_16x16x32_bf16 v[0:3], v[188:191], v[238:241], v[0:3]
	v_mfma_f32_16x16x32_bf16 v[4:7], v[176:179], v[238:241], v[4:7]
	v_mfma_f32_16x16x32_bf16 v[4:7], v[172:175], v[234:237], v[4:7]
	s_setprio 0
	s_barrier
	s_add_i32 s29, 0, 0x18000
	s_add_i32 s36, 0, 0x1c000
	v_add_u32_e32 v168, s29, v180
	v_add_u32_e32 v183, s36, v180
	ds_read_b128 v[120:123], v168
	ds_read_b128 v[132:135], v168 offset:1024
	ds_read_b128 v[140:143], v168 offset:2048
	ds_read_b128 v[168:171], v168 offset:3072
	ds_read_b128 v[172:175], v183
	ds_read_b128 v[176:179], v183 offset:1024
	ds_read_b128 v[184:187], v183 offset:2048
	ds_read_b128 v[188:191], v183 offset:3072
	s_add_u32 s54, s74, 0x1000
	s_addc_u32 s55, s75, 0
	s_mov_b32 m0, s80
	v_lshl_add_u64 v[242:243], s[54:55], 0, v[144:145]
	ds_read_b128 v[192:195], v182 offset:32768
	ds_read_b128 v[196:199], v182 offset:33792
	ds_read_b128 v[200:203], v182 offset:34816
	ds_read_b128 v[208:211], v182 offset:35840
	ds_read_b128 v[214:217], v182 offset:36864
	ds_read_b128 v[230:233], v182 offset:37888
	ds_read_b128 v[234:237], v182 offset:38912
	ds_read_b128 v[238:241], v182 offset:39936
	global_load_lds_dwordx4 v[242:243], off
	v_lshl_add_u64 v[242:243], s[54:55], 0, v[148:149]
	s_mov_b32 m0, s81
	s_nop 0
	global_load_lds_dwordx4 v[242:243], off
	s_waitcnt vmcnt(8)
	s_waitcnt lgkmcnt(0)
	s_barrier
	s_setprio 1
	s_waitcnt lgkmcnt(0)
	v_mfma_f32_16x16x32_bf16 v[136:139], v[120:123], v[192:195], v[136:139]
	v_mfma_f32_16x16x32_bf16 v[136:139], v[132:135], v[196:199], v[136:139]
	v_mfma_f32_16x16x32_bf16 v[128:131], v[168:171], v[196:199], v[128:131]
	v_mfma_f32_16x16x32_bf16 v[128:131], v[140:143], v[192:195], v[128:131]
	v_mfma_f32_16x16x32_bf16 v[104:107], v[140:143], v[200:203], v[104:107]
	v_mfma_f32_16x16x32_bf16 v[104:107], v[168:171], v[208:211], v[104:107]
	v_mfma_f32_16x16x32_bf16 v[112:115], v[132:135], v[208:211], v[112:115]
	v_mfma_f32_16x16x32_bf16 v[112:115], v[120:123], v[200:203], v[112:115]
	v_mfma_f32_16x16x32_bf16 v[92:95], v[120:123], v[214:217], v[92:95]
	v_mfma_f32_16x16x32_bf16 v[92:95], v[132:135], v[230:233], v[92:95]
	v_mfma_f32_16x16x32_bf16 v[88:91], v[168:171], v[230:233], v[88:91]
	v_mfma_f32_16x16x32_bf16 v[88:91], v[140:143], v[214:217], v[88:91]
	v_mfma_f32_16x16x32_bf16 v[72:75], v[140:143], v[234:237], v[72:75]
	v_mfma_f32_16x16x32_bf16 v[72:75], v[168:171], v[238:241], v[72:75]
	v_mfma_f32_16x16x32_bf16 v[76:79], v[132:135], v[238:241], v[76:79]
	v_mfma_f32_16x16x32_bf16 v[76:79], v[120:123], v[234:237], v[76:79]
	s_setprio 0
	s_setprio 1
	v_mfma_f32_16x16x32_bf16 v[124:127], v[172:175], v[192:195], v[124:127]
	v_mfma_f32_16x16x32_bf16 v[124:127], v[176:179], v[196:199], v[124:127]
	v_mfma_f32_16x16x32_bf16 v[116:119], v[188:191], v[196:199], v[116:119]
	v_mfma_f32_16x16x32_bf16 v[116:119], v[184:187], v[192:195], v[116:119]
	v_mfma_f32_16x16x32_bf16 v[96:99], v[184:187], v[200:203], v[96:99]
	v_mfma_f32_16x16x32_bf16 v[96:99], v[188:191], v[208:211], v[96:99]
	v_mfma_f32_16x16x32_bf16 v[100:103], v[176:179], v[208:211], v[100:103]
	v_mfma_f32_16x16x32_bf16 v[100:103], v[172:175], v[200:203], v[100:103]
	v_mfma_f32_16x16x32_bf16 v[84:87], v[172:175], v[214:217], v[84:87]
	v_mfma_f32_16x16x32_bf16 v[84:87], v[176:179], v[230:233], v[84:87]
	v_mfma_f32_16x16x32_bf16 v[80:83], v[188:191], v[230:233], v[80:83]
	v_mfma_f32_16x16x32_bf16 v[80:83], v[184:187], v[214:217], v[80:83]
	v_mfma_f32_16x16x32_bf16 v[64:67], v[184:187], v[234:237], v[64:67]
	v_mfma_f32_16x16x32_bf16 v[64:67], v[188:191], v[238:241], v[64:67]
	v_mfma_f32_16x16x32_bf16 v[68:71], v[176:179], v[238:241], v[68:71]
	v_mfma_f32_16x16x32_bf16 v[68:71], v[172:175], v[234:237], v[68:71]
	s_setprio 0
	s_barrier
; #define PG8_STAGE(bufoff, gbase, voff) do { _Pragma("unroll") for (int _i = 0; _i < 2; ++_i) \
;         __builtin_amdgcn_global_load_lds((const unsigned*)((const char*)(gbase) + (voff)[_i]), (LAS unsigned*)(lds + (bufoff) + ldsw + _i * 8192), 16, 0, 0); } while (0)
; #define PG8_LDA(dst, b, h) do { _Pragma("unroll") for (int m = 0; m < 4; ++m) _Pragma("unroll") for (int k = 0; k < 2; ++k) dst[m][k] = *(const LAS bf16x8*)(lds + PG8_SA(b, h) + aoff + m * 2048 + k * 1024); } while (0)
; #define PG8_MMA(ai, bj, At, Bt) do { __builtin_amdgcn_s_setprio(1); _Pragma("unroll") for (int m = 0; m < 4; ++m) _Pragma("unroll") for (int n = 0; n < 2; ++n) _Pragma("unroll") for (int k = 0; k < 2; ++k) \
;         acc[ai][bj][m][n] = __builtin_amdgcn_mfma_f32_16x16x32_bf16(Bt[n][k], At[m][k], acc[ai][bj][m][n], 0, 0, 0); __builtin_amdgcn_s_setprio(0); } while (0)
; #define PG8_WAIT_V(n) asm volatile("s_waitcnt vmcnt(" #n ")" ::: "memory")
; #define PG8_WAIT_L(n) asm volatile("s_waitcnt lgkmcnt(" #n ")" ::: "memory")
; #define PG8_BAR __builtin_amdgcn_s_barrier()
; #define PG8_SCHED __builtin_amdgcn_sched_barrier(0)
;     ...
;             PG8_LDA(At, 1, 1); PG8_STAGE(PG8_SB(1, 0), b3, voffB); PG8_STAGE(PG8_SB(1, 1), b3 + hB, voffB); PG8_STAGE(PG8_SA(1, 0), a3, voffA);
;             PG8_WAIT_V(8); PG8_WAIT_L(0); PG8_BAR; PG8_MMA(1, 0, At, B0); PG8_MMA(1, 1, At, B1); PG8_BAR; PG8_SCHED;
;     ...
;         }
;         if constexpr (ALIGN_EPI) { if (wr == 0) PG8_BAR; }
	s_add_i32 s29, s29, s77
	v_lshl_add_u64 v[204:205], v[204:205], 0, s[38:39]
	s_mov_b32 m0, s29
	ds_read_b128 v[192:195], v182 offset:49152
	ds_read_b128 v[196:199], v182 offset:50176
	ds_read_b128 v[200:203], v182 offset:51200
	ds_read_b128 v[208:211], v182 offset:52224
	ds_read_b128 v[214:217], v182 offset:53248
	ds_read_b128 v[230:233], v182 offset:54272
	ds_read_b128 v[234:237], v182 offset:55296
	ds_read_b128 v[238:241], v182 offset:56320
	global_load_lds_dwordx4 v[204:205], off
	s_add_i32 m0, s29, 0x2000
	s_add_u32 s54, s72, 0x40080
	v_lshl_add_u64 v[204:205], v[206:207], 0, s[38:39]
	s_addc_u32 s55, s73, 0
	s_add_i32 s29, s36, s77
	global_load_lds_dwordx4 v[204:205], off
	v_lshl_add_u64 v[204:205], s[54:55], 0, v[146:147]
	s_mov_b32 m0, s29
	s_nop 0
	global_load_lds_dwordx4 v[204:205], off
	v_lshl_add_u64 v[204:205], s[54:55], 0, v[150:151]
	s_add_i32 m0, s29, 0x2000
	s_nop 0
	global_load_lds_dwordx4 v[204:205], off
	v_lshl_add_u64 v[204:205], s[52:53], 0, v[144:145]
	s_mov_b32 m0, s89
	s_nop 0
	global_load_lds_dwordx4 v[204:205], off
	v_lshl_add_u64 v[204:205], s[52:53], 0, v[148:149]
	s_mov_b32 m0, s90
	s_nop 0
	global_load_lds_dwordx4 v[204:205], off
	s_waitcnt vmcnt(8)
	s_waitcnt lgkmcnt(0)
	s_barrier
	s_setprio 1
	s_waitcnt lgkmcnt(0)
	v_mfma_f32_16x16x32_bf16 v[60:63], v[120:123], v[192:195], v[60:63]
	v_mfma_f32_16x16x32_bf16 v[60:63], v[132:135], v[196:199], v[60:63]
	v_mfma_f32_16x16x32_bf16 v[56:59], v[168:171], v[196:199], v[56:59]
	v_mfma_f32_16x16x32_bf16 v[56:59], v[140:143], v[192:195], v[56:59]
	v_mfma_f32_16x16x32_bf16 v[40:43], v[140:143], v[200:203], v[40:43]
	v_mfma_f32_16x16x32_bf16 v[40:43], v[168:171], v[208:211], v[40:43]
	v_mfma_f32_16x16x32_bf16 v[44:47], v[132:135], v[208:211], v[44:47]
	v_mfma_f32_16x16x32_bf16 v[44:47], v[120:123], v[200:203], v[44:47]
	v_mfma_f32_16x16x32_bf16 v[28:31], v[120:123], v[214:217], v[28:31]
	v_mfma_f32_16x16x32_bf16 v[28:31], v[132:135], v[230:233], v[28:31]
	v_mfma_f32_16x16x32_bf16 v[24:27], v[168:171], v[230:233], v[24:27]
	v_mfma_f32_16x16x32_bf16 v[24:27], v[140:143], v[214:217], v[24:27]
	v_mfma_f32_16x16x32_bf16 v[8:11], v[140:143], v[234:237], v[8:11]
	v_mfma_f32_16x16x32_bf16 v[8:11], v[168:171], v[238:241], v[8:11]
	v_mfma_f32_16x16x32_bf16 v[12:15], v[132:135], v[238:241], v[12:15]
	v_mfma_f32_16x16x32_bf16 v[12:15], v[120:123], v[234:237], v[12:15]
	s_setprio 0
	s_setprio 1
	v_mfma_f32_16x16x32_bf16 v[52:55], v[172:175], v[192:195], v[52:55]
	v_mfma_f32_16x16x32_bf16 v[52:55], v[176:179], v[196:199], v[52:55]
	v_mfma_f32_16x16x32_bf16 v[48:51], v[188:191], v[196:199], v[48:51]
	v_mfma_f32_16x16x32_bf16 v[48:51], v[184:187], v[192:195], v[48:51]
	v_mfma_f32_16x16x32_bf16 v[32:35], v[184:187], v[200:203], v[32:35]
	v_mfma_f32_16x16x32_bf16 v[32:35], v[188:191], v[208:211], v[32:35]
	v_mfma_f32_16x16x32_bf16 v[36:39], v[176:179], v[208:211], v[36:39]
	v_mfma_f32_16x16x32_bf16 v[36:39], v[172:175], v[200:203], v[36:39]
	v_mfma_f32_16x16x32_bf16 v[20:23], v[172:175], v[214:217], v[20:23]
	v_mfma_f32_16x16x32_bf16 v[20:23], v[176:179], v[230:233], v[20:23]
	v_mfma_f32_16x16x32_bf16 v[16:19], v[188:191], v[230:233], v[16:19]
	v_mfma_f32_16x16x32_bf16 v[16:19], v[184:187], v[214:217], v[16:19]
	v_mfma_f32_16x16x32_bf16 v[0:3], v[184:187], v[234:237], v[0:3]
	v_mfma_f32_16x16x32_bf16 v[0:3], v[188:191], v[238:241], v[0:3]
	v_mfma_f32_16x16x32_bf16 v[4:7], v[176:179], v[238:241], v[4:7]
	v_mfma_f32_16x16x32_bf16 v[4:7], v[172:175], v[234:237], v[4:7]
	s_setprio 0
	s_barrier
	s_add_i32 s27, s27, 2
	s_add_u32 s9, s9, 0x100
	s_addc_u32 s17, s17, 0
	s_add_u32 s44, s44, 0x800000
	s_addc_u32 s45, s45, 0
	s_cmp_gt_u32 s27, 13
	s_cbranch_scc0 .LBB0_155
	s_and_b64 vcc, exec, s[14:15]
	s_cbranch_vccz .LBB0_158
	s_barrier

; #define PG8_STAGE(bufoff, gbase, voff) do { _Pragma("unroll") for (int _i = 0; _i < 2; ++_i) \
;         __builtin_amdgcn_global_load_lds((const unsigned*)((const char*)(gbase) + (voff)[_i]), (LAS unsigned*)(lds + (bufoff) + ldsw + _i * 8192), 16, 0, 0); } while (0)
; #define PG8_LDA(dst, b, h) do { _Pragma("unroll") for (int m = 0; m < 4; ++m) _Pragma("unroll") for (int k = 0; k < 2; ++k) dst[m][k] = *(const LAS bf16x8*)(lds + PG8_SA(b, h) + aoff + m * 2048 + k * 1024); } while (0)
; #define PG8_LDB(dst, b, h) do { _Pragma("unroll") for (int n = 0; n < 2; ++n) _Pragma("unroll") for (int k = 0; k < 2; ++k) dst[n][k] = *(const LAS bf16x8*)(lds + PG8_SB(b, h) + boff + n * 2048 + k * 1024); } while (0)
; #define PG8_MMA(ai, bj, At, Bt) do { __builtin_amdgcn_s_setprio(1); _Pragma("unroll") for (int m = 0; m < 4; ++m) _Pragma("unroll") for (int n = 0; n < 2; ++n) _Pragma("unroll") for (int k = 0; k < 2; ++k) \
;         acc[ai][bj][m][n] = __builtin_amdgcn_mfma_f32_16x16x32_bf16(Bt[n][k], At[m][k], acc[ai][bj][m][n], 0, 0, 0); __builtin_amdgcn_s_setprio(0); } while (0)
; #define PG8_WAIT_V(n) asm volatile("s_waitcnt vmcnt(" #n ")" ::: "memory")
; #define PG8_WAIT_L(n) asm volatile("s_waitcnt lgkmcnt(" #n ")" ::: "memory")
; #define PG8_BAR __builtin_amdgcn_s_barrier()
; #define PG8_SCHED __builtin_amdgcn_sched_barrier(0)
;     ...
;             const bool last = (t == nt - 2);
;             const char* a1 = PG8_ATILE(cA, cA2, t + 1);
;             const char* a2 = last ? nA : PG8_ATILE(cA, cA2, t + 2); const char* b2 = last ? nB : cB + (size_t)(t + 2) * 128;
;             const char* a3 = last ? nA + kA1 : PG8_ATILE(cA, cA2, t + 3); const char* b3 = b2 + kB1;
;             if constexpr (SP2) {
;             PG8_LDB(B0, 0, 0); PG8_LDB(B1, 0, 1); PG8_SCHED; PG8_LDA(At, 0, 0); PG8_STAGE(PG8_SA(1, 1), a1 + hA, voffA);
;             PG8_WAIT_V(8); PG8_WAIT_L(0); PG8_BAR; PG8_MMA(0, 0, At, B0); PG8_MMA(0, 1, At, B1); PG8_BAR; PG8_SCHED;
;             PG8_LDA(At, 0, 1); PG8_STAGE(PG8_SB(0, 0), b2, voffB); PG8_STAGE(PG8_SB(0, 1), b2 + hB, voffB); PG8_STAGE(PG8_SA(0, 0), a2, voffA);
;             PG8_WAIT_V(8); PG8_WAIT_L(0); PG8_BAR; PG8_MMA(1, 0, At, B0); PG8_MMA(1, 1, At, B1); PG8_BAR; PG8_SCHED;
.LBB0_191:
	s_add_u32 s72, s44, s52
	s_addc_u32 s73, s45, s53
	s_add_u32 s76, s72, 0x100
	s_addc_u32 s77, s73, 0
	s_add_u32 s74, s80, s52
	s_addc_u32 s75, s81, s53
	s_add_u32 s72, s72, 0x180
	s_addc_u32 s73, s73, 0
	s_add_i32 s83, 0, 0x10000
	s_add_i32 s89, 0, 0x14000
	v_add_u32_e32 v146, s83, v150
	ds_read_b128 v[100:103], v146
	ds_read_b128 v[168:171], v146 offset:1024
	ds_read_b128 v[172:175], v146 offset:2048
	ds_read_b128 v[176:179], v146 offset:3072
	v_add_u32_e32 v146, s89, v150
	ds_read_b128 v[180:183], v146
	ds_read_b128 v[184:187], v146 offset:1024
	ds_read_b128 v[188:191], v146 offset:2048
	ds_read_b128 v[192:195], v146 offset:3072
	s_cmpk_eq_i32 s52, 0x700
	s_cselect_b32 s73, s79, s73
	s_cselect_b32 s72, s78, s72
	s_cselect_b32 s75, s17, s75
	s_cselect_b32 s74, s55, s74
	s_cselect_b32 s77, s27, s77
	s_cselect_b32 s76, s54, s76
	v_lshl_add_u64 v[146:147], v[96:97], 0, s[52:53]
	s_add_i32 m0, s6, 0xc000
	ds_read_b128 v[196:199], v154
	ds_read_b128 v[200:203], v154 offset:1024
	ds_read_b128 v[208:211], v154 offset:2048
	ds_read_b128 v[214:217], v154 offset:3072
	ds_read_b128 v[230:233], v154 offset:4096
	ds_read_b128 v[234:237], v154 offset:5120
	ds_read_b128 v[238:241], v154 offset:6144
	ds_read_b128 v[242:245], v154 offset:7168
	global_load_lds_dwordx4 v[146:147], off
	v_lshl_add_u64 v[146:147], v[98:99], 0, s[52:53]
	s_add_i32 m0, s6, 0xe000
	s_nop 0
	global_load_lds_dwordx4 v[146:147], off
	s_waitcnt vmcnt(8)
	s_waitcnt lgkmcnt(0)
	s_barrier
	s_setprio 1
	s_waitcnt lgkmcnt(0)
	v_mfma_f32_16x16x32_bf16 v[132:135], v[100:103], v[196:199], v[132:135]
	v_mfma_f32_16x16x32_bf16 v[132:135], v[168:171], v[200:203], v[132:135]
	v_mfma_f32_16x16x32_bf16 v[128:131], v[176:179], v[200:203], v[128:131]
	v_mfma_f32_16x16x32_bf16 v[128:131], v[172:175], v[196:199], v[128:131]
	v_mfma_f32_16x16x32_bf16 v[120:123], v[172:175], v[208:211], v[120:123]
	v_mfma_f32_16x16x32_bf16 v[120:123], v[176:179], v[214:217], v[120:123]
	v_mfma_f32_16x16x32_bf16 v[124:127], v[168:171], v[214:217], v[124:127]
	v_mfma_f32_16x16x32_bf16 v[124:127], v[100:103], v[208:211], v[124:127]
	v_mfma_f32_16x16x32_bf16 v[116:119], v[100:103], v[230:233], v[116:119]
	v_mfma_f32_16x16x32_bf16 v[116:119], v[168:171], v[234:237], v[116:119]
	v_mfma_f32_16x16x32_bf16 v[112:115], v[176:179], v[234:237], v[112:115]
	v_mfma_f32_16x16x32_bf16 v[112:115], v[172:175], v[230:233], v[112:115]
	v_mfma_f32_16x16x32_bf16 v[104:107], v[172:175], v[238:241], v[104:107]
	v_mfma_f32_16x16x32_bf16 v[104:107], v[176:179], v[242:245], v[104:107]
	v_mfma_f32_16x16x32_bf16 v[108:111], v[168:171], v[242:245], v[108:111]
	v_mfma_f32_16x16x32_bf16 v[108:111], v[100:103], v[238:241], v[108:111]
	s_setprio 0
	s_setprio 1
	v_mfma_f32_16x16x32_bf16 v[68:71], v[180:183], v[196:199], v[68:71]
	v_mfma_f32_16x16x32_bf16 v[68:71], v[184:187], v[200:203], v[68:71]
	v_mfma_f32_16x16x32_bf16 v[56:59], v[192:195], v[200:203], v[56:59]
	v_mfma_f32_16x16x32_bf16 v[56:59], v[188:191], v[196:199], v[56:59]
	v_mfma_f32_16x16x32_bf16 v[48:51], v[188:191], v[208:211], v[48:51]
	v_mfma_f32_16x16x32_bf16 v[48:51], v[192:195], v[214:217], v[48:51]
	v_mfma_f32_16x16x32_bf16 v[52:55], v[184:187], v[214:217], v[52:55]
	v_mfma_f32_16x16x32_bf16 v[52:55], v[180:183], v[208:211], v[52:55]
	v_mfma_f32_16x16x32_bf16 v[44:47], v[180:183], v[230:233], v[44:47]
	v_mfma_f32_16x16x32_bf16 v[44:47], v[184:187], v[234:237], v[44:47]
	v_mfma_f32_16x16x32_bf16 v[40:43], v[192:195], v[234:237], v[40:43]
	v_mfma_f32_16x16x32_bf16 v[40:43], v[188:191], v[230:233], v[40:43]
	v_mfma_f32_16x16x32_bf16 v[32:35], v[188:191], v[238:241], v[32:35]
	v_mfma_f32_16x16x32_bf16 v[32:35], v[192:195], v[242:245], v[32:35]
	v_mfma_f32_16x16x32_bf16 v[36:39], v[184:187], v[242:245], v[36:39]
	v_mfma_f32_16x16x32_bf16 v[36:39], v[180:183], v[238:241], v[36:39]
	s_setprio 0
	s_barrier
	s_add_i32 s83, s83, s5
	v_lshl_add_u64 v[146:147], s[74:75], 0, v[156:157]
	s_mov_b32 m0, s83
	ds_read_b128 v[196:199], v154 offset:16384
	ds_read_b128 v[200:203], v154 offset:17408
	ds_read_b128 v[208:211], v154 offset:18432
	ds_read_b128 v[214:217], v154 offset:19456
	ds_read_b128 v[230:233], v154 offset:20480
	ds_read_b128 v[234:237], v154 offset:21504
	ds_read_b128 v[238:241], v154 offset:22528
	ds_read_b128 v[242:245], v154 offset:23552
	global_load_lds_dwordx4 v[146:147], off
	s_add_i32 m0, s83, 0x2000
	s_add_u32 s90, s74, 0x40000
	v_lshl_add_u64 v[204:205], s[74:75], 0, v[140:141]
	s_addc_u32 s91, s75, 0
	s_add_i32 s83, s89, s5
	global_load_lds_dwordx4 v[204:205], off
	v_lshl_add_u64 v[206:207], s[90:91], 0, v[156:157]
	s_mov_b32 m0, s83
	s_nop 0
	global_load_lds_dwordx4 v[206:207], off
	v_lshl_add_u64 v[206:207], s[90:91], 0, v[140:141]
	s_add_i32 m0, s83, 0x2000
	s_nop 0
	global_load_lds_dwordx4 v[206:207], off
	v_lshl_add_u64 v[206:207], s[76:77], 0, v[136:137]
	s_mov_b32 m0, s6
	s_nop 0
	global_load_lds_dwordx4 v[206:207], off
	v_lshl_add_u64 v[206:207], s[76:77], 0, v[138:139]
	s_mov_b32 m0, s7
	s_nop 0
	global_load_lds_dwordx4 v[206:207], off
	s_waitcnt vmcnt(8)
	s_waitcnt lgkmcnt(0)
	s_barrier
; #define PG8_STAGE(bufoff, gbase, voff) do { _Pragma("unroll") for (int _i = 0; _i < 2; ++_i) \
;         __builtin_amdgcn_global_load_lds((const unsigned*)((const char*)(gbase) + (voff)[_i]), (LAS unsigned*)(lds + (bufoff) + ldsw + _i * 8192), 16, 0, 0); } while (0)
; #define PG8_LDA(dst, b, h) do { _Pragma("unroll") for (int m = 0; m < 4; ++m) _Pragma("unroll") for (int k = 0; k < 2; ++k) dst[m][k] = *(const LAS bf16x8*)(lds + PG8_SA(b, h) + aoff + m * 2048 + k * 1024); } while (0)
; #define PG8_LDB(dst, b, h) do { _Pragma("unroll") for (int n = 0; n < 2; ++n) _Pragma("unroll") for (int k = 0; k < 2; ++k) dst[n][k] = *(const LAS bf16x8*)(lds + PG8_SB(b, h) + boff + n * 2048 + k * 1024); } while (0)
; #define PG8_MMA(ai, bj, At, Bt) do { __builtin_amdgcn_s_setprio(1); _Pragma("unroll") for (int m = 0; m < 4; ++m) _Pragma("unroll") for (int n = 0; n < 2; ++n) _Pragma("unroll") for (int k = 0; k < 2; ++k) \
;         acc[ai][bj][m][n] = __builtin_amdgcn_mfma_f32_16x16x32_bf16(Bt[n][k], At[m][k], acc[ai][bj][m][n], 0, 0, 0); __builtin_amdgcn_s_setprio(0); } while (0)
; #define PG8_WAIT_V(n) asm volatile("s_waitcnt vmcnt(" #n ")" ::: "memory")
; #define PG8_WAIT_L(n) asm volatile("s_waitcnt lgkmcnt(" #n ")" ::: "memory")
; #define PG8_BAR __builtin_amdgcn_s_barrier()
; #define PG8_SCHED __builtin_amdgcn_sched_barrier(0)
;     ...
;             PG8_WAIT_V(8); PG8_WAIT_L(0); PG8_BAR; PG8_MMA(1, 0, At, B0); PG8_MMA(1, 1, At, B1); PG8_BAR; PG8_SCHED;
;             PG8_LDB(B0, 1, 0); PG8_LDB(B1, 1, 1); PG8_SCHED; PG8_LDA(At, 1, 0); PG8_STAGE(PG8_SA(0, 1), a2 + hA, voffA);
;             PG8_WAIT_V(8); PG8_WAIT_L(0); PG8_BAR; PG8_MMA(0, 0, At, B0); PG8_MMA(0, 1, At, B1); PG8_BAR; PG8_SCHED;
	s_setprio 1
	s_waitcnt lgkmcnt(0)
	v_mfma_f32_16x16x32_bf16 v[92:95], v[100:103], v[196:199], v[92:95]
	v_mfma_f32_16x16x32_bf16 v[92:95], v[168:171], v[200:203], v[92:95]
	v_mfma_f32_16x16x32_bf16 v[88:91], v[176:179], v[200:203], v[88:91]
	v_mfma_f32_16x16x32_bf16 v[88:91], v[172:175], v[196:199], v[88:91]
	v_mfma_f32_16x16x32_bf16 v[80:83], v[172:175], v[208:211], v[80:83]
	v_mfma_f32_16x16x32_bf16 v[80:83], v[176:179], v[214:217], v[80:83]
	v_mfma_f32_16x16x32_bf16 v[84:87], v[168:171], v[214:217], v[84:87]
	v_mfma_f32_16x16x32_bf16 v[84:87], v[100:103], v[208:211], v[84:87]
	v_mfma_f32_16x16x32_bf16 v[76:79], v[100:103], v[230:233], v[76:79]
	v_mfma_f32_16x16x32_bf16 v[76:79], v[168:171], v[234:237], v[76:79]
	v_mfma_f32_16x16x32_bf16 v[72:75], v[176:179], v[234:237], v[72:75]
	v_mfma_f32_16x16x32_bf16 v[72:75], v[172:175], v[230:233], v[72:75]
	v_mfma_f32_16x16x32_bf16 v[60:63], v[172:175], v[238:241], v[60:63]
	v_mfma_f32_16x16x32_bf16 v[60:63], v[176:179], v[242:245], v[60:63]
	v_mfma_f32_16x16x32_bf16 v[64:67], v[168:171], v[242:245], v[64:67]
	v_mfma_f32_16x16x32_bf16 v[64:67], v[100:103], v[238:241], v[64:67]
	s_setprio 0
	s_setprio 1
	v_mfma_f32_16x16x32_bf16 v[28:31], v[180:183], v[196:199], v[28:31]
	v_mfma_f32_16x16x32_bf16 v[28:31], v[184:187], v[200:203], v[28:31]
	v_mfma_f32_16x16x32_bf16 v[24:27], v[192:195], v[200:203], v[24:27]
	v_mfma_f32_16x16x32_bf16 v[24:27], v[188:191], v[196:199], v[24:27]
	v_mfma_f32_16x16x32_bf16 v[16:19], v[188:191], v[208:211], v[16:19]
	v_mfma_f32_16x16x32_bf16 v[16:19], v[192:195], v[214:217], v[16:19]
	v_mfma_f32_16x16x32_bf16 v[20:23], v[184:187], v[214:217], v[20:23]
	v_mfma_f32_16x16x32_bf16 v[20:23], v[180:183], v[208:211], v[20:23]
	v_mfma_f32_16x16x32_bf16 v[12:15], v[180:183], v[230:233], v[12:15]
	v_mfma_f32_16x16x32_bf16 v[12:15], v[184:187], v[234:237], v[12:15]
	v_mfma_f32_16x16x32_bf16 v[8:11], v[192:195], v[234:237], v[8:11]
	v_mfma_f32_16x16x32_bf16 v[8:11], v[188:191], v[230:233], v[8:11]
	v_mfma_f32_16x16x32_bf16 v[0:3], v[188:191], v[238:241], v[0:3]
	v_mfma_f32_16x16x32_bf16 v[0:3], v[192:195], v[242:245], v[0:3]
	v_mfma_f32_16x16x32_bf16 v[4:7], v[184:187], v[242:245], v[4:7]
	v_mfma_f32_16x16x32_bf16 v[4:7], v[180:183], v[238:241], v[4:7]
	s_setprio 0
	s_barrier
	s_add_i32 s83, 0, 0x18000
	v_add_u32_e32 v155, s83, v150
	s_add_i32 s89, 0, 0x1c000
	ds_read_b128 v[100:103], v155
	ds_read_b128 v[168:171], v155 offset:1024
	ds_read_b128 v[172:175], v155 offset:2048
	ds_read_b128 v[176:179], v155 offset:3072
	v_add_u32_e32 v155, s89, v150
	ds_read_b128 v[180:183], v155
	ds_read_b128 v[184:187], v155 offset:1024
	ds_read_b128 v[188:191], v155 offset:2048
	ds_read_b128 v[192:195], v155 offset:3072
	s_add_u32 s76, s76, 0x40000
	s_addc_u32 s77, s77, 0
	s_mov_b32 m0, s8
	v_lshl_add_u64 v[206:207], s[76:77], 0, v[136:137]
	ds_read_b128 v[196:199], v154 offset:32768
	ds_read_b128 v[200:203], v154 offset:33792
	ds_read_b128 v[208:211], v154 offset:34816
	ds_read_b128 v[214:217], v154 offset:35840
	ds_read_b128 v[230:233], v154 offset:36864
	ds_read_b128 v[234:237], v154 offset:37888
	ds_read_b128 v[238:241], v154 offset:38912
	ds_read_b128 v[242:245], v154 offset:39936
	global_load_lds_dwordx4 v[206:207], off
	v_lshl_add_u64 v[206:207], s[76:77], 0, v[138:139]
	s_mov_b32 m0, s9
	s_nop 0
	global_load_lds_dwordx4 v[206:207], off
	s_waitcnt vmcnt(8)
	s_waitcnt lgkmcnt(0)
	s_barrier
	s_setprio 1
	s_waitcnt lgkmcnt(0)
	v_mfma_f32_16x16x32_bf16 v[132:135], v[100:103], v[196:199], v[132:135]
	v_mfma_f32_16x16x32_bf16 v[132:135], v[168:171], v[200:203], v[132:135]
	v_mfma_f32_16x16x32_bf16 v[128:131], v[176:179], v[200:203], v[128:131]
	v_mfma_f32_16x16x32_bf16 v[128:131], v[172:175], v[196:199], v[128:131]
	v_mfma_f32_16x16x32_bf16 v[120:123], v[172:175], v[208:211], v[120:123]
	v_mfma_f32_16x16x32_bf16 v[120:123], v[176:179], v[214:217], v[120:123]
	v_mfma_f32_16x16x32_bf16 v[124:127], v[168:171], v[214:217], v[124:127]
	v_mfma_f32_16x16x32_bf16 v[124:127], v[100:103], v[208:211], v[124:127]
	v_mfma_f32_16x16x32_bf16 v[116:119], v[100:103], v[230:233], v[116:119]
	v_mfma_f32_16x16x32_bf16 v[116:119], v[168:171], v[234:237], v[116:119]
	v_mfma_f32_16x16x32_bf16 v[112:115], v[176:179], v[234:237], v[112:115]
	v_mfma_f32_16x16x32_bf16 v[112:115], v[172:175], v[230:233], v[112:115]
	v_mfma_f32_16x16x32_bf16 v[104:107], v[172:175], v[238:241], v[104:107]
	v_mfma_f32_16x16x32_bf16 v[104:107], v[176:179], v[242:245], v[104:107]
	v_mfma_f32_16x16x32_bf16 v[108:111], v[168:171], v[242:245], v[108:111]
	v_mfma_f32_16x16x32_bf16 v[108:111], v[100:103], v[238:241], v[108:111]
	s_setprio 0
	s_setprio 1
	v_mfma_f32_16x16x32_bf16 v[68:71], v[180:183], v[196:199], v[68:71]
	v_mfma_f32_16x16x32_bf16 v[68:71], v[184:187], v[200:203], v[68:71]
	v_mfma_f32_16x16x32_bf16 v[56:59], v[192:195], v[200:203], v[56:59]
	v_mfma_f32_16x16x32_bf16 v[56:59], v[188:191], v[196:199], v[56:59]
	v_mfma_f32_16x16x32_bf16 v[48:51], v[188:191], v[208:211], v[48:51]
	v_mfma_f32_16x16x32_bf16 v[48:51], v[192:195], v[214:217], v[48:51]
	v_mfma_f32_16x16x32_bf16 v[52:55], v[184:187], v[214:217], v[52:55]
	v_mfma_f32_16x16x32_bf16 v[52:55], v[180:183], v[208:211], v[52:55]
	v_mfma_f32_16x16x32_bf16 v[44:47], v[180:183], v[230:233], v[44:47]
	v_mfma_f32_16x16x32_bf16 v[44:47], v[184:187], v[234:237], v[44:47]
	v_mfma_f32_16x16x32_bf16 v[40:43], v[192:195], v[234:237], v[40:43]
	v_mfma_f32_16x16x32_bf16 v[40:43], v[188:191], v[230:233], v[40:43]
	v_mfma_f32_16x16x32_bf16 v[32:35], v[188:191], v[238:241], v[32:35]
	v_mfma_f32_16x16x32_bf16 v[32:35], v[192:195], v[242:245], v[32:35]
	v_mfma_f32_16x16x32_bf16 v[36:39], v[184:187], v[242:245], v[36:39]
	v_mfma_f32_16x16x32_bf16 v[36:39], v[180:183], v[238:241], v[36:39]
	s_setprio 0
	s_barrier
; #define PG8_STAGE(bufoff, gbase, voff) do { _Pragma("unroll") for (int _i = 0; _i < 2; ++_i) \
;         __builtin_amdgcn_global_load_lds((const unsigned*)((const char*)(gbase) + (voff)[_i]), (LAS unsigned*)(lds + (bufoff) + ldsw + _i * 8192), 16, 0, 0); } while (0)
; #define PG8_LDA(dst, b, h) do { _Pragma("unroll") for (int m = 0; m < 4; ++m) _Pragma("unroll") for (int k = 0; k < 2; ++k) dst[m][k] = *(const LAS bf16x8*)(lds + PG8_SA(b, h) + aoff + m * 2048 + k * 1024); } while (0)
; #define PG8_MMA(ai, bj, At, Bt) do { __builtin_amdgcn_s_setprio(1); _Pragma("unroll") for (int m = 0; m < 4; ++m) _Pragma("unroll") for (int n = 0; n < 2; ++n) _Pragma("unroll") for (int k = 0; k < 2; ++k) \
;         acc[ai][bj][m][n] = __builtin_amdgcn_mfma_f32_16x16x32_bf16(Bt[n][k], At[m][k], acc[ai][bj][m][n], 0, 0, 0); __builtin_amdgcn_s_setprio(0); } while (0)
; #define PG8_WAIT_V(n) asm volatile("s_waitcnt vmcnt(" #n ")" ::: "memory")
; #define PG8_WAIT_L(n) asm volatile("s_waitcnt lgkmcnt(" #n ")" ::: "memory")
; #define PG8_BAR __builtin_amdgcn_s_barrier()
; #define PG8_SCHED __builtin_amdgcn_sched_barrier(0)
;     ...
;             PG8_LDA(At, 1, 1); PG8_STAGE(PG8_SB(1, 0), b3, voffB); PG8_STAGE(PG8_SB(1, 1), b3 + hB, voffB); PG8_STAGE(PG8_SA(1, 0), a3, voffA);
;             PG8_WAIT_V(8); PG8_WAIT_L(0); PG8_BAR; PG8_MMA(1, 0, At, B0); PG8_MMA(1, 1, At, B1); PG8_BAR; PG8_SCHED;
;     ...
;         }
;         if constexpr (ALIGN_EPI) { if (wr == 0) PG8_BAR; }
	s_add_i32 s76, s83, s5
	v_lshl_add_u64 v[146:147], v[146:147], 0, s[38:39]
	s_mov_b32 m0, s76
	ds_read_b128 v[196:199], v154 offset:49152
	ds_read_b128 v[200:203], v154 offset:50176
	ds_read_b128 v[208:211], v154 offset:51200
	ds_read_b128 v[214:217], v154 offset:52224
	ds_read_b128 v[230:233], v154 offset:53248
	ds_read_b128 v[234:237], v154 offset:54272
	ds_read_b128 v[238:241], v154 offset:55296
	ds_read_b128 v[242:245], v154 offset:56320
	global_load_lds_dwordx4 v[146:147], off
	s_add_i32 m0, s76, 0x2000
	s_add_u32 s74, s74, 0x40080
	v_lshl_add_u64 v[146:147], v[204:205], 0, s[38:39]
	s_addc_u32 s75, s75, 0
	s_add_i32 s76, s89, s5
	global_load_lds_dwordx4 v[146:147], off
	v_lshl_add_u64 v[146:147], s[74:75], 0, v[156:157]
	s_mov_b32 m0, s76
	s_nop 0
	global_load_lds_dwordx4 v[146:147], off
	v_lshl_add_u64 v[146:147], s[74:75], 0, v[140:141]
	s_add_i32 m0, s76, 0x2000
	s_nop 0
	global_load_lds_dwordx4 v[146:147], off
	v_lshl_add_u64 v[146:147], s[72:73], 0, v[136:137]
	s_mov_b32 m0, s42
	s_nop 0
	global_load_lds_dwordx4 v[146:147], off
	v_lshl_add_u64 v[146:147], s[72:73], 0, v[138:139]
	s_mov_b32 m0, s43
	s_nop 0
	global_load_lds_dwordx4 v[146:147], off
	s_waitcnt vmcnt(8)
	s_waitcnt lgkmcnt(0)
	s_barrier
	s_setprio 1
	s_waitcnt lgkmcnt(0)
	v_mfma_f32_16x16x32_bf16 v[92:95], v[100:103], v[196:199], v[92:95]
	v_mfma_f32_16x16x32_bf16 v[92:95], v[168:171], v[200:203], v[92:95]
	v_mfma_f32_16x16x32_bf16 v[88:91], v[176:179], v[200:203], v[88:91]
	v_mfma_f32_16x16x32_bf16 v[88:91], v[172:175], v[196:199], v[88:91]
	v_mfma_f32_16x16x32_bf16 v[80:83], v[172:175], v[208:211], v[80:83]
	v_mfma_f32_16x16x32_bf16 v[80:83], v[176:179], v[214:217], v[80:83]
	v_mfma_f32_16x16x32_bf16 v[84:87], v[168:171], v[214:217], v[84:87]
	v_mfma_f32_16x16x32_bf16 v[84:87], v[100:103], v[208:211], v[84:87]
	v_mfma_f32_16x16x32_bf16 v[76:79], v[100:103], v[230:233], v[76:79]
	v_mfma_f32_16x16x32_bf16 v[76:79], v[168:171], v[234:237], v[76:79]
	v_mfma_f32_16x16x32_bf16 v[72:75], v[176:179], v[234:237], v[72:75]
	v_mfma_f32_16x16x32_bf16 v[72:75], v[172:175], v[230:233], v[72:75]
	v_mfma_f32_16x16x32_bf16 v[60:63], v[172:175], v[238:241], v[60:63]
	v_mfma_f32_16x16x32_bf16 v[60:63], v[176:179], v[242:245], v[60:63]
	v_mfma_f32_16x16x32_bf16 v[64:67], v[168:171], v[242:245], v[64:67]
	v_mfma_f32_16x16x32_bf16 v[64:67], v[100:103], v[238:241], v[64:67]
	s_setprio 0
	s_setprio 1
	v_mfma_f32_16x16x32_bf16 v[28:31], v[180:183], v[196:199], v[28:31]
	v_mfma_f32_16x16x32_bf16 v[28:31], v[184:187], v[200:203], v[28:31]
	v_mfma_f32_16x16x32_bf16 v[24:27], v[192:195], v[200:203], v[24:27]
	v_mfma_f32_16x16x32_bf16 v[24:27], v[188:191], v[196:199], v[24:27]
	v_mfma_f32_16x16x32_bf16 v[16:19], v[188:191], v[208:211], v[16:19]
	v_mfma_f32_16x16x32_bf16 v[16:19], v[192:195], v[214:217], v[16:19]
	v_mfma_f32_16x16x32_bf16 v[20:23], v[184:187], v[214:217], v[20:23]
	v_mfma_f32_16x16x32_bf16 v[20:23], v[180:183], v[208:211], v[20:23]
	v_mfma_f32_16x16x32_bf16 v[12:15], v[180:183], v[230:233], v[12:15]
	v_mfma_f32_16x16x32_bf16 v[12:15], v[184:187], v[234:237], v[12:15]
	v_mfma_f32_16x16x32_bf16 v[8:11], v[192:195], v[234:237], v[8:11]
	v_mfma_f32_16x16x32_bf16 v[8:11], v[188:191], v[230:233], v[8:11]
	v_mfma_f32_16x16x32_bf16 v[0:3], v[188:191], v[238:241], v[0:3]
	v_mfma_f32_16x16x32_bf16 v[0:3], v[192:195], v[242:245], v[0:3]
	v_mfma_f32_16x16x32_bf16 v[4:7], v[184:187], v[242:245], v[4:7]
	v_mfma_f32_16x16x32_bf16 v[4:7], v[180:183], v[238:241], v[4:7]
	s_setprio 0
	s_barrier
	s_add_i32 s82, s82, 2
	s_add_u32 s52, s52, 0x100
	s_addc_u32 s53, s53, 0
	s_cmp_gt_u32 s82, 13
	s_cbranch_scc0 .LBB0_191
	s_and_b64 vcc, exec, s[14:15]
	s_cbranch_vccz .LBB0_194
	s_barrier

; #define PG8_STAGE(bufoff, gbase, voff) do { _Pragma("unroll") for (int _i = 0; _i < 2; ++_i) \
;         __builtin_amdgcn_global_load_lds((const unsigned*)((const char*)(gbase) + (voff)[_i]), (LAS unsigned*)(lds + (bufoff) + ldsw + _i * 8192), 16, 0, 0); } while (0)
; #define PG8_LDA(dst, b, h) do { _Pragma("unroll") for (int m = 0; m < 4; ++m) _Pragma("unroll") for (int k = 0; k < 2; ++k) dst[m][k] = *(const LAS bf16x8*)(lds + PG8_SA(b, h) + aoff + m * 2048 + k * 1024); } while (0)
; #define PG8_LDB(dst, b, h) do { _Pragma("unroll") for (int n = 0; n < 2; ++n) _Pragma("unroll") for (int k = 0; k < 2; ++k) dst[n][k] = *(const LAS bf16x8*)(lds + PG8_SB(b, h) + boff + n * 2048 + k * 1024); } while (0)
; #define PG8_WAIT_V(n) asm volatile("s_waitcnt vmcnt(" #n ")" ::: "memory")
; #define PG8_WAIT_L(n) asm volatile("s_waitcnt lgkmcnt(" #n ")" ::: "memory")
; #define PG8_BAR __builtin_amdgcn_s_barrier()
; #define PG8_SCHED __builtin_amdgcn_sched_barrier(0)
;     ...
;         for (int t = 0; t < nt; t += 2) {
;             const bool last = (t == nt - 2);
;             const char* a1 = PG8_ATILE(cA, cA2, t + 1);
;             const char* a2 = last ? nA : PG8_ATILE(cA, cA2, t + 2); const char* b2 = last ? nB : cB + (size_t)(t + 2) * 128;
;             const char* a3 = last ? nA + kA1 : PG8_ATILE(cA, cA2, t + 3); const char* b3 = b2 + kB1;
;             if constexpr (SP2) {
;             PG8_LDB(B0, 0, 0); PG8_LDB(B1, 0, 1); PG8_SCHED; PG8_LDA(At, 0, 0); PG8_STAGE(PG8_SA(1, 1), a1 + hA, voffA);
;             PG8_WAIT_V(8); PG8_WAIT_L(0); PG8_BAR; PG8_MMA(0, 0, At, B0); PG8_MMA(0, 1, At, B1); PG8_BAR; PG8_SCHED;
;             PG8_LDA(At, 0, 1); PG8_STAGE(PG8_SB(0, 0), b2, voffB); PG8_STAGE(PG8_SB(0, 1), b2 + hB, voffB); PG8_STAGE(PG8_SA(0, 0), a2, voffA);
;             PG8_WAIT_V(8); PG8_WAIT_L(0); PG8_BAR; PG8_MMA(1, 0, At, B0); PG8_MMA(1, 1, At, B1); PG8_BAR; PG8_SCHED;
;             PG8_LDB(B0, 1, 0); PG8_LDB(B1, 1, 1); PG8_SCHED; PG8_LDA(At, 1, 0); PG8_STAGE(PG8_SA(0, 1), a2 + hA, voffA);
;             PG8_WAIT_V(8); PG8_WAIT_L(0); PG8_BAR; PG8_MMA(0, 0, At, B0); PG8_MMA(0, 1, At, B1); PG8_BAR; PG8_SCHED;
;             PG8_LDA(At, 1, 1); PG8_STAGE(PG8_SB(1, 0), b3, voffB); PG8_STAGE(PG8_SB(1, 1), b3 + hB, voffB); PG8_STAGE(PG8_SA(1, 0), a3, voffA);
;             PG8_WAIT_V(8); PG8_WAIT_L(0); PG8_BAR; PG8_MMA(1, 0, At, B0); PG8_MMA(1, 1, At, B1); PG8_BAR; PG8_SCHED;
.LBB0_271:
	s_add_u32 s31, s52, s90
	s_addc_u32 s36, s53, s91
	s_add_u32 s45, s31, 0x100
	s_addc_u32 s54, s36, 0
	s_add_u32 s55, s8, s90
	s_addc_u32 s74, s9, s91
	s_add_u32 s31, s31, 0x180
	s_addc_u32 s36, s36, 0
	s_add_i32 s82, 0, 0x10000
	s_add_i32 s83, 0, 0x14000
	v_add_u32_e32 v144, s82, v231
	v_add_u32_e32 v156, s83, v231
	ds_read_b128 v[132:135], v144
	ds_read_b128 v[136:139], v144 offset:1024
	ds_read_b128 v[140:143], v144 offset:2048
	ds_read_b128 v[144:147], v144 offset:3072
	ds_read_b128 v[148:151], v156
	ds_read_b128 v[152:155], v156 offset:1024
	ds_read_b128 v[182:185], v156 offset:2048
	ds_read_b128 v[186:189], v156 offset:3072
	s_cmpk_eq_i32 s90, 0x700
	s_cselect_b32 s73, s7, s36
	s_cselect_b32 s72, s6, s31
	s_cselect_b32 s75, s4, s74
	s_cselect_b32 s74, s5, s55
	s_cselect_b32 s77, s1, s54
	s_cselect_b32 s76, s3, s45
	v_lshl_add_u64 v[206:207], v[128:129], 0, s[90:91]
	s_add_i32 m0, s80, 0xc000
	ds_read_b128 v[190:193], v233
	ds_read_b128 v[194:197], v233 offset:1024
	ds_read_b128 v[198:201], v233 offset:2048
	ds_read_b128 v[202:205], v233 offset:3072
	ds_read_b128 v[208:211], v233 offset:4096
	ds_read_b128 v[214:217], v233 offset:5120
	ds_read_b128 v[234:237], v233 offset:6144
	ds_read_b128 v[238:241], v233 offset:7168
	global_load_lds_dwordx4 v[206:207], off
	v_lshl_add_u64 v[206:207], v[130:131], 0, s[90:91]
	s_add_i32 m0, s80, 0xe000
	s_nop 0
	global_load_lds_dwordx4 v[206:207], off
	s_waitcnt vmcnt(8)
	s_waitcnt lgkmcnt(0)
	s_barrier
	s_setprio 1
	s_waitcnt lgkmcnt(0)
	v_mfma_f32_16x16x32_bf16 v[124:127], v[132:135], v[190:193], v[124:127]
	v_mfma_f32_16x16x32_bf16 v[124:127], v[136:139], v[194:197], v[124:127]
	v_mfma_f32_16x16x32_bf16 v[120:123], v[144:147], v[194:197], v[120:123]
	v_mfma_f32_16x16x32_bf16 v[120:123], v[140:143], v[190:193], v[120:123]
	v_mfma_f32_16x16x32_bf16 v[104:107], v[140:143], v[198:201], v[104:107]
	v_mfma_f32_16x16x32_bf16 v[104:107], v[144:147], v[202:205], v[104:107]
	v_mfma_f32_16x16x32_bf16 v[108:111], v[136:139], v[202:205], v[108:111]
	v_mfma_f32_16x16x32_bf16 v[108:111], v[132:135], v[198:201], v[108:111]
	v_mfma_f32_16x16x32_bf16 v[92:95], v[132:135], v[208:211], v[92:95]
	v_mfma_f32_16x16x32_bf16 v[92:95], v[136:139], v[214:217], v[92:95]
	v_mfma_f32_16x16x32_bf16 v[88:91], v[144:147], v[214:217], v[88:91]
	v_mfma_f32_16x16x32_bf16 v[88:91], v[140:143], v[208:211], v[88:91]
	v_mfma_f32_16x16x32_bf16 v[72:75], v[140:143], v[234:237], v[72:75]
	v_mfma_f32_16x16x32_bf16 v[72:75], v[144:147], v[238:241], v[72:75]
	v_mfma_f32_16x16x32_bf16 v[76:79], v[136:139], v[238:241], v[76:79]
	v_mfma_f32_16x16x32_bf16 v[76:79], v[132:135], v[234:237], v[76:79]
	s_setprio 0
	s_setprio 1
	v_mfma_f32_16x16x32_bf16 v[116:119], v[148:151], v[190:193], v[116:119]
	v_mfma_f32_16x16x32_bf16 v[116:119], v[152:155], v[194:197], v[116:119]
	v_mfma_f32_16x16x32_bf16 v[112:115], v[186:189], v[194:197], v[112:115]
	v_mfma_f32_16x16x32_bf16 v[112:115], v[182:185], v[190:193], v[112:115]
	v_mfma_f32_16x16x32_bf16 v[96:99], v[182:185], v[198:201], v[96:99]
	v_mfma_f32_16x16x32_bf16 v[96:99], v[186:189], v[202:205], v[96:99]
	v_mfma_f32_16x16x32_bf16 v[100:103], v[152:155], v[202:205], v[100:103]
	v_mfma_f32_16x16x32_bf16 v[100:103], v[148:151], v[198:201], v[100:103]
	v_mfma_f32_16x16x32_bf16 v[84:87], v[148:151], v[208:211], v[84:87]
	v_mfma_f32_16x16x32_bf16 v[84:87], v[152:155], v[214:217], v[84:87]
	v_mfma_f32_16x16x32_bf16 v[80:83], v[186:189], v[214:217], v[80:83]
	v_mfma_f32_16x16x32_bf16 v[80:83], v[182:185], v[208:211], v[80:83]
	v_mfma_f32_16x16x32_bf16 v[64:67], v[182:185], v[234:237], v[64:67]
	v_mfma_f32_16x16x32_bf16 v[64:67], v[186:189], v[238:241], v[64:67]
	v_mfma_f32_16x16x32_bf16 v[68:71], v[152:155], v[238:241], v[68:71]
	v_mfma_f32_16x16x32_bf16 v[68:71], v[148:151], v[234:237], v[68:71]
	s_setprio 0
	s_barrier
	s_add_i32 s31, s82, s79
	v_lshl_add_u64 v[206:207], s[74:75], 0, v[170:171]
	s_mov_b32 m0, s31
	ds_read_b128 v[190:193], v233 offset:16384
	ds_read_b128 v[194:197], v233 offset:17408
	ds_read_b128 v[198:201], v233 offset:18432
	ds_read_b128 v[202:205], v233 offset:19456
	ds_read_b128 v[208:211], v233 offset:20480
	ds_read_b128 v[214:217], v233 offset:21504
	ds_read_b128 v[234:237], v233 offset:22528
	ds_read_b128 v[238:241], v233 offset:23552
	global_load_lds_dwordx4 v[206:207], off
	s_add_i32 m0, s31, 0x2000
	s_add_u32 s54, s74, 0x40000
	v_lshl_add_u64 v[242:243], s[74:75], 0, v[174:175]
	s_addc_u32 s55, s75, 0
	s_add_i32 s31, s83, s79
	global_load_lds_dwordx4 v[242:243], off
	v_lshl_add_u64 v[244:245], s[54:55], 0, v[170:171]
	s_mov_b32 m0, s31
	s_nop 0
	global_load_lds_dwordx4 v[244:245], off
	v_lshl_add_u64 v[244:245], s[54:55], 0, v[174:175]
	s_add_i32 m0, s31, 0x2000
	s_nop 0
	global_load_lds_dwordx4 v[244:245], off
	v_lshl_add_u64 v[244:245], s[76:77], 0, v[168:169]
	s_mov_b32 m0, s80
	s_nop 0
	global_load_lds_dwordx4 v[244:245], off
	v_lshl_add_u64 v[244:245], s[76:77], 0, v[172:173]
	s_mov_b32 m0, s81
	s_nop 0
	global_load_lds_dwordx4 v[244:245], off
	s_waitcnt vmcnt(8)
	s_waitcnt lgkmcnt(0)
	s_barrier
; #define PG8_STAGE(bufoff, gbase, voff) do { _Pragma("unroll") for (int _i = 0; _i < 2; ++_i) \
;         __builtin_amdgcn_global_load_lds((const unsigned*)((const char*)(gbase) + (voff)[_i]), (LAS unsigned*)(lds + (bufoff) + ldsw + _i * 8192), 16, 0, 0); } while (0)
; #define PG8_LDA(dst, b, h) do { _Pragma("unroll") for (int m = 0; m < 4; ++m) _Pragma("unroll") for (int k = 0; k < 2; ++k) dst[m][k] = *(const LAS bf16x8*)(lds + PG8_SA(b, h) + aoff + m * 2048 + k * 1024); } while (0)
; #define PG8_LDB(dst, b, h) do { _Pragma("unroll") for (int n = 0; n < 2; ++n) _Pragma("unroll") for (int k = 0; k < 2; ++k) dst[n][k] = *(const LAS bf16x8*)(lds + PG8_SB(b, h) + boff + n * 2048 + k * 1024); } while (0)
; #define PG8_MMA(ai, bj, At, Bt) do { __builtin_amdgcn_s_setprio(1); _Pragma("unroll") for (int m = 0; m < 4; ++m) _Pragma("unroll") for (int n = 0; n < 2; ++n) _Pragma("unroll") for (int k = 0; k < 2; ++k) \
;         acc[ai][bj][m][n] = __builtin_amdgcn_mfma_f32_16x16x32_bf16(Bt[n][k], At[m][k], acc[ai][bj][m][n], 0, 0, 0); __builtin_amdgcn_s_setprio(0); } while (0)
; #define PG8_WAIT_V(n) asm volatile("s_waitcnt vmcnt(" #n ")" ::: "memory")
; #define PG8_WAIT_L(n) asm volatile("s_waitcnt lgkmcnt(" #n ")" ::: "memory")
; #define PG8_BAR __builtin_amdgcn_s_barrier()
; #define PG8_SCHED __builtin_amdgcn_sched_barrier(0)
;     ...
;             PG8_WAIT_V(8); PG8_WAIT_L(0); PG8_BAR; PG8_MMA(0, 0, At, B0); PG8_MMA(0, 1, At, B1); PG8_BAR; PG8_SCHED;
;             PG8_LDA(At, 0, 1); PG8_STAGE(PG8_SB(0, 0), b2, voffB); PG8_STAGE(PG8_SB(0, 1), b2 + hB, voffB); PG8_STAGE(PG8_SA(0, 0), a2, voffA);
;             PG8_WAIT_V(8); PG8_WAIT_L(0); PG8_BAR; PG8_MMA(1, 0, At, B0); PG8_MMA(1, 1, At, B1); PG8_BAR; PG8_SCHED;
;             PG8_LDB(B0, 1, 0); PG8_LDB(B1, 1, 1); PG8_SCHED; PG8_LDA(At, 1, 0); PG8_STAGE(PG8_SA(0, 1), a2 + hA, voffA);
;             PG8_WAIT_V(8); PG8_WAIT_L(0); PG8_BAR; PG8_MMA(0, 0, At, B0); PG8_MMA(0, 1, At, B1); PG8_BAR; PG8_SCHED;
;             PG8_LDA(At, 1, 1); PG8_STAGE(PG8_SB(1, 0), b3, voffB); PG8_STAGE(PG8_SB(1, 1), b3 + hB, voffB); PG8_STAGE(PG8_SA(1, 0), a3, voffA);
;             PG8_WAIT_V(8); PG8_WAIT_L(0); PG8_BAR; PG8_MMA(1, 0, At, B0); PG8_MMA(1, 1, At, B1); PG8_BAR; PG8_SCHED;
	s_setprio 1
	s_waitcnt lgkmcnt(0)
	v_mfma_f32_16x16x32_bf16 v[60:63], v[132:135], v[190:193], v[60:63]
	v_mfma_f32_16x16x32_bf16 v[60:63], v[136:139], v[194:197], v[60:63]
	v_mfma_f32_16x16x32_bf16 v[56:59], v[144:147], v[194:197], v[56:59]
	v_mfma_f32_16x16x32_bf16 v[56:59], v[140:143], v[190:193], v[56:59]
	v_mfma_f32_16x16x32_bf16 v[40:43], v[140:143], v[198:201], v[40:43]
	v_mfma_f32_16x16x32_bf16 v[40:43], v[144:147], v[202:205], v[40:43]
	v_mfma_f32_16x16x32_bf16 v[44:47], v[136:139], v[202:205], v[44:47]
	v_mfma_f32_16x16x32_bf16 v[44:47], v[132:135], v[198:201], v[44:47]
	v_mfma_f32_16x16x32_bf16 v[28:31], v[132:135], v[208:211], v[28:31]
	v_mfma_f32_16x16x32_bf16 v[28:31], v[136:139], v[214:217], v[28:31]
	v_mfma_f32_16x16x32_bf16 v[24:27], v[144:147], v[214:217], v[24:27]
	v_mfma_f32_16x16x32_bf16 v[24:27], v[140:143], v[208:211], v[24:27]
	v_mfma_f32_16x16x32_bf16 v[8:11], v[140:143], v[234:237], v[8:11]
	v_mfma_f32_16x16x32_bf16 v[8:11], v[144:147], v[238:241], v[8:11]
	v_mfma_f32_16x16x32_bf16 v[12:15], v[136:139], v[238:241], v[12:15]
	v_mfma_f32_16x16x32_bf16 v[12:15], v[132:135], v[234:237], v[12:15]
	s_setprio 0
	s_setprio 1
	v_mfma_f32_16x16x32_bf16 v[52:55], v[148:151], v[190:193], v[52:55]
	v_mfma_f32_16x16x32_bf16 v[52:55], v[152:155], v[194:197], v[52:55]
	v_mfma_f32_16x16x32_bf16 v[48:51], v[186:189], v[194:197], v[48:51]
	v_mfma_f32_16x16x32_bf16 v[48:51], v[182:185], v[190:193], v[48:51]
	v_mfma_f32_16x16x32_bf16 v[32:35], v[182:185], v[198:201], v[32:35]
	v_mfma_f32_16x16x32_bf16 v[32:35], v[186:189], v[202:205], v[32:35]
	v_mfma_f32_16x16x32_bf16 v[36:39], v[152:155], v[202:205], v[36:39]
	v_mfma_f32_16x16x32_bf16 v[36:39], v[148:151], v[198:201], v[36:39]
	v_mfma_f32_16x16x32_bf16 v[20:23], v[148:151], v[208:211], v[20:23]
	v_mfma_f32_16x16x32_bf16 v[20:23], v[152:155], v[214:217], v[20:23]
	v_mfma_f32_16x16x32_bf16 v[16:19], v[186:189], v[214:217], v[16:19]
	v_mfma_f32_16x16x32_bf16 v[16:19], v[182:185], v[208:211], v[16:19]
	v_mfma_f32_16x16x32_bf16 v[0:3], v[182:185], v[234:237], v[0:3]
	v_mfma_f32_16x16x32_bf16 v[0:3], v[186:189], v[238:241], v[0:3]
	v_mfma_f32_16x16x32_bf16 v[4:7], v[152:155], v[238:241], v[4:7]
	v_mfma_f32_16x16x32_bf16 v[4:7], v[148:151], v[234:237], v[4:7]
	s_setprio 0
	s_barrier
	s_add_i32 s31, 0, 0x18000
	s_add_i32 s36, 0, 0x1c000
	v_add_u32_e32 v144, s31, v231
	v_add_u32_e32 v156, s36, v231
	ds_read_b128 v[132:135], v144
	ds_read_b128 v[136:139], v144 offset:1024
	ds_read_b128 v[140:143], v144 offset:2048
	ds_read_b128 v[144:147], v144 offset:3072
	ds_read_b128 v[148:151], v156
	ds_read_b128 v[152:155], v156 offset:1024
	ds_read_b128 v[182:185], v156 offset:2048
	ds_read_b128 v[186:189], v156 offset:3072
	s_add_u32 s54, s76, 0x40000
	s_addc_u32 s55, s77, 0
	s_mov_b32 m0, s89
	v_lshl_add_u64 v[244:245], s[54:55], 0, v[168:169]
	ds_read_b128 v[190:193], v233 offset:32768
	ds_read_b128 v[194:197], v233 offset:33792
	ds_read_b128 v[198:201], v233 offset:34816
	ds_read_b128 v[202:205], v233 offset:35840
	ds_read_b128 v[208:211], v233 offset:36864
	ds_read_b128 v[214:217], v233 offset:37888
	ds_read_b128 v[234:237], v233 offset:38912
	ds_read_b128 v[238:241], v233 offset:39936
	global_load_lds_dwordx4 v[244:245], off
	v_lshl_add_u64 v[244:245], s[54:55], 0, v[172:173]
	s_mov_b32 m0, s92
	s_nop 0
	global_load_lds_dwordx4 v[244:245], off
	s_waitcnt vmcnt(8)
	s_waitcnt lgkmcnt(0)
	s_barrier
	s_setprio 1
	s_waitcnt lgkmcnt(0)
	v_mfma_f32_16x16x32_bf16 v[124:127], v[132:135], v[190:193], v[124:127]
	v_mfma_f32_16x16x32_bf16 v[124:127], v[136:139], v[194:197], v[124:127]
	v_mfma_f32_16x16x32_bf16 v[120:123], v[144:147], v[194:197], v[120:123]
	v_mfma_f32_16x16x32_bf16 v[120:123], v[140:143], v[190:193], v[120:123]
	v_mfma_f32_16x16x32_bf16 v[104:107], v[140:143], v[198:201], v[104:107]
	v_mfma_f32_16x16x32_bf16 v[104:107], v[144:147], v[202:205], v[104:107]
	v_mfma_f32_16x16x32_bf16 v[108:111], v[136:139], v[202:205], v[108:111]
	v_mfma_f32_16x16x32_bf16 v[108:111], v[132:135], v[198:201], v[108:111]
	v_mfma_f32_16x16x32_bf16 v[92:95], v[132:135], v[208:211], v[92:95]
	v_mfma_f32_16x16x32_bf16 v[92:95], v[136:139], v[214:217], v[92:95]
	v_mfma_f32_16x16x32_bf16 v[88:91], v[144:147], v[214:217], v[88:91]
	v_mfma_f32_16x16x32_bf16 v[88:91], v[140:143], v[208:211], v[88:91]
	v_mfma_f32_16x16x32_bf16 v[72:75], v[140:143], v[234:237], v[72:75]
	v_mfma_f32_16x16x32_bf16 v[72:75], v[144:147], v[238:241], v[72:75]
	v_mfma_f32_16x16x32_bf16 v[76:79], v[136:139], v[238:241], v[76:79]
	v_mfma_f32_16x16x32_bf16 v[76:79], v[132:135], v[234:237], v[76:79]
	s_setprio 0
	s_setprio 1
	v_mfma_f32_16x16x32_bf16 v[116:119], v[148:151], v[190:193], v[116:119]
	v_mfma_f32_16x16x32_bf16 v[116:119], v[152:155], v[194:197], v[116:119]
	v_mfma_f32_16x16x32_bf16 v[112:115], v[186:189], v[194:197], v[112:115]
	v_mfma_f32_16x16x32_bf16 v[112:115], v[182:185], v[190:193], v[112:115]
	v_mfma_f32_16x16x32_bf16 v[96:99], v[182:185], v[198:201], v[96:99]
	v_mfma_f32_16x16x32_bf16 v[96:99], v[186:189], v[202:205], v[96:99]
	v_mfma_f32_16x16x32_bf16 v[100:103], v[152:155], v[202:205], v[100:103]
	v_mfma_f32_16x16x32_bf16 v[100:103], v[148:151], v[198:201], v[100:103]
	v_mfma_f32_16x16x32_bf16 v[84:87], v[148:151], v[208:211], v[84:87]
	v_mfma_f32_16x16x32_bf16 v[84:87], v[152:155], v[214:217], v[84:87]
	v_mfma_f32_16x16x32_bf16 v[80:83], v[186:189], v[214:217], v[80:83]
	v_mfma_f32_16x16x32_bf16 v[80:83], v[182:185], v[208:211], v[80:83]
	v_mfma_f32_16x16x32_bf16 v[64:67], v[182:185], v[234:237], v[64:67]
	v_mfma_f32_16x16x32_bf16 v[64:67], v[186:189], v[238:241], v[64:67]
	v_mfma_f32_16x16x32_bf16 v[68:71], v[152:155], v[238:241], v[68:71]
	v_mfma_f32_16x16x32_bf16 v[68:71], v[148:151], v[234:237], v[68:71]
	s_setprio 0
	s_barrier
; #define PG8_STAGE(bufoff, gbase, voff) do { _Pragma("unroll") for (int _i = 0; _i < 2; ++_i) \
;         __builtin_amdgcn_global_load_lds((const unsigned*)((const char*)(gbase) + (voff)[_i]), (LAS unsigned*)(lds + (bufoff) + ldsw + _i * 8192), 16, 0, 0); } while (0)
; #define PG8_LDA(dst, b, h) do { _Pragma("unroll") for (int m = 0; m < 4; ++m) _Pragma("unroll") for (int k = 0; k < 2; ++k) dst[m][k] = *(const LAS bf16x8*)(lds + PG8_SA(b, h) + aoff + m * 2048 + k * 1024); } while (0)
; #define PG8_LDB(dst, b, h) do { _Pragma("unroll") for (int n = 0; n < 2; ++n) _Pragma("unroll") for (int k = 0; k < 2; ++k) dst[n][k] = *(const LAS bf16x8*)(lds + PG8_SB(b, h) + boff + n * 2048 + k * 1024); } while (0)
; #define PG8_WAIT_V(n) asm volatile("s_waitcnt vmcnt(" #n ")" ::: "memory")
;     ...
;             PG8_LDA(At, 1, 1); PG8_STAGE(PG8_SB(1, 0), b3, voffB); PG8_STAGE(PG8_SB(1, 1), b3 + hB, voffB); PG8_STAGE(PG8_SA(1, 0), a3, voffA);
;             PG8_WAIT_V(8); PG8_WAIT_L(0); PG8_BAR; PG8_MMA(1, 0, At, B0); PG8_MMA(1, 1, At, B1); PG8_BAR; PG8_SCHED;
;             } else {
;             PG8_LDB(B0, 0, 0); PG8_SCHED; PG8_LDA(At, 0, 0); PG8_STAGE(PG8_SA(1, 1), a1 + hA, voffA);
;             PG8_WAIT_L(8); PG8_BAR; PG8_WAIT_L(0); PG8_MMA(0, 0, At, B0); PG8_BAR; PG8_SCHED;
;             PG8_LDB(B1, 0, 1); PG8_STAGE(PG8_SB(0, 0), b2, voffB);
;             PG8_BAR; PG8_WAIT_L(0); PG8_MMA(0, 1, At, B1); PG8_BAR;
;             PG8_LDA(At, 0, 1); PG8_STAGE(PG8_SA(0, 0), a2, voffA);
;             PG8_BAR; PG8_WAIT_L(0); PG8_MMA(1, 0, At, B0); PG8_BAR; PG8_SCHED;
;             PG8_STAGE(PG8_SB(0, 1), b2 + hB, voffB);
;             PG8_WAIT_V(6); PG8_BAR; PG8_MMA(1, 1, At, B1); PG8_BAR;
;             PG8_LDB(B0, 1, 0); PG8_SCHED; PG8_LDA(At, 1, 0); PG8_STAGE(PG8_SA(0, 1), a2 + hA, voffA);
;             PG8_WAIT_L(8); PG8_BAR; PG8_WAIT_L(0); PG8_MMA(0, 0, At, B0); PG8_BAR; PG8_SCHED;
;             PG8_LDB(B1, 1, 1); PG8_STAGE(PG8_SB(1, 0), b3, voffB);
;             PG8_BAR; PG8_WAIT_L(0); PG8_MMA(0, 1, At, B1); PG8_BAR;
;             PG8_LDA(At, 1, 1); PG8_STAGE(PG8_SA(1, 0), a3, voffA);
;             PG8_BAR; PG8_WAIT_L(0); PG8_MMA(1, 0, At, B0); PG8_BAR; PG8_SCHED;
;             PG8_STAGE(PG8_SB(1, 1), b3 + hB, voffB);
;             PG8_WAIT_V(6); PG8_BAR; PG8_MMA(1, 1, At, B1); PG8_BAR;
;             }
;         }
;         if constexpr (ALIGN_EPI) { if (wr == 0) PG8_BAR; }
	s_add_i32 s31, s31, s79
	v_lshl_add_u64 v[206:207], v[206:207], 0, s[38:39]
	s_mov_b32 m0, s31
	ds_read_b128 v[190:193], v233 offset:49152
	ds_read_b128 v[194:197], v233 offset:50176
	ds_read_b128 v[198:201], v233 offset:51200
	ds_read_b128 v[202:205], v233 offset:52224
	ds_read_b128 v[208:211], v233 offset:53248
	ds_read_b128 v[214:217], v233 offset:54272
	ds_read_b128 v[234:237], v233 offset:55296
	ds_read_b128 v[238:241], v233 offset:56320
	global_load_lds_dwordx4 v[206:207], off
	s_add_i32 m0, s31, 0x2000
	s_add_u32 s54, s74, 0x40080
	v_lshl_add_u64 v[206:207], v[242:243], 0, s[38:39]
	s_addc_u32 s55, s75, 0
	s_add_i32 s31, s36, s79
	global_load_lds_dwordx4 v[206:207], off
	v_lshl_add_u64 v[206:207], s[54:55], 0, v[170:171]
	s_mov_b32 m0, s31
	s_nop 0
	global_load_lds_dwordx4 v[206:207], off
	v_lshl_add_u64 v[206:207], s[54:55], 0, v[174:175]
	s_add_i32 m0, s31, 0x2000
	s_nop 0
	global_load_lds_dwordx4 v[206:207], off
	v_lshl_add_u64 v[206:207], s[72:73], 0, v[168:169]
	s_mov_b32 m0, s95
	s_nop 0
	global_load_lds_dwordx4 v[206:207], off
	v_lshl_add_u64 v[206:207], s[72:73], 0, v[172:173]
	s_mov_b32 m0, s42
	s_nop 0
	global_load_lds_dwordx4 v[206:207], off
	s_waitcnt vmcnt(8)
	s_waitcnt lgkmcnt(0)
	s_barrier
	s_setprio 1
	s_waitcnt lgkmcnt(0)
	v_mfma_f32_16x16x32_bf16 v[60:63], v[132:135], v[190:193], v[60:63]
	v_mfma_f32_16x16x32_bf16 v[60:63], v[136:139], v[194:197], v[60:63]
	v_mfma_f32_16x16x32_bf16 v[56:59], v[144:147], v[194:197], v[56:59]
	v_mfma_f32_16x16x32_bf16 v[56:59], v[140:143], v[190:193], v[56:59]
	v_mfma_f32_16x16x32_bf16 v[40:43], v[140:143], v[198:201], v[40:43]
	v_mfma_f32_16x16x32_bf16 v[40:43], v[144:147], v[202:205], v[40:43]
	v_mfma_f32_16x16x32_bf16 v[44:47], v[136:139], v[202:205], v[44:47]
	v_mfma_f32_16x16x32_bf16 v[44:47], v[132:135], v[198:201], v[44:47]
	v_mfma_f32_16x16x32_bf16 v[28:31], v[132:135], v[208:211], v[28:31]
	v_mfma_f32_16x16x32_bf16 v[28:31], v[136:139], v[214:217], v[28:31]
	v_mfma_f32_16x16x32_bf16 v[24:27], v[144:147], v[214:217], v[24:27]
	v_mfma_f32_16x16x32_bf16 v[24:27], v[140:143], v[208:211], v[24:27]
	v_mfma_f32_16x16x32_bf16 v[8:11], v[140:143], v[234:237], v[8:11]
	v_mfma_f32_16x16x32_bf16 v[8:11], v[144:147], v[238:241], v[8:11]
	v_mfma_f32_16x16x32_bf16 v[12:15], v[136:139], v[238:241], v[12:15]
	v_mfma_f32_16x16x32_bf16 v[12:15], v[132:135], v[234:237], v[12:15]
	s_setprio 0
	s_setprio 1
	v_mfma_f32_16x16x32_bf16 v[52:55], v[148:151], v[190:193], v[52:55]
	v_mfma_f32_16x16x32_bf16 v[52:55], v[152:155], v[194:197], v[52:55]
	v_mfma_f32_16x16x32_bf16 v[48:51], v[186:189], v[194:197], v[48:51]
	v_mfma_f32_16x16x32_bf16 v[48:51], v[182:185], v[190:193], v[48:51]
	v_mfma_f32_16x16x32_bf16 v[32:35], v[182:185], v[198:201], v[32:35]
	v_mfma_f32_16x16x32_bf16 v[32:35], v[186:189], v[202:205], v[32:35]
	v_mfma_f32_16x16x32_bf16 v[36:39], v[152:155], v[202:205], v[36:39]
	v_mfma_f32_16x16x32_bf16 v[36:39], v[148:151], v[198:201], v[36:39]
	v_mfma_f32_16x16x32_bf16 v[20:23], v[148:151], v[208:211], v[20:23]
	v_mfma_f32_16x16x32_bf16 v[20:23], v[152:155], v[214:217], v[20:23]
	v_mfma_f32_16x16x32_bf16 v[16:19], v[186:189], v[214:217], v[16:19]
	v_mfma_f32_16x16x32_bf16 v[16:19], v[182:185], v[208:211], v[16:19]
	v_mfma_f32_16x16x32_bf16 v[0:3], v[182:185], v[234:237], v[0:3]
	v_mfma_f32_16x16x32_bf16 v[0:3], v[186:189], v[238:241], v[0:3]
	v_mfma_f32_16x16x32_bf16 v[4:7], v[152:155], v[238:241], v[4:7]
	v_mfma_f32_16x16x32_bf16 v[4:7], v[148:151], v[234:237], v[4:7]
	s_setprio 0
	s_barrier
	s_add_i32 s13, s13, 2
	s_add_u32 s90, s90, 0x100
	s_addc_u32 s91, s91, 0
	s_cmp_gt_u32 s13, 13
	s_cbranch_scc0 .LBB0_271
	s_and_b64 vcc, exec, s[28:29]
	s_cbranch_vccz .LBB0_274
	s_barrier

; #define PG8_STAGE(bufoff, gbase, voff) do { _Pragma("unroll") for (int _i = 0; _i < 2; ++_i) \
;         __builtin_amdgcn_global_load_lds((const unsigned*)((const char*)(gbase) + (voff)[_i]), (LAS unsigned*)(lds + (bufoff) + ldsw + _i * 8192), 16, 0, 0); } while (0)
; #define PG8_LDA(dst, b, h) do { _Pragma("unroll") for (int m = 0; m < 4; ++m) _Pragma("unroll") for (int k = 0; k < 2; ++k) dst[m][k] = *(const LAS bf16x8*)(lds + PG8_SA(b, h) + aoff + m * 2048 + k * 1024); } while (0)
; #define PG8_LDB(dst, b, h) do { _Pragma("unroll") for (int n = 0; n < 2; ++n) _Pragma("unroll") for (int k = 0; k < 2; ++k) dst[n][k] = *(const LAS bf16x8*)(lds + PG8_SB(b, h) + boff + n * 2048 + k * 1024); } while (0)
; #define PG8_WAIT_V(n) asm volatile("s_waitcnt vmcnt(" #n ")" ::: "memory")
; #define PG8_WAIT_L(n) asm volatile("s_waitcnt lgkmcnt(" #n ")" ::: "memory")
; #define PG8_BAR __builtin_amdgcn_s_barrier()
; #define PG8_SCHED __builtin_amdgcn_sched_barrier(0)
;     ...
;         for (int t = 0; t < nt; t += 2) {
;             const bool last = (t == nt - 2);
;             const char* a1 = PG8_ATILE(cA, cA2, t + 1);
;             const char* a2 = last ? nA : PG8_ATILE(cA, cA2, t + 2); const char* b2 = last ? nB : cB + (size_t)(t + 2) * 128;
;             const char* a3 = last ? nA + kA1 : PG8_ATILE(cA, cA2, t + 3); const char* b3 = b2 + kB1;
;             if constexpr (SP2) {
;             PG8_LDB(B0, 0, 0); PG8_LDB(B1, 0, 1); PG8_SCHED; PG8_LDA(At, 0, 0); PG8_STAGE(PG8_SA(1, 1), a1 + hA, voffA);
;             PG8_WAIT_V(8); PG8_WAIT_L(0); PG8_BAR; PG8_MMA(0, 0, At, B0); PG8_MMA(0, 1, At, B1); PG8_BAR; PG8_SCHED;
;             PG8_LDA(At, 0, 1); PG8_STAGE(PG8_SB(0, 0), b2, voffB); PG8_STAGE(PG8_SB(0, 1), b2 + hB, voffB); PG8_STAGE(PG8_SA(0, 0), a2, voffA);
;             PG8_WAIT_V(8); PG8_WAIT_L(0); PG8_BAR; PG8_MMA(1, 0, At, B0); PG8_MMA(1, 1, At, B1); PG8_BAR; PG8_SCHED;
;             PG8_LDB(B0, 1, 0); PG8_LDB(B1, 1, 1); PG8_SCHED; PG8_LDA(At, 1, 0); PG8_STAGE(PG8_SA(0, 1), a2 + hA, voffA);
;             PG8_WAIT_V(8); PG8_WAIT_L(0); PG8_BAR; PG8_MMA(0, 0, At, B0); PG8_MMA(0, 1, At, B1); PG8_BAR; PG8_SCHED;
;             PG8_LDA(At, 1, 1); PG8_STAGE(PG8_SB(1, 0), b3, voffB); PG8_STAGE(PG8_SB(1, 1), b3 + hB, voffB); PG8_STAGE(PG8_SA(1, 0), a3, voffA);
;             PG8_WAIT_V(8); PG8_WAIT_L(0); PG8_BAR; PG8_MMA(1, 0, At, B0); PG8_MMA(1, 1, At, B1); PG8_BAR; PG8_SCHED;
.LBB0_299:
	s_add_u32 s72, s44, s52
	s_addc_u32 s73, s45, s53
	s_add_u32 s98, s72, 0x40080
	s_addc_u32 s99, s73, 0
	s_add_u32 s76, s72, 0x100
	s_addc_u32 s77, s73, 0
	s_add_u32 s74, s79, s52
	s_addc_u32 s75, s80, s53
	s_add_u32 s72, s72, 0x180
	s_addc_u32 s73, s73, 0
	s_add_i32 s82, 0, 0x10000
	s_add_i32 s89, 0, 0x14000
	v_add_u32_e32 v144, s82, v193
	v_add_u32_e32 v184, s89, v193
	ds_read_b128 v[132:135], v144
	ds_read_b128 v[136:139], v144 offset:1024
	ds_read_b128 v[140:143], v144 offset:2048
	ds_read_b128 v[144:147], v144 offset:3072
	ds_read_b128 v[148:151], v184
	ds_read_b128 v[176:179], v184 offset:1024
	ds_read_b128 v[180:183], v184 offset:2048
	ds_read_b128 v[184:187], v184 offset:3072
	s_cmpk_eq_i32 s52, 0x700
	s_cselect_b32 s73, s78, s73
	s_cselect_b32 s72, s55, s72
	s_cselect_b32 s75, s27, s75
	s_cselect_b32 s74, s54, s74
	s_cselect_b32 s77, s3, s77
	s_cselect_b32 s76, s29, s76
	s_add_i32 m0, s6, 0xc000
	ds_read_b128 v[188:191], v198
	ds_read_b128 v[200:203], v198 offset:1024
	ds_read_b128 v[208:211], v198 offset:2048
	ds_read_b128 v[214:217], v198 offset:3072
	ds_read_b128 v[230:233], v198 offset:4096
	ds_read_b128 v[234:237], v198 offset:5120
	ds_read_b128 v[238:241], v198 offset:6144
	ds_read_b128 v[242:245], v198 offset:7168
	global_load_lds_dwordx4 v172, s[98:99]
	s_add_i32 m0, s6, 0xe000
	s_nop 0
	global_load_lds_dwordx4 v174, s[98:99]
	s_waitcnt vmcnt(8)
	s_waitcnt lgkmcnt(0)
	s_barrier
	s_setprio 1
	s_waitcnt lgkmcnt(0)
	v_mfma_f32_16x16x32_bf16 v[124:127], v[132:135], v[188:191], v[124:127]
	v_mfma_f32_16x16x32_bf16 v[124:127], v[136:139], v[200:203], v[124:127]
	v_mfma_f32_16x16x32_bf16 v[120:123], v[144:147], v[200:203], v[120:123]
	v_mfma_f32_16x16x32_bf16 v[120:123], v[140:143], v[188:191], v[120:123]
	v_mfma_f32_16x16x32_bf16 v[104:107], v[140:143], v[208:211], v[104:107]
	v_mfma_f32_16x16x32_bf16 v[104:107], v[144:147], v[214:217], v[104:107]
	v_mfma_f32_16x16x32_bf16 v[108:111], v[136:139], v[214:217], v[108:111]
	v_mfma_f32_16x16x32_bf16 v[108:111], v[132:135], v[208:211], v[108:111]
	v_mfma_f32_16x16x32_bf16 v[92:95], v[132:135], v[230:233], v[92:95]
	v_mfma_f32_16x16x32_bf16 v[92:95], v[136:139], v[234:237], v[92:95]
	v_mfma_f32_16x16x32_bf16 v[88:91], v[144:147], v[234:237], v[88:91]
	v_mfma_f32_16x16x32_bf16 v[88:91], v[140:143], v[230:233], v[88:91]
	v_mfma_f32_16x16x32_bf16 v[72:75], v[140:143], v[238:241], v[72:75]
	v_mfma_f32_16x16x32_bf16 v[72:75], v[144:147], v[242:245], v[72:75]
	v_mfma_f32_16x16x32_bf16 v[76:79], v[136:139], v[242:245], v[76:79]
	v_mfma_f32_16x16x32_bf16 v[76:79], v[132:135], v[238:241], v[76:79]
	s_setprio 0
	s_setprio 1
	v_mfma_f32_16x16x32_bf16 v[116:119], v[148:151], v[188:191], v[116:119]
	v_mfma_f32_16x16x32_bf16 v[116:119], v[176:179], v[200:203], v[116:119]
	v_mfma_f32_16x16x32_bf16 v[112:115], v[184:187], v[200:203], v[112:115]
	v_mfma_f32_16x16x32_bf16 v[112:115], v[180:183], v[188:191], v[112:115]
	v_mfma_f32_16x16x32_bf16 v[96:99], v[180:183], v[208:211], v[96:99]
	v_mfma_f32_16x16x32_bf16 v[96:99], v[184:187], v[214:217], v[96:99]
	v_mfma_f32_16x16x32_bf16 v[100:103], v[176:179], v[214:217], v[100:103]
	v_mfma_f32_16x16x32_bf16 v[100:103], v[148:151], v[208:211], v[100:103]
	v_mfma_f32_16x16x32_bf16 v[84:87], v[148:151], v[230:233], v[84:87]
	v_mfma_f32_16x16x32_bf16 v[84:87], v[176:179], v[234:237], v[84:87]
	v_mfma_f32_16x16x32_bf16 v[80:83], v[184:187], v[234:237], v[80:83]
	v_mfma_f32_16x16x32_bf16 v[80:83], v[180:183], v[230:233], v[80:83]
	v_mfma_f32_16x16x32_bf16 v[64:67], v[180:183], v[238:241], v[64:67]
	v_mfma_f32_16x16x32_bf16 v[64:67], v[184:187], v[242:245], v[64:67]
	v_mfma_f32_16x16x32_bf16 v[68:71], v[176:179], v[242:245], v[68:71]
	v_mfma_f32_16x16x32_bf16 v[68:71], v[148:151], v[238:241], v[68:71]
	s_setprio 0
	s_barrier
	s_add_i32 s82, s82, s5
	s_mov_b32 m0, s82
	ds_read_b128 v[188:191], v198 offset:16384
	ds_read_b128 v[200:203], v198 offset:17408
	ds_read_b128 v[208:211], v198 offset:18432
	ds_read_b128 v[214:217], v198 offset:19456
	ds_read_b128 v[230:233], v198 offset:20480
	ds_read_b128 v[234:237], v198 offset:21504
	ds_read_b128 v[238:241], v198 offset:22528
	ds_read_b128 v[242:245], v198 offset:23552
	global_load_lds_dwordx4 v156, s[74:75]
	s_add_i32 m0, s82, 0x2000
	s_add_u32 s82, s74, 0x40000
	s_addc_u32 s83, s75, 0
	s_add_i32 s89, s89, s5
	global_load_lds_dwordx4 v168, s[74:75]
	s_mov_b32 m0, s89
	s_nop 0
	global_load_lds_dwordx4 v156, s[82:83]
	s_add_i32 m0, s89, 0x2000
	s_nop 0
	global_load_lds_dwordx4 v168, s[82:83]
	s_mov_b32 m0, s6
	s_nop 0
	global_load_lds_dwordx4 v152, s[76:77]
	s_mov_b32 m0, s7
	s_nop 0
	global_load_lds_dwordx4 v154, s[76:77]
	s_waitcnt vmcnt(8)
	s_waitcnt lgkmcnt(0)
	s_barrier
; #define PG8_STAGE(bufoff, gbase, voff) do { _Pragma("unroll") for (int _i = 0; _i < 2; ++_i) \
;         __builtin_amdgcn_global_load_lds((const unsigned*)((const char*)(gbase) + (voff)[_i]), (LAS unsigned*)(lds + (bufoff) + ldsw + _i * 8192), 16, 0, 0); } while (0)
; #define PG8_LDA(dst, b, h) do { _Pragma("unroll") for (int m = 0; m < 4; ++m) _Pragma("unroll") for (int k = 0; k < 2; ++k) dst[m][k] = *(const LAS bf16x8*)(lds + PG8_SA(b, h) + aoff + m * 2048 + k * 1024); } while (0)
; #define PG8_LDB(dst, b, h) do { _Pragma("unroll") for (int n = 0; n < 2; ++n) _Pragma("unroll") for (int k = 0; k < 2; ++k) dst[n][k] = *(const LAS bf16x8*)(lds + PG8_SB(b, h) + boff + n * 2048 + k * 1024); } while (0)
; #define PG8_MMA(ai, bj, At, Bt) do { __builtin_amdgcn_s_setprio(1); _Pragma("unroll") for (int m = 0; m < 4; ++m) _Pragma("unroll") for (int n = 0; n < 2; ++n) _Pragma("unroll") for (int k = 0; k < 2; ++k) \
;         acc[ai][bj][m][n] = __builtin_amdgcn_mfma_f32_16x16x32_bf16(Bt[n][k], At[m][k], acc[ai][bj][m][n], 0, 0, 0); __builtin_amdgcn_s_setprio(0); } while (0)
; #define PG8_WAIT_V(n) asm volatile("s_waitcnt vmcnt(" #n ")" ::: "memory")
; #define PG8_WAIT_L(n) asm volatile("s_waitcnt lgkmcnt(" #n ")" ::: "memory")
; #define PG8_BAR __builtin_amdgcn_s_barrier()
; #define PG8_SCHED __builtin_amdgcn_sched_barrier(0)
;     ...
;             PG8_WAIT_V(8); PG8_WAIT_L(0); PG8_BAR; PG8_MMA(0, 0, At, B0); PG8_MMA(0, 1, At, B1); PG8_BAR; PG8_SCHED;
;             PG8_LDA(At, 0, 1); PG8_STAGE(PG8_SB(0, 0), b2, voffB); PG8_STAGE(PG8_SB(0, 1), b2 + hB, voffB); PG8_STAGE(PG8_SA(0, 0), a2, voffA);
;             PG8_WAIT_V(8); PG8_WAIT_L(0); PG8_BAR; PG8_MMA(1, 0, At, B0); PG8_MMA(1, 1, At, B1); PG8_BAR; PG8_SCHED;
;             PG8_LDB(B0, 1, 0); PG8_LDB(B1, 1, 1); PG8_SCHED; PG8_LDA(At, 1, 0); PG8_STAGE(PG8_SA(0, 1), a2 + hA, voffA);
;             PG8_WAIT_V(8); PG8_WAIT_L(0); PG8_BAR; PG8_MMA(0, 0, At, B0); PG8_MMA(0, 1, At, B1); PG8_BAR; PG8_SCHED;
;             PG8_LDA(At, 1, 1); PG8_STAGE(PG8_SB(1, 0), b3, voffB); PG8_STAGE(PG8_SB(1, 1), b3 + hB, voffB); PG8_STAGE(PG8_SA(1, 0), a3, voffA);
;             PG8_WAIT_V(8); PG8_WAIT_L(0); PG8_BAR; PG8_MMA(1, 0, At, B0); PG8_MMA(1, 1, At, B1); PG8_BAR; PG8_SCHED;
	s_setprio 1
	s_waitcnt lgkmcnt(0)
	v_mfma_f32_16x16x32_bf16 v[60:63], v[132:135], v[188:191], v[60:63]
	v_mfma_f32_16x16x32_bf16 v[60:63], v[136:139], v[200:203], v[60:63]
	v_mfma_f32_16x16x32_bf16 v[56:59], v[144:147], v[200:203], v[56:59]
	v_mfma_f32_16x16x32_bf16 v[56:59], v[140:143], v[188:191], v[56:59]
	v_mfma_f32_16x16x32_bf16 v[40:43], v[140:143], v[208:211], v[40:43]
	v_mfma_f32_16x16x32_bf16 v[40:43], v[144:147], v[214:217], v[40:43]
	v_mfma_f32_16x16x32_bf16 v[44:47], v[136:139], v[214:217], v[44:47]
	v_mfma_f32_16x16x32_bf16 v[44:47], v[132:135], v[208:211], v[44:47]
	v_mfma_f32_16x16x32_bf16 v[28:31], v[132:135], v[230:233], v[28:31]
	v_mfma_f32_16x16x32_bf16 v[28:31], v[136:139], v[234:237], v[28:31]
	v_mfma_f32_16x16x32_bf16 v[24:27], v[144:147], v[234:237], v[24:27]
	v_mfma_f32_16x16x32_bf16 v[24:27], v[140:143], v[230:233], v[24:27]
	v_mfma_f32_16x16x32_bf16 v[8:11], v[140:143], v[238:241], v[8:11]
	v_mfma_f32_16x16x32_bf16 v[8:11], v[144:147], v[242:245], v[8:11]
	v_mfma_f32_16x16x32_bf16 v[12:15], v[136:139], v[242:245], v[12:15]
	v_mfma_f32_16x16x32_bf16 v[12:15], v[132:135], v[238:241], v[12:15]
	s_setprio 0
	s_setprio 1
	v_mfma_f32_16x16x32_bf16 v[52:55], v[148:151], v[188:191], v[52:55]
	v_mfma_f32_16x16x32_bf16 v[52:55], v[176:179], v[200:203], v[52:55]
	v_mfma_f32_16x16x32_bf16 v[48:51], v[184:187], v[200:203], v[48:51]
	v_mfma_f32_16x16x32_bf16 v[48:51], v[180:183], v[188:191], v[48:51]
	v_mfma_f32_16x16x32_bf16 v[32:35], v[180:183], v[208:211], v[32:35]
	v_mfma_f32_16x16x32_bf16 v[32:35], v[184:187], v[214:217], v[32:35]
	v_mfma_f32_16x16x32_bf16 v[36:39], v[176:179], v[214:217], v[36:39]
	v_mfma_f32_16x16x32_bf16 v[36:39], v[148:151], v[208:211], v[36:39]
	v_mfma_f32_16x16x32_bf16 v[20:23], v[148:151], v[230:233], v[20:23]
	v_mfma_f32_16x16x32_bf16 v[20:23], v[176:179], v[234:237], v[20:23]
	v_mfma_f32_16x16x32_bf16 v[16:19], v[184:187], v[234:237], v[16:19]
	v_mfma_f32_16x16x32_bf16 v[16:19], v[180:183], v[230:233], v[16:19]
	v_mfma_f32_16x16x32_bf16 v[0:3], v[180:183], v[238:241], v[0:3]
	v_mfma_f32_16x16x32_bf16 v[0:3], v[184:187], v[242:245], v[0:3]
	v_mfma_f32_16x16x32_bf16 v[4:7], v[176:179], v[242:245], v[4:7]
	v_mfma_f32_16x16x32_bf16 v[4:7], v[148:151], v[238:241], v[4:7]
	s_setprio 0
	s_barrier
	s_add_i32 s82, 0, 0x18000
	s_add_i32 s83, 0, 0x1c000
	v_add_u32_e32 v144, s82, v193
	v_add_u32_e32 v184, s83, v193
	ds_read_b128 v[132:135], v144
	ds_read_b128 v[136:139], v144 offset:1024
	ds_read_b128 v[140:143], v144 offset:2048
	ds_read_b128 v[144:147], v144 offset:3072
	ds_read_b128 v[148:151], v184
	ds_read_b128 v[176:179], v184 offset:1024
	ds_read_b128 v[180:183], v184 offset:2048
	ds_read_b128 v[184:187], v184 offset:3072
	s_add_u32 s76, s76, 0x40000
	s_addc_u32 s77, s77, 0
	s_mov_b32 m0, s8
	ds_read_b128 v[188:191], v198 offset:32768
	ds_read_b128 v[200:203], v198 offset:33792
	ds_read_b128 v[208:211], v198 offset:34816
	ds_read_b128 v[214:217], v198 offset:35840
	ds_read_b128 v[230:233], v198 offset:36864
	ds_read_b128 v[234:237], v198 offset:37888
	ds_read_b128 v[238:241], v198 offset:38912
	ds_read_b128 v[242:245], v198 offset:39936
	global_load_lds_dwordx4 v152, s[76:77]
	s_mov_b32 m0, s9
	s_nop 0
	global_load_lds_dwordx4 v154, s[76:77]
	s_waitcnt vmcnt(8)
	s_waitcnt lgkmcnt(0)
	s_barrier
	s_setprio 1
	s_waitcnt lgkmcnt(0)
	v_mfma_f32_16x16x32_bf16 v[124:127], v[132:135], v[188:191], v[124:127]
	v_mfma_f32_16x16x32_bf16 v[124:127], v[136:139], v[200:203], v[124:127]
	v_mfma_f32_16x16x32_bf16 v[120:123], v[144:147], v[200:203], v[120:123]
	v_mfma_f32_16x16x32_bf16 v[120:123], v[140:143], v[188:191], v[120:123]
	v_mfma_f32_16x16x32_bf16 v[104:107], v[140:143], v[208:211], v[104:107]
	v_mfma_f32_16x16x32_bf16 v[104:107], v[144:147], v[214:217], v[104:107]
	v_mfma_f32_16x16x32_bf16 v[108:111], v[136:139], v[214:217], v[108:111]
	v_mfma_f32_16x16x32_bf16 v[108:111], v[132:135], v[208:211], v[108:111]
	v_mfma_f32_16x16x32_bf16 v[92:95], v[132:135], v[230:233], v[92:95]
	v_mfma_f32_16x16x32_bf16 v[92:95], v[136:139], v[234:237], v[92:95]
	v_mfma_f32_16x16x32_bf16 v[88:91], v[144:147], v[234:237], v[88:91]
	v_mfma_f32_16x16x32_bf16 v[88:91], v[140:143], v[230:233], v[88:91]
	v_mfma_f32_16x16x32_bf16 v[72:75], v[140:143], v[238:241], v[72:75]
	v_mfma_f32_16x16x32_bf16 v[72:75], v[144:147], v[242:245], v[72:75]
	v_mfma_f32_16x16x32_bf16 v[76:79], v[136:139], v[242:245], v[76:79]
	v_mfma_f32_16x16x32_bf16 v[76:79], v[132:135], v[238:241], v[76:79]
	s_setprio 0
	s_setprio 1
	v_mfma_f32_16x16x32_bf16 v[116:119], v[148:151], v[188:191], v[116:119]
	v_mfma_f32_16x16x32_bf16 v[116:119], v[176:179], v[200:203], v[116:119]
	v_mfma_f32_16x16x32_bf16 v[112:115], v[184:187], v[200:203], v[112:115]
	v_mfma_f32_16x16x32_bf16 v[112:115], v[180:183], v[188:191], v[112:115]
	v_mfma_f32_16x16x32_bf16 v[96:99], v[180:183], v[208:211], v[96:99]
	v_mfma_f32_16x16x32_bf16 v[96:99], v[184:187], v[214:217], v[96:99]
	v_mfma_f32_16x16x32_bf16 v[100:103], v[176:179], v[214:217], v[100:103]
	v_mfma_f32_16x16x32_bf16 v[100:103], v[148:151], v[208:211], v[100:103]
	v_mfma_f32_16x16x32_bf16 v[84:87], v[148:151], v[230:233], v[84:87]
	v_mfma_f32_16x16x32_bf16 v[84:87], v[176:179], v[234:237], v[84:87]
	v_mfma_f32_16x16x32_bf16 v[80:83], v[184:187], v[234:237], v[80:83]
	v_mfma_f32_16x16x32_bf16 v[80:83], v[180:183], v[230:233], v[80:83]
	v_mfma_f32_16x16x32_bf16 v[64:67], v[180:183], v[238:241], v[64:67]
	v_mfma_f32_16x16x32_bf16 v[64:67], v[184:187], v[242:245], v[64:67]
	v_mfma_f32_16x16x32_bf16 v[68:71], v[176:179], v[242:245], v[68:71]
	v_mfma_f32_16x16x32_bf16 v[68:71], v[148:151], v[238:241], v[68:71]
	s_setprio 0
	s_barrier
; #define PG8_STAGE(bufoff, gbase, voff) do { _Pragma("unroll") for (int _i = 0; _i < 2; ++_i) \
;         __builtin_amdgcn_global_load_lds((const unsigned*)((const char*)(gbase) + (voff)[_i]), (LAS unsigned*)(lds + (bufoff) + ldsw + _i * 8192), 16, 0, 0); } while (0)
; #define PG8_LDA(dst, b, h) do { _Pragma("unroll") for (int m = 0; m < 4; ++m) _Pragma("unroll") for (int k = 0; k < 2; ++k) dst[m][k] = *(const LAS bf16x8*)(lds + PG8_SA(b, h) + aoff + m * 2048 + k * 1024); } while (0)
; #define PG8_LDB(dst, b, h) do { _Pragma("unroll") for (int n = 0; n < 2; ++n) _Pragma("unroll") for (int k = 0; k < 2; ++k) dst[n][k] = *(const LAS bf16x8*)(lds + PG8_SB(b, h) + boff + n * 2048 + k * 1024); } while (0)
; #define PG8_WAIT_V(n) asm volatile("s_waitcnt vmcnt(" #n ")" ::: "memory")
;     ...
;             PG8_LDA(At, 1, 1); PG8_STAGE(PG8_SB(1, 0), b3, voffB); PG8_STAGE(PG8_SB(1, 1), b3 + hB, voffB); PG8_STAGE(PG8_SA(1, 0), a3, voffA);
;             PG8_WAIT_V(8); PG8_WAIT_L(0); PG8_BAR; PG8_MMA(1, 0, At, B0); PG8_MMA(1, 1, At, B1); PG8_BAR; PG8_SCHED;
;             } else {
;             PG8_LDB(B0, 0, 0); PG8_SCHED; PG8_LDA(At, 0, 0); PG8_STAGE(PG8_SA(1, 1), a1 + hA, voffA);
;             PG8_WAIT_L(8); PG8_BAR; PG8_WAIT_L(0); PG8_MMA(0, 0, At, B0); PG8_BAR; PG8_SCHED;
;             PG8_LDB(B1, 0, 1); PG8_STAGE(PG8_SB(0, 0), b2, voffB);
;             PG8_BAR; PG8_WAIT_L(0); PG8_MMA(0, 1, At, B1); PG8_BAR;
;             PG8_LDA(At, 0, 1); PG8_STAGE(PG8_SA(0, 0), a2, voffA);
;             PG8_BAR; PG8_WAIT_L(0); PG8_MMA(1, 0, At, B0); PG8_BAR; PG8_SCHED;
;             PG8_STAGE(PG8_SB(0, 1), b2 + hB, voffB);
;             PG8_WAIT_V(6); PG8_BAR; PG8_MMA(1, 1, At, B1); PG8_BAR;
;             PG8_LDB(B0, 1, 0); PG8_SCHED; PG8_LDA(At, 1, 0); PG8_STAGE(PG8_SA(0, 1), a2 + hA, voffA);
;             PG8_WAIT_L(8); PG8_BAR; PG8_WAIT_L(0); PG8_MMA(0, 0, At, B0); PG8_BAR; PG8_SCHED;
;             PG8_LDB(B1, 1, 1); PG8_STAGE(PG8_SB(1, 0), b3, voffB);
;             PG8_BAR; PG8_WAIT_L(0); PG8_MMA(0, 1, At, B1); PG8_BAR;
;             PG8_LDA(At, 1, 1); PG8_STAGE(PG8_SA(1, 0), a3, voffA);
;             PG8_BAR; PG8_WAIT_L(0); PG8_MMA(1, 0, At, B0); PG8_BAR; PG8_SCHED;
;             PG8_STAGE(PG8_SB(1, 1), b3 + hB, voffB);
;             PG8_WAIT_V(6); PG8_BAR; PG8_MMA(1, 1, At, B1); PG8_BAR;
;             }
;         }
;         if constexpr (ALIGN_EPI) { if (wr == 0) PG8_BAR; }
	s_add_i32 s76, s82, s5
	s_add_u32 s100, s74, s38
	s_addc_u32 s101, s75, s39
	s_mov_b32 m0, s76
	ds_read_b128 v[188:191], v198 offset:49152
	ds_read_b128 v[200:203], v198 offset:50176
	ds_read_b128 v[208:211], v198 offset:51200
	ds_read_b128 v[214:217], v198 offset:52224
	ds_read_b128 v[230:233], v198 offset:53248
	ds_read_b128 v[234:237], v198 offset:54272
	ds_read_b128 v[238:241], v198 offset:55296
	ds_read_b128 v[242:245], v198 offset:56320
	global_load_lds_dwordx4 v156, s[100:101]
	s_add_i32 m0, s76, 0x2000
	s_add_u32 s74, s74, 0x40080
	s_addc_u32 s75, s75, 0
	s_add_i32 s76, s83, s5
	global_load_lds_dwordx4 v168, s[100:101]
	s_mov_b32 m0, s76
	s_nop 0
	global_load_lds_dwordx4 v156, s[74:75]
	s_add_i32 m0, s76, 0x2000
	s_nop 0
	global_load_lds_dwordx4 v168, s[74:75]
	s_mov_b32 m0, s36
	s_nop 0
	global_load_lds_dwordx4 v152, s[72:73]
	s_mov_b32 m0, s42
	s_nop 0
	global_load_lds_dwordx4 v154, s[72:73]
	s_waitcnt vmcnt(8)
	s_waitcnt lgkmcnt(0)
	s_barrier
	s_setprio 1
	s_waitcnt lgkmcnt(0)
	v_mfma_f32_16x16x32_bf16 v[60:63], v[132:135], v[188:191], v[60:63]
	v_mfma_f32_16x16x32_bf16 v[60:63], v[136:139], v[200:203], v[60:63]
	v_mfma_f32_16x16x32_bf16 v[56:59], v[144:147], v[200:203], v[56:59]
	v_mfma_f32_16x16x32_bf16 v[56:59], v[140:143], v[188:191], v[56:59]
	v_mfma_f32_16x16x32_bf16 v[40:43], v[140:143], v[208:211], v[40:43]
	v_mfma_f32_16x16x32_bf16 v[40:43], v[144:147], v[214:217], v[40:43]
	v_mfma_f32_16x16x32_bf16 v[44:47], v[136:139], v[214:217], v[44:47]
	v_mfma_f32_16x16x32_bf16 v[44:47], v[132:135], v[208:211], v[44:47]
	v_mfma_f32_16x16x32_bf16 v[28:31], v[132:135], v[230:233], v[28:31]
	v_mfma_f32_16x16x32_bf16 v[28:31], v[136:139], v[234:237], v[28:31]
	v_mfma_f32_16x16x32_bf16 v[24:27], v[144:147], v[234:237], v[24:27]
	v_mfma_f32_16x16x32_bf16 v[24:27], v[140:143], v[230:233], v[24:27]
	v_mfma_f32_16x16x32_bf16 v[8:11], v[140:143], v[238:241], v[8:11]
	v_mfma_f32_16x16x32_bf16 v[8:11], v[144:147], v[242:245], v[8:11]
	v_mfma_f32_16x16x32_bf16 v[12:15], v[136:139], v[242:245], v[12:15]
	v_mfma_f32_16x16x32_bf16 v[12:15], v[132:135], v[238:241], v[12:15]
	s_setprio 0
	s_setprio 1
	v_mfma_f32_16x16x32_bf16 v[52:55], v[148:151], v[188:191], v[52:55]
	v_mfma_f32_16x16x32_bf16 v[52:55], v[176:179], v[200:203], v[52:55]
	v_mfma_f32_16x16x32_bf16 v[48:51], v[184:187], v[200:203], v[48:51]
	v_mfma_f32_16x16x32_bf16 v[48:51], v[180:183], v[188:191], v[48:51]
	v_mfma_f32_16x16x32_bf16 v[32:35], v[180:183], v[208:211], v[32:35]
	v_mfma_f32_16x16x32_bf16 v[32:35], v[184:187], v[214:217], v[32:35]
	v_mfma_f32_16x16x32_bf16 v[36:39], v[176:179], v[214:217], v[36:39]
	v_mfma_f32_16x16x32_bf16 v[36:39], v[148:151], v[208:211], v[36:39]
	v_mfma_f32_16x16x32_bf16 v[20:23], v[148:151], v[230:233], v[20:23]
	v_mfma_f32_16x16x32_bf16 v[20:23], v[176:179], v[234:237], v[20:23]
	v_mfma_f32_16x16x32_bf16 v[16:19], v[184:187], v[234:237], v[16:19]
	v_mfma_f32_16x16x32_bf16 v[16:19], v[180:183], v[230:233], v[16:19]
	v_mfma_f32_16x16x32_bf16 v[0:3], v[180:183], v[238:241], v[0:3]
	v_mfma_f32_16x16x32_bf16 v[0:3], v[184:187], v[242:245], v[0:3]
	v_mfma_f32_16x16x32_bf16 v[4:7], v[176:179], v[242:245], v[4:7]
	v_mfma_f32_16x16x32_bf16 v[4:7], v[148:151], v[238:241], v[4:7]
	s_setprio 0
	s_barrier
	s_add_i32 s81, s81, 2
	s_add_u32 s52, s52, 0x100
	s_addc_u32 s53, s53, 0
	s_cmp_gt_u32 s81, 13
	s_cbranch_scc0 .LBB0_299
	s_and_b64 vcc, exec, s[16:17]
	s_cbranch_vccz .LBB0_302
	s_barrier

; #define PG8_STAGE(bufoff, gbase, voff) do { _Pragma("unroll") for (int _i = 0; _i < 2; ++_i) \
;         __builtin_amdgcn_global_load_lds((const unsigned*)((const char*)(gbase) + (voff)[_i]), (LAS unsigned*)(lds + (bufoff) + ldsw + _i * 8192), 16, 0, 0); } while (0)
; #define PG8_LDA(dst, b, h) do { _Pragma("unroll") for (int m = 0; m < 4; ++m) _Pragma("unroll") for (int k = 0; k < 2; ++k) dst[m][k] = *(const LAS bf16x8*)(lds + PG8_SA(b, h) + aoff + m * 2048 + k * 1024); } while (0)
; #define PG8_LDB(dst, b, h) do { _Pragma("unroll") for (int n = 0; n < 2; ++n) _Pragma("unroll") for (int k = 0; k < 2; ++k) dst[n][k] = *(const LAS bf16x8*)(lds + PG8_SB(b, h) + boff + n * 2048 + k * 1024); } while (0)
; #define PG8_WAIT_V(n) asm volatile("s_waitcnt vmcnt(" #n ")" ::: "memory")
; #define PG8_WAIT_L(n) asm volatile("s_waitcnt lgkmcnt(" #n ")" ::: "memory")
; #define PG8_BAR __builtin_amdgcn_s_barrier()
; #define PG8_SCHED __builtin_amdgcn_sched_barrier(0)
;     ...
;         for (int t = 0; t < nt; t += 2) {
;             const bool last = (t == nt - 2);
;             const char* a1 = PG8_ATILE(cA, cA2, t + 1);
;             const char* a2 = last ? nA : PG8_ATILE(cA, cA2, t + 2); const char* b2 = last ? nB : cB + (size_t)(t + 2) * 128;
;             const char* a3 = last ? nA + kA1 : PG8_ATILE(cA, cA2, t + 3); const char* b3 = b2 + kB1;
;             if constexpr (SP2) {
;             PG8_LDB(B0, 0, 0); PG8_LDB(B1, 0, 1); PG8_SCHED; PG8_LDA(At, 0, 0); PG8_STAGE(PG8_SA(1, 1), a1 + hA, voffA);
;             PG8_WAIT_V(8); PG8_WAIT_L(0); PG8_BAR; PG8_MMA(0, 0, At, B0); PG8_MMA(0, 1, At, B1); PG8_BAR; PG8_SCHED;
;             PG8_LDA(At, 0, 1); PG8_STAGE(PG8_SB(0, 0), b2, voffB); PG8_STAGE(PG8_SB(0, 1), b2 + hB, voffB); PG8_STAGE(PG8_SA(0, 0), a2, voffA);
;             PG8_WAIT_V(8); PG8_WAIT_L(0); PG8_BAR; PG8_MMA(1, 0, At, B0); PG8_MMA(1, 1, At, B1); PG8_BAR; PG8_SCHED;
;             PG8_LDB(B0, 1, 0); PG8_LDB(B1, 1, 1); PG8_SCHED; PG8_LDA(At, 1, 0); PG8_STAGE(PG8_SA(0, 1), a2 + hA, voffA);
;             PG8_WAIT_V(8); PG8_WAIT_L(0); PG8_BAR; PG8_MMA(0, 0, At, B0); PG8_MMA(0, 1, At, B1); PG8_BAR; PG8_SCHED;
;             PG8_LDA(At, 1, 1); PG8_STAGE(PG8_SB(1, 0), b3, voffB); PG8_STAGE(PG8_SB(1, 1), b3 + hB, voffB); PG8_STAGE(PG8_SA(1, 0), a3, voffA);
;             PG8_WAIT_V(8); PG8_WAIT_L(0); PG8_BAR; PG8_MMA(1, 0, At, B0); PG8_MMA(1, 1, At, B1); PG8_BAR; PG8_SCHED;
.LBB0_364:
	s_add_i32 s6, s74, 2
	s_add_u32 s26, s92, vcc_lo
	s_addc_u32 s27, s93, vcc_hi
	s_add_u32 s98, s26, 0x80
	s_addc_u32 s99, s27, 0
	s_add_u32 s76, s26, 0x100
	s_addc_u32 s77, s27, 0
	s_add_u32 s9, s94, vcc_lo
	s_addc_u32 s8, s95, vcc_hi
	s_add_u32 s26, s26, 0x180
	s_addc_u32 s27, s27, 0
	s_add_i32 s50, 0, 0x10000
	s_add_i32 s51, 0, 0x14000
	v_add_u32_e32 v154, s50, v168
	ds_read_b128 v[132:135], v154
	ds_read_b128 v[146:149], v154 offset:1024
	ds_read_b128 v[150:153], v154 offset:2048
	ds_read_b128 v[172:175], v154 offset:3072
	v_add_u32_e32 v154, s51, v168
	ds_read_b128 v[176:179], v154
	ds_read_b128 v[180:183], v154 offset:1024
	ds_read_b128 v[184:187], v154 offset:2048
	ds_read_b128 v[188:191], v154 offset:3072
	s_cmp_eq_u32 s5, s74
	s_cselect_b32 s74, s97, s26
	s_cselect_b32 s75, s79, s27
	s_cselect_b32 s27, s45, s8
	s_cselect_b32 s26, s96, s9
	s_cselect_b32 s77, s43, s77
	s_cselect_b32 s76, s82, s76
	s_add_i32 m0, s83, 0xc000
	ds_read_b128 v[192:195], v170
	ds_read_b128 v[196:199], v170 offset:1024
	ds_read_b128 v[200:203], v170 offset:2048
	ds_read_b128 v[208:211], v170 offset:3072
	ds_read_b128 v[214:217], v170 offset:4096
	ds_read_b128 v[230:233], v170 offset:5120
	ds_read_b128 v[234:237], v170 offset:6144
	ds_read_b128 v[238:241], v170 offset:7168
	global_load_lds_dwordx4 v144, s[98:99]
	s_add_i32 m0, s83, 0xe000
	s_nop 0
	global_load_lds_dwordx4 v142, s[98:99]
	s_waitcnt vmcnt(8)
	s_waitcnt lgkmcnt(0)
	s_barrier
	s_setprio 1
	s_waitcnt lgkmcnt(0)
	v_mfma_f32_16x16x32_bf16 v[124:127], v[132:135], v[192:195], v[124:127]
	v_mfma_f32_16x16x32_bf16 v[124:127], v[146:149], v[196:199], v[124:127]
	v_mfma_f32_16x16x32_bf16 v[120:123], v[172:175], v[196:199], v[120:123]
	v_mfma_f32_16x16x32_bf16 v[120:123], v[150:153], v[192:195], v[120:123]
	v_mfma_f32_16x16x32_bf16 v[104:107], v[150:153], v[200:203], v[104:107]
	v_mfma_f32_16x16x32_bf16 v[104:107], v[172:175], v[208:211], v[104:107]
	v_mfma_f32_16x16x32_bf16 v[108:111], v[146:149], v[208:211], v[108:111]
	v_mfma_f32_16x16x32_bf16 v[108:111], v[132:135], v[200:203], v[108:111]
	v_mfma_f32_16x16x32_bf16 v[92:95], v[132:135], v[214:217], v[92:95]
	v_mfma_f32_16x16x32_bf16 v[92:95], v[146:149], v[230:233], v[92:95]
	v_mfma_f32_16x16x32_bf16 v[88:91], v[172:175], v[230:233], v[88:91]
	v_mfma_f32_16x16x32_bf16 v[88:91], v[150:153], v[214:217], v[88:91]
	v_mfma_f32_16x16x32_bf16 v[72:75], v[150:153], v[234:237], v[72:75]
	v_mfma_f32_16x16x32_bf16 v[72:75], v[172:175], v[238:241], v[72:75]
	v_mfma_f32_16x16x32_bf16 v[76:79], v[146:149], v[238:241], v[76:79]
	v_mfma_f32_16x16x32_bf16 v[76:79], v[132:135], v[234:237], v[76:79]
	s_setprio 0
	s_setprio 1
	v_mfma_f32_16x16x32_bf16 v[116:119], v[176:179], v[192:195], v[116:119]
	v_mfma_f32_16x16x32_bf16 v[116:119], v[180:183], v[196:199], v[116:119]
	v_mfma_f32_16x16x32_bf16 v[112:115], v[188:191], v[196:199], v[112:115]
	v_mfma_f32_16x16x32_bf16 v[112:115], v[184:187], v[192:195], v[112:115]
	v_mfma_f32_16x16x32_bf16 v[96:99], v[184:187], v[200:203], v[96:99]
	v_mfma_f32_16x16x32_bf16 v[96:99], v[188:191], v[208:211], v[96:99]
	v_mfma_f32_16x16x32_bf16 v[100:103], v[180:183], v[208:211], v[100:103]
	v_mfma_f32_16x16x32_bf16 v[100:103], v[176:179], v[200:203], v[100:103]
	v_mfma_f32_16x16x32_bf16 v[84:87], v[176:179], v[214:217], v[84:87]
	v_mfma_f32_16x16x32_bf16 v[84:87], v[180:183], v[230:233], v[84:87]
	v_mfma_f32_16x16x32_bf16 v[80:83], v[188:191], v[230:233], v[80:83]
	v_mfma_f32_16x16x32_bf16 v[80:83], v[184:187], v[214:217], v[80:83]
	v_mfma_f32_16x16x32_bf16 v[64:67], v[184:187], v[234:237], v[64:67]
	v_mfma_f32_16x16x32_bf16 v[64:67], v[188:191], v[238:241], v[64:67]
	v_mfma_f32_16x16x32_bf16 v[68:71], v[180:183], v[238:241], v[68:71]
	v_mfma_f32_16x16x32_bf16 v[68:71], v[176:179], v[234:237], v[68:71]
	s_setprio 0
	s_barrier
	s_add_i32 s8, s50, s81
	s_mov_b32 m0, s8
	ds_read_b128 v[192:195], v170 offset:16384
	ds_read_b128 v[196:199], v170 offset:17408
	ds_read_b128 v[200:203], v170 offset:18432
	ds_read_b128 v[208:211], v170 offset:19456
	ds_read_b128 v[214:217], v170 offset:20480
	ds_read_b128 v[230:233], v170 offset:21504
	ds_read_b128 v[234:237], v170 offset:22528
	ds_read_b128 v[238:241], v170 offset:23552
	global_load_lds_dwordx4 v156, s[26:27]
	s_add_i32 m0, s8, 0x2000
	s_mov_b64 s[100:101], s[26:27]
	s_add_u32 s26, s26, s16
	s_addc_u32 s27, s27, 0
	s_add_i32 s8, s51, s81
	global_load_lds_dwordx4 v140, s[100:101]
	s_mov_b32 m0, s8
	s_nop 0
	global_load_lds_dwordx4 v156, s[26:27]
	s_add_i32 m0, s8, 0x2000
	s_nop 0
	global_load_lds_dwordx4 v140, s[26:27]
	s_mov_b32 m0, s83
	s_nop 0
	global_load_lds_dwordx4 v136, s[76:77]
	s_mov_b32 m0, s2
	s_nop 0
	global_load_lds_dwordx4 v138, s[76:77]
	s_waitcnt vmcnt(8)
	s_waitcnt lgkmcnt(0)
	s_barrier
; #define PG8_STAGE(bufoff, gbase, voff) do { _Pragma("unroll") for (int _i = 0; _i < 2; ++_i) \
;         __builtin_amdgcn_global_load_lds((const unsigned*)((const char*)(gbase) + (voff)[_i]), (LAS unsigned*)(lds + (bufoff) + ldsw + _i * 8192), 16, 0, 0); } while (0)
; #define PG8_LDA(dst, b, h) do { _Pragma("unroll") for (int m = 0; m < 4; ++m) _Pragma("unroll") for (int k = 0; k < 2; ++k) dst[m][k] = *(const LAS bf16x8*)(lds + PG8_SA(b, h) + aoff + m * 2048 + k * 1024); } while (0)
; #define PG8_LDB(dst, b, h) do { _Pragma("unroll") for (int n = 0; n < 2; ++n) _Pragma("unroll") for (int k = 0; k < 2; ++k) dst[n][k] = *(const LAS bf16x8*)(lds + PG8_SB(b, h) + boff + n * 2048 + k * 1024); } while (0)
; #define PG8_MMA(ai, bj, At, Bt) do { __builtin_amdgcn_s_setprio(1); _Pragma("unroll") for (int m = 0; m < 4; ++m) _Pragma("unroll") for (int n = 0; n < 2; ++n) _Pragma("unroll") for (int k = 0; k < 2; ++k) \
;         acc[ai][bj][m][n] = __builtin_amdgcn_mfma_f32_16x16x32_bf16(Bt[n][k], At[m][k], acc[ai][bj][m][n], 0, 0, 0); __builtin_amdgcn_s_setprio(0); } while (0)
; #define PG8_WAIT_V(n) asm volatile("s_waitcnt vmcnt(" #n ")" ::: "memory")
; #define PG8_WAIT_L(n) asm volatile("s_waitcnt lgkmcnt(" #n ")" ::: "memory")
; #define PG8_BAR __builtin_amdgcn_s_barrier()
; #define PG8_SCHED __builtin_amdgcn_sched_barrier(0)
;     ...
;             PG8_WAIT_V(8); PG8_WAIT_L(0); PG8_BAR; PG8_MMA(0, 0, At, B0); PG8_MMA(0, 1, At, B1); PG8_BAR; PG8_SCHED;
;             PG8_LDA(At, 0, 1); PG8_STAGE(PG8_SB(0, 0), b2, voffB); PG8_STAGE(PG8_SB(0, 1), b2 + hB, voffB); PG8_STAGE(PG8_SA(0, 0), a2, voffA);
;             PG8_WAIT_V(8); PG8_WAIT_L(0); PG8_BAR; PG8_MMA(1, 0, At, B0); PG8_MMA(1, 1, At, B1); PG8_BAR; PG8_SCHED;
;             PG8_LDB(B0, 1, 0); PG8_LDB(B1, 1, 1); PG8_SCHED; PG8_LDA(At, 1, 0); PG8_STAGE(PG8_SA(0, 1), a2 + hA, voffA);
;             PG8_WAIT_V(8); PG8_WAIT_L(0); PG8_BAR; PG8_MMA(0, 0, At, B0); PG8_MMA(0, 1, At, B1); PG8_BAR; PG8_SCHED;
;             PG8_LDA(At, 1, 1); PG8_STAGE(PG8_SB(1, 0), b3, voffB); PG8_STAGE(PG8_SB(1, 1), b3 + hB, voffB); PG8_STAGE(PG8_SA(1, 0), a3, voffA);
;             PG8_WAIT_V(8); PG8_WAIT_L(0); PG8_BAR; PG8_MMA(1, 0, At, B0); PG8_MMA(1, 1, At, B1); PG8_BAR; PG8_SCHED;
	s_setprio 1
	s_waitcnt lgkmcnt(0)
	v_mfma_f32_16x16x32_bf16 v[60:63], v[132:135], v[192:195], v[60:63]
	v_mfma_f32_16x16x32_bf16 v[60:63], v[146:149], v[196:199], v[60:63]
	v_mfma_f32_16x16x32_bf16 v[56:59], v[172:175], v[196:199], v[56:59]
	v_mfma_f32_16x16x32_bf16 v[56:59], v[150:153], v[192:195], v[56:59]
	v_mfma_f32_16x16x32_bf16 v[40:43], v[150:153], v[200:203], v[40:43]
	v_mfma_f32_16x16x32_bf16 v[40:43], v[172:175], v[208:211], v[40:43]
	v_mfma_f32_16x16x32_bf16 v[44:47], v[146:149], v[208:211], v[44:47]
	v_mfma_f32_16x16x32_bf16 v[44:47], v[132:135], v[200:203], v[44:47]
	v_mfma_f32_16x16x32_bf16 v[28:31], v[132:135], v[214:217], v[28:31]
	v_mfma_f32_16x16x32_bf16 v[28:31], v[146:149], v[230:233], v[28:31]
	v_mfma_f32_16x16x32_bf16 v[24:27], v[172:175], v[230:233], v[24:27]
	v_mfma_f32_16x16x32_bf16 v[24:27], v[150:153], v[214:217], v[24:27]
	v_mfma_f32_16x16x32_bf16 v[8:11], v[150:153], v[234:237], v[8:11]
	v_mfma_f32_16x16x32_bf16 v[8:11], v[172:175], v[238:241], v[8:11]
	v_mfma_f32_16x16x32_bf16 v[12:15], v[146:149], v[238:241], v[12:15]
	v_mfma_f32_16x16x32_bf16 v[12:15], v[132:135], v[234:237], v[12:15]
	s_setprio 0
	s_setprio 1
	v_mfma_f32_16x16x32_bf16 v[52:55], v[176:179], v[192:195], v[52:55]
	v_mfma_f32_16x16x32_bf16 v[52:55], v[180:183], v[196:199], v[52:55]
	v_mfma_f32_16x16x32_bf16 v[48:51], v[188:191], v[196:199], v[48:51]
	v_mfma_f32_16x16x32_bf16 v[48:51], v[184:187], v[192:195], v[48:51]
	v_mfma_f32_16x16x32_bf16 v[32:35], v[184:187], v[200:203], v[32:35]
	v_mfma_f32_16x16x32_bf16 v[32:35], v[188:191], v[208:211], v[32:35]
	v_mfma_f32_16x16x32_bf16 v[36:39], v[180:183], v[208:211], v[36:39]
	v_mfma_f32_16x16x32_bf16 v[36:39], v[176:179], v[200:203], v[36:39]
	v_mfma_f32_16x16x32_bf16 v[20:23], v[176:179], v[214:217], v[20:23]
	v_mfma_f32_16x16x32_bf16 v[20:23], v[180:183], v[230:233], v[20:23]
	v_mfma_f32_16x16x32_bf16 v[16:19], v[188:191], v[230:233], v[16:19]
	v_mfma_f32_16x16x32_bf16 v[16:19], v[184:187], v[214:217], v[16:19]
	v_mfma_f32_16x16x32_bf16 v[0:3], v[184:187], v[234:237], v[0:3]
	v_mfma_f32_16x16x32_bf16 v[0:3], v[188:191], v[238:241], v[0:3]
	v_mfma_f32_16x16x32_bf16 v[4:7], v[180:183], v[238:241], v[4:7]
	v_mfma_f32_16x16x32_bf16 v[4:7], v[176:179], v[234:237], v[4:7]
	s_setprio 0
	s_barrier
	s_add_i32 s8, 0, 0x18000
	v_add_u32_e32 v171, s8, v168
	s_add_i32 s9, 0, 0x1c000
	ds_read_b128 v[132:135], v171
	ds_read_b128 v[146:149], v171 offset:1024
	ds_read_b128 v[150:153], v171 offset:2048
	ds_read_b128 v[172:175], v171 offset:3072
	v_add_u32_e32 v171, s9, v168
	ds_read_b128 v[176:179], v171
	ds_read_b128 v[180:183], v171 offset:1024
	ds_read_b128 v[184:187], v171 offset:2048
	ds_read_b128 v[188:191], v171 offset:3072
	s_add_u32 s26, s76, s16
	s_addc_u32 s27, s77, 0
	s_mov_b32 m0, s3
	ds_read_b128 v[192:195], v170 offset:32768
	ds_read_b128 v[196:199], v170 offset:33792
	ds_read_b128 v[200:203], v170 offset:34816
	ds_read_b128 v[208:211], v170 offset:35840
	ds_read_b128 v[214:217], v170 offset:36864
	ds_read_b128 v[230:233], v170 offset:37888
	ds_read_b128 v[234:237], v170 offset:38912
	ds_read_b128 v[238:241], v170 offset:39936
	global_load_lds_dwordx4 v136, s[26:27]
	s_mov_b32 m0, s0
	s_nop 0
	global_load_lds_dwordx4 v138, s[26:27]
	s_waitcnt vmcnt(8)
	s_waitcnt lgkmcnt(0)
	s_barrier
	s_setprio 1
	s_waitcnt lgkmcnt(0)
	v_mfma_f32_16x16x32_bf16 v[124:127], v[132:135], v[192:195], v[124:127]
	v_mfma_f32_16x16x32_bf16 v[124:127], v[146:149], v[196:199], v[124:127]
	v_mfma_f32_16x16x32_bf16 v[120:123], v[172:175], v[196:199], v[120:123]
	v_mfma_f32_16x16x32_bf16 v[120:123], v[150:153], v[192:195], v[120:123]
	v_mfma_f32_16x16x32_bf16 v[104:107], v[150:153], v[200:203], v[104:107]
	v_mfma_f32_16x16x32_bf16 v[104:107], v[172:175], v[208:211], v[104:107]
	v_mfma_f32_16x16x32_bf16 v[108:111], v[146:149], v[208:211], v[108:111]
	v_mfma_f32_16x16x32_bf16 v[108:111], v[132:135], v[200:203], v[108:111]
	v_mfma_f32_16x16x32_bf16 v[92:95], v[132:135], v[214:217], v[92:95]
	v_mfma_f32_16x16x32_bf16 v[92:95], v[146:149], v[230:233], v[92:95]
	v_mfma_f32_16x16x32_bf16 v[88:91], v[172:175], v[230:233], v[88:91]
	v_mfma_f32_16x16x32_bf16 v[88:91], v[150:153], v[214:217], v[88:91]
	v_mfma_f32_16x16x32_bf16 v[72:75], v[150:153], v[234:237], v[72:75]
	v_mfma_f32_16x16x32_bf16 v[72:75], v[172:175], v[238:241], v[72:75]
	v_mfma_f32_16x16x32_bf16 v[76:79], v[146:149], v[238:241], v[76:79]
	v_mfma_f32_16x16x32_bf16 v[76:79], v[132:135], v[234:237], v[76:79]
	s_setprio 0
	s_setprio 1
	v_mfma_f32_16x16x32_bf16 v[116:119], v[176:179], v[192:195], v[116:119]
	v_mfma_f32_16x16x32_bf16 v[116:119], v[180:183], v[196:199], v[116:119]
	v_mfma_f32_16x16x32_bf16 v[112:115], v[188:191], v[196:199], v[112:115]
	v_mfma_f32_16x16x32_bf16 v[112:115], v[184:187], v[192:195], v[112:115]
	v_mfma_f32_16x16x32_bf16 v[96:99], v[184:187], v[200:203], v[96:99]
	v_mfma_f32_16x16x32_bf16 v[96:99], v[188:191], v[208:211], v[96:99]
	v_mfma_f32_16x16x32_bf16 v[100:103], v[180:183], v[208:211], v[100:103]
	v_mfma_f32_16x16x32_bf16 v[100:103], v[176:179], v[200:203], v[100:103]
	v_mfma_f32_16x16x32_bf16 v[84:87], v[176:179], v[214:217], v[84:87]
	v_mfma_f32_16x16x32_bf16 v[84:87], v[180:183], v[230:233], v[84:87]
	v_mfma_f32_16x16x32_bf16 v[80:83], v[188:191], v[230:233], v[80:83]
	v_mfma_f32_16x16x32_bf16 v[80:83], v[184:187], v[214:217], v[80:83]
	v_mfma_f32_16x16x32_bf16 v[64:67], v[184:187], v[234:237], v[64:67]
	v_mfma_f32_16x16x32_bf16 v[64:67], v[188:191], v[238:241], v[64:67]
	v_mfma_f32_16x16x32_bf16 v[68:71], v[180:183], v[238:241], v[68:71]
	v_mfma_f32_16x16x32_bf16 v[68:71], v[176:179], v[234:237], v[68:71]
	s_setprio 0
	s_barrier
; #define PG8_STAGE(bufoff, gbase, voff) do { _Pragma("unroll") for (int _i = 0; _i < 2; ++_i) \
;         __builtin_amdgcn_global_load_lds((const unsigned*)((const char*)(gbase) + (voff)[_i]), (LAS unsigned*)(lds + (bufoff) + ldsw + _i * 8192), 16, 0, 0); } while (0)
; #define PG8_LDA(dst, b, h) do { _Pragma("unroll") for (int m = 0; m < 4; ++m) _Pragma("unroll") for (int k = 0; k < 2; ++k) dst[m][k] = *(const LAS bf16x8*)(lds + PG8_SA(b, h) + aoff + m * 2048 + k * 1024); } while (0)
; #define PG8_LDB(dst, b, h) do { _Pragma("unroll") for (int n = 0; n < 2; ++n) _Pragma("unroll") for (int k = 0; k < 2; ++k) dst[n][k] = *(const LAS bf16x8*)(lds + PG8_SB(b, h) + boff + n * 2048 + k * 1024); } while (0)
; #define PG8_WAIT_V(n) asm volatile("s_waitcnt vmcnt(" #n ")" ::: "memory")
;     ...
;             PG8_LDA(At, 1, 1); PG8_STAGE(PG8_SB(1, 0), b3, voffB); PG8_STAGE(PG8_SB(1, 1), b3 + hB, voffB); PG8_STAGE(PG8_SA(1, 0), a3, voffA);
;             PG8_WAIT_V(8); PG8_WAIT_L(0); PG8_BAR; PG8_MMA(1, 0, At, B0); PG8_MMA(1, 1, At, B1); PG8_BAR; PG8_SCHED;
;             } else {
;             PG8_LDB(B0, 0, 0); PG8_SCHED; PG8_LDA(At, 0, 0); PG8_STAGE(PG8_SA(1, 1), a1 + hA, voffA);
;             PG8_WAIT_L(8); PG8_BAR; PG8_WAIT_L(0); PG8_MMA(0, 0, At, B0); PG8_BAR; PG8_SCHED;
;             PG8_LDB(B1, 0, 1); PG8_STAGE(PG8_SB(0, 0), b2, voffB);
;             PG8_BAR; PG8_WAIT_L(0); PG8_MMA(0, 1, At, B1); PG8_BAR;
;             PG8_LDA(At, 0, 1); PG8_STAGE(PG8_SA(0, 0), a2, voffA);
;             PG8_BAR; PG8_WAIT_L(0); PG8_MMA(1, 0, At, B0); PG8_BAR; PG8_SCHED;
;             PG8_STAGE(PG8_SB(0, 1), b2 + hB, voffB);
;             PG8_WAIT_V(6); PG8_BAR; PG8_MMA(1, 1, At, B1); PG8_BAR;
;             PG8_LDB(B0, 1, 0); PG8_SCHED; PG8_LDA(At, 1, 0); PG8_STAGE(PG8_SA(0, 1), a2 + hA, voffA);
;             PG8_WAIT_L(8); PG8_BAR; PG8_WAIT_L(0); PG8_MMA(0, 0, At, B0); PG8_BAR; PG8_SCHED;
;             PG8_LDB(B1, 1, 1); PG8_STAGE(PG8_SB(1, 0), b3, voffB);
;             PG8_BAR; PG8_WAIT_L(0); PG8_MMA(0, 1, At, B1); PG8_BAR;
;             PG8_LDA(At, 1, 1); PG8_STAGE(PG8_SA(1, 0), a3, voffA);
;             PG8_BAR; PG8_WAIT_L(0); PG8_MMA(1, 0, At, B0); PG8_BAR; PG8_SCHED;
;             PG8_STAGE(PG8_SB(1, 1), b3 + hB, voffB);
;             PG8_WAIT_V(6); PG8_BAR; PG8_MMA(1, 1, At, B1); PG8_BAR;
;             }
;         }
;         if constexpr (ALIGN_EPI) { if (wr == 0) PG8_BAR; }
	s_add_i32 s8, s8, s81
	s_add_u32 s98, s100, s38
	s_addc_u32 s99, s101, s39
	s_add_u32 s100, s98, s16
	s_addc_u32 s101, s99, 0
	s_mov_b32 m0, s8
	ds_read_b128 v[192:195], v170 offset:49152
	ds_read_b128 v[196:199], v170 offset:50176
	ds_read_b128 v[200:203], v170 offset:51200
	ds_read_b128 v[208:211], v170 offset:52224
	ds_read_b128 v[214:217], v170 offset:53248
	ds_read_b128 v[230:233], v170 offset:54272
	ds_read_b128 v[234:237], v170 offset:55296
	ds_read_b128 v[238:241], v170 offset:56320
	global_load_lds_dwordx4 v156, s[98:99]
	s_add_i32 m0, s8, 0x2000
	s_add_i32 s8, s9, s81
	global_load_lds_dwordx4 v140, s[98:99]
	s_mov_b32 m0, s8
	s_nop 0
	global_load_lds_dwordx4 v156, s[100:101]
	s_add_i32 m0, s8, 0x2000
	s_nop 0
	global_load_lds_dwordx4 v140, s[100:101]
	s_mov_b32 m0, s1
	s_nop 0
	global_load_lds_dwordx4 v136, s[74:75]
	s_mov_b32 m0, s54
	s_nop 0
	global_load_lds_dwordx4 v138, s[74:75]
	s_waitcnt vmcnt(8)
	s_waitcnt lgkmcnt(0)
	s_barrier
	s_setprio 1
	s_waitcnt lgkmcnt(0)
	v_mfma_f32_16x16x32_bf16 v[60:63], v[132:135], v[192:195], v[60:63]
	v_mfma_f32_16x16x32_bf16 v[60:63], v[146:149], v[196:199], v[60:63]
	v_mfma_f32_16x16x32_bf16 v[56:59], v[172:175], v[196:199], v[56:59]
	v_mfma_f32_16x16x32_bf16 v[56:59], v[150:153], v[192:195], v[56:59]
	v_mfma_f32_16x16x32_bf16 v[40:43], v[150:153], v[200:203], v[40:43]
	v_mfma_f32_16x16x32_bf16 v[40:43], v[172:175], v[208:211], v[40:43]
	v_mfma_f32_16x16x32_bf16 v[44:47], v[146:149], v[208:211], v[44:47]
	v_mfma_f32_16x16x32_bf16 v[44:47], v[132:135], v[200:203], v[44:47]
	v_mfma_f32_16x16x32_bf16 v[28:31], v[132:135], v[214:217], v[28:31]
	v_mfma_f32_16x16x32_bf16 v[28:31], v[146:149], v[230:233], v[28:31]
	v_mfma_f32_16x16x32_bf16 v[24:27], v[172:175], v[230:233], v[24:27]
	v_mfma_f32_16x16x32_bf16 v[24:27], v[150:153], v[214:217], v[24:27]
	v_mfma_f32_16x16x32_bf16 v[8:11], v[150:153], v[234:237], v[8:11]
	v_mfma_f32_16x16x32_bf16 v[8:11], v[172:175], v[238:241], v[8:11]
	v_mfma_f32_16x16x32_bf16 v[12:15], v[146:149], v[238:241], v[12:15]
	v_mfma_f32_16x16x32_bf16 v[12:15], v[132:135], v[234:237], v[12:15]
	s_setprio 0
	s_setprio 1
	v_mfma_f32_16x16x32_bf16 v[52:55], v[176:179], v[192:195], v[52:55]
	v_mfma_f32_16x16x32_bf16 v[52:55], v[180:183], v[196:199], v[52:55]
	v_mfma_f32_16x16x32_bf16 v[48:51], v[188:191], v[196:199], v[48:51]
	v_mfma_f32_16x16x32_bf16 v[48:51], v[184:187], v[192:195], v[48:51]
	v_mfma_f32_16x16x32_bf16 v[32:35], v[184:187], v[200:203], v[32:35]
	v_mfma_f32_16x16x32_bf16 v[32:35], v[188:191], v[208:211], v[32:35]
	v_mfma_f32_16x16x32_bf16 v[36:39], v[180:183], v[208:211], v[36:39]
	v_mfma_f32_16x16x32_bf16 v[36:39], v[176:179], v[200:203], v[36:39]
	v_mfma_f32_16x16x32_bf16 v[20:23], v[176:179], v[214:217], v[20:23]
	v_mfma_f32_16x16x32_bf16 v[20:23], v[180:183], v[230:233], v[20:23]
	v_mfma_f32_16x16x32_bf16 v[16:19], v[188:191], v[230:233], v[16:19]
	v_mfma_f32_16x16x32_bf16 v[16:19], v[184:187], v[214:217], v[16:19]
	v_mfma_f32_16x16x32_bf16 v[0:3], v[184:187], v[234:237], v[0:3]
	v_mfma_f32_16x16x32_bf16 v[0:3], v[188:191], v[238:241], v[0:3]
	v_mfma_f32_16x16x32_bf16 v[4:7], v[180:183], v[238:241], v[4:7]
	v_mfma_f32_16x16x32_bf16 v[4:7], v[176:179], v[234:237], v[4:7]
	s_setprio 0
	s_barrier
	s_add_u32 vcc_lo, vcc_lo, 0x100
	s_addc_u32 vcc_hi, vcc_hi, 0
	s_cmp_ge_u32 s6, s4
	s_mov_b32 s74, s6
	s_cbranch_scc0 .LBB0_364
	s_and_b64 vcc, exec, s[30:31]
	s_cbranch_vccz .LBB0_367
	s_barrier

; #define PG8_STAGE(bufoff, gbase, voff) do { _Pragma("unroll") for (int _i = 0; _i < 2; ++_i) \
;         __builtin_amdgcn_global_load_lds((const unsigned*)((const char*)(gbase) + (voff)[_i]), (LAS unsigned*)(lds + (bufoff) + ldsw + _i * 8192), 16, 0, 0); } while (0)
; #define PG8_LDA(dst, b, h) do { _Pragma("unroll") for (int m = 0; m < 4; ++m) _Pragma("unroll") for (int k = 0; k < 2; ++k) dst[m][k] = *(const LAS bf16x8*)(lds + PG8_SA(b, h) + aoff + m * 2048 + k * 1024); } while (0)
; #define PG8_LDB(dst, b, h) do { _Pragma("unroll") for (int n = 0; n < 2; ++n) _Pragma("unroll") for (int k = 0; k < 2; ++k) dst[n][k] = *(const LAS bf16x8*)(lds + PG8_SB(b, h) + boff + n * 2048 + k * 1024); } while (0)
; #define PG8_WAIT_V(n) asm volatile("s_waitcnt vmcnt(" #n ")" ::: "memory")
; #define PG8_WAIT_L(n) asm volatile("s_waitcnt lgkmcnt(" #n ")" ::: "memory")
; #define PG8_BAR __builtin_amdgcn_s_barrier()
; #define PG8_SCHED __builtin_amdgcn_sched_barrier(0)
;     ...
;         for (int t = 0; t < nt; t += 2) {
;             const bool last = (t == nt - 2);
;             const char* a1 = PG8_ATILE(cA, cA2, t + 1);
;             const char* a2 = last ? nA : PG8_ATILE(cA, cA2, t + 2); const char* b2 = last ? nB : cB + (size_t)(t + 2) * 128;
;             const char* a3 = last ? nA + kA1 : PG8_ATILE(cA, cA2, t + 3); const char* b3 = b2 + kB1;
;             if constexpr (SP2) {
;             PG8_LDB(B0, 0, 0); PG8_LDB(B1, 0, 1); PG8_SCHED; PG8_LDA(At, 0, 0); PG8_STAGE(PG8_SA(1, 1), a1 + hA, voffA);
;             PG8_WAIT_V(8); PG8_WAIT_L(0); PG8_BAR; PG8_MMA(0, 0, At, B0); PG8_MMA(0, 1, At, B1); PG8_BAR; PG8_SCHED;
;             PG8_LDA(At, 0, 1); PG8_STAGE(PG8_SB(0, 0), b2, voffB); PG8_STAGE(PG8_SB(0, 1), b2 + hB, voffB); PG8_STAGE(PG8_SA(0, 0), a2, voffA);
;             PG8_WAIT_V(8); PG8_WAIT_L(0); PG8_BAR; PG8_MMA(1, 0, At, B0); PG8_MMA(1, 1, At, B1); PG8_BAR; PG8_SCHED;
;             PG8_LDB(B0, 1, 0); PG8_LDB(B1, 1, 1); PG8_SCHED; PG8_LDA(At, 1, 0); PG8_STAGE(PG8_SA(0, 1), a2 + hA, voffA);
;             PG8_WAIT_V(8); PG8_WAIT_L(0); PG8_BAR; PG8_MMA(0, 0, At, B0); PG8_MMA(0, 1, At, B1); PG8_BAR; PG8_SCHED;
;             PG8_LDA(At, 1, 1); PG8_STAGE(PG8_SB(1, 0), b3, voffB); PG8_STAGE(PG8_SB(1, 1), b3 + hB, voffB); PG8_STAGE(PG8_SA(1, 0), a3, voffA);
;             PG8_WAIT_V(8); PG8_WAIT_L(0); PG8_BAR; PG8_MMA(1, 0, At, B0); PG8_MMA(1, 1, At, B1); PG8_BAR; PG8_SCHED;
.LBB0_406:
	s_add_u32 s42, s30, s34
	s_addc_u32 s43, s31, s35
	s_add_u32 s48, s42, 0x100
	s_addc_u32 s49, s43, 0
	s_add_u32 s44, s74, s34
	s_addc_u32 s45, s75, s35
	s_add_u32 s42, s42, 0x180
	s_addc_u32 s43, s43, 0
	s_add_i32 s77, 0, 0x10000
	s_add_i32 s80, 0, 0x14000
	v_add_u32_e32 v144, s77, v179
	v_add_u32_e32 v178, s80, v179
	ds_read_b128 v[132:135], v144
	ds_read_b128 v[136:139], v144 offset:1024
	ds_read_b128 v[140:143], v144 offset:2048
	ds_read_b128 v[144:147], v144 offset:3072
	ds_read_b128 v[148:151], v178
	ds_read_b128 v[186:189], v178 offset:1024
	ds_read_b128 v[190:193], v178 offset:2048
	ds_read_b128 v[194:197], v178 offset:3072
	s_cmpk_eq_i32 s34, 0x700
	s_cselect_b32 s43, s73, s43
	s_cselect_b32 s42, s72, s42
	s_cselect_b32 s45, s17, s45
	s_cselect_b32 s44, s55, s44
	s_cselect_b32 s49, s3, s49
	s_cselect_b32 s48, s25, s48
	v_lshl_add_u64 v[182:183], v[128:129], 0, s[34:35]
	s_add_i32 m0, s6, 0xc000
	ds_read_b128 v[208:211], v181
	ds_read_b128 v[230:233], v181 offset:1024
	ds_read_b128 v[234:237], v181 offset:2048
	ds_read_b128 v[238:241], v181 offset:3072
	ds_read_b128 v[242:245], v181 offset:4096
	ds_read_b128 v[246:249], v181 offset:5120
	ds_read_b128 v[214:217], v181 offset:6144
	ds_read_b128 v[198:201], v181 offset:7168
	global_load_lds_dwordx4 v[182:183], off
	v_lshl_add_u64 v[182:183], v[130:131], 0, s[34:35]
	s_add_i32 m0, s6, 0xe000
	s_nop 0
	global_load_lds_dwordx4 v[182:183], off
	s_waitcnt vmcnt(8)
	s_waitcnt lgkmcnt(0)
	s_barrier
	s_setprio 1
	s_waitcnt lgkmcnt(0)
	v_mfma_f32_16x16x32_bf16 v[124:127], v[132:135], v[208:211], v[124:127]
	v_mfma_f32_16x16x32_bf16 v[124:127], v[136:139], v[230:233], v[124:127]
	v_mfma_f32_16x16x32_bf16 v[120:123], v[144:147], v[230:233], v[120:123]
	v_mfma_f32_16x16x32_bf16 v[120:123], v[140:143], v[208:211], v[120:123]
	v_mfma_f32_16x16x32_bf16 v[104:107], v[140:143], v[234:237], v[104:107]
	v_mfma_f32_16x16x32_bf16 v[104:107], v[144:147], v[238:241], v[104:107]
	v_mfma_f32_16x16x32_bf16 v[108:111], v[136:139], v[238:241], v[108:111]
	v_mfma_f32_16x16x32_bf16 v[108:111], v[132:135], v[234:237], v[108:111]
	v_mfma_f32_16x16x32_bf16 v[92:95], v[132:135], v[242:245], v[92:95]
	v_mfma_f32_16x16x32_bf16 v[92:95], v[136:139], v[246:249], v[92:95]
	v_mfma_f32_16x16x32_bf16 v[88:91], v[144:147], v[246:249], v[88:91]
	v_mfma_f32_16x16x32_bf16 v[88:91], v[140:143], v[242:245], v[88:91]
	v_mfma_f32_16x16x32_bf16 v[72:75], v[140:143], v[214:217], v[72:75]
	v_mfma_f32_16x16x32_bf16 v[72:75], v[144:147], v[198:201], v[72:75]
	v_mfma_f32_16x16x32_bf16 v[76:79], v[136:139], v[198:201], v[76:79]
	v_mfma_f32_16x16x32_bf16 v[76:79], v[132:135], v[214:217], v[76:79]
	s_setprio 0
	s_setprio 1
	v_mfma_f32_16x16x32_bf16 v[116:119], v[148:151], v[208:211], v[116:119]
	v_mfma_f32_16x16x32_bf16 v[116:119], v[186:189], v[230:233], v[116:119]
	v_mfma_f32_16x16x32_bf16 v[112:115], v[194:197], v[230:233], v[112:115]
	v_mfma_f32_16x16x32_bf16 v[112:115], v[190:193], v[208:211], v[112:115]
	v_mfma_f32_16x16x32_bf16 v[96:99], v[190:193], v[234:237], v[96:99]
	v_mfma_f32_16x16x32_bf16 v[96:99], v[194:197], v[238:241], v[96:99]
	v_mfma_f32_16x16x32_bf16 v[100:103], v[186:189], v[238:241], v[100:103]
	v_mfma_f32_16x16x32_bf16 v[100:103], v[148:151], v[234:237], v[100:103]
	v_mfma_f32_16x16x32_bf16 v[84:87], v[148:151], v[242:245], v[84:87]
	v_mfma_f32_16x16x32_bf16 v[84:87], v[186:189], v[246:249], v[84:87]
	v_mfma_f32_16x16x32_bf16 v[80:83], v[194:197], v[246:249], v[80:83]
	v_mfma_f32_16x16x32_bf16 v[80:83], v[190:193], v[242:245], v[80:83]
	v_mfma_f32_16x16x32_bf16 v[64:67], v[190:193], v[214:217], v[64:67]
	v_mfma_f32_16x16x32_bf16 v[64:67], v[194:197], v[198:201], v[64:67]
	v_mfma_f32_16x16x32_bf16 v[68:71], v[186:189], v[198:201], v[68:71]
	v_mfma_f32_16x16x32_bf16 v[68:71], v[148:151], v[214:217], v[68:71]
	s_setprio 0
	s_barrier
	s_add_i32 s77, s77, s5
	v_lshl_add_u64 v[182:183], s[44:45], 0, v[156:157]
	s_mov_b32 m0, s77
	ds_read_b128 v[198:201], v181 offset:16384
	ds_read_b128 v[208:211], v181 offset:17408
	ds_read_b128 v[214:217], v181 offset:18432
	ds_read_b128 v[230:233], v181 offset:19456
	ds_read_b128 v[234:237], v181 offset:20480
	ds_read_b128 v[238:241], v181 offset:21504
	ds_read_b128 v[242:245], v181 offset:22528
	ds_read_b128 v[246:249], v181 offset:23552
	global_load_lds_dwordx4 v[182:183], off
	s_add_i32 m0, s77, 0x2000
	s_add_u32 s78, s44, 0x40000
	v_lshl_add_u64 v[202:203], s[44:45], 0, v[168:169]
	s_addc_u32 s79, s45, 0
	s_add_i32 s77, s80, s5
	global_load_lds_dwordx4 v[202:203], off
	v_lshl_add_u64 v[204:205], s[78:79], 0, v[156:157]
	s_mov_b32 m0, s77
	s_nop 0
	global_load_lds_dwordx4 v[204:205], off
	v_lshl_add_u64 v[204:205], s[78:79], 0, v[168:169]
	s_add_i32 m0, s77, 0x2000
	s_nop 0
	global_load_lds_dwordx4 v[204:205], off
	v_lshl_add_u64 v[204:205], s[48:49], 0, v[152:153]
	s_mov_b32 m0, s6
	s_nop 0
	global_load_lds_dwordx4 v[204:205], off
	v_lshl_add_u64 v[204:205], s[48:49], 0, v[154:155]
	s_mov_b32 m0, s7
	s_nop 0
	global_load_lds_dwordx4 v[204:205], off
	s_waitcnt vmcnt(8)
	s_waitcnt lgkmcnt(0)
	s_barrier
; #define PG8_STAGE(bufoff, gbase, voff) do { _Pragma("unroll") for (int _i = 0; _i < 2; ++_i) \
;         __builtin_amdgcn_global_load_lds((const unsigned*)((const char*)(gbase) + (voff)[_i]), (LAS unsigned*)(lds + (bufoff) + ldsw + _i * 8192), 16, 0, 0); } while (0)
; #define PG8_LDA(dst, b, h) do { _Pragma("unroll") for (int m = 0; m < 4; ++m) _Pragma("unroll") for (int k = 0; k < 2; ++k) dst[m][k] = *(const LAS bf16x8*)(lds + PG8_SA(b, h) + aoff + m * 2048 + k * 1024); } while (0)
; #define PG8_LDB(dst, b, h) do { _Pragma("unroll") for (int n = 0; n < 2; ++n) _Pragma("unroll") for (int k = 0; k < 2; ++k) dst[n][k] = *(const LAS bf16x8*)(lds + PG8_SB(b, h) + boff + n * 2048 + k * 1024); } while (0)
; #define PG8_MMA(ai, bj, At, Bt) do { __builtin_amdgcn_s_setprio(1); _Pragma("unroll") for (int m = 0; m < 4; ++m) _Pragma("unroll") for (int n = 0; n < 2; ++n) _Pragma("unroll") for (int k = 0; k < 2; ++k) \
;         acc[ai][bj][m][n] = __builtin_amdgcn_mfma_f32_16x16x32_bf16(Bt[n][k], At[m][k], acc[ai][bj][m][n], 0, 0, 0); __builtin_amdgcn_s_setprio(0); } while (0)
; #define PG8_WAIT_V(n) asm volatile("s_waitcnt vmcnt(" #n ")" ::: "memory")
; #define PG8_WAIT_L(n) asm volatile("s_waitcnt lgkmcnt(" #n ")" ::: "memory")
; #define PG8_BAR __builtin_amdgcn_s_barrier()
; #define PG8_SCHED __builtin_amdgcn_sched_barrier(0)
;     ...
;             PG8_WAIT_V(8); PG8_WAIT_L(0); PG8_BAR; PG8_MMA(0, 0, At, B0); PG8_MMA(0, 1, At, B1); PG8_BAR; PG8_SCHED;
;             PG8_LDA(At, 0, 1); PG8_STAGE(PG8_SB(0, 0), b2, voffB); PG8_STAGE(PG8_SB(0, 1), b2 + hB, voffB); PG8_STAGE(PG8_SA(0, 0), a2, voffA);
;             PG8_WAIT_V(8); PG8_WAIT_L(0); PG8_BAR; PG8_MMA(1, 0, At, B0); PG8_MMA(1, 1, At, B1); PG8_BAR; PG8_SCHED;
;             PG8_LDB(B0, 1, 0); PG8_LDB(B1, 1, 1); PG8_SCHED; PG8_LDA(At, 1, 0); PG8_STAGE(PG8_SA(0, 1), a2 + hA, voffA);
;             PG8_WAIT_V(8); PG8_WAIT_L(0); PG8_BAR; PG8_MMA(0, 0, At, B0); PG8_MMA(0, 1, At, B1); PG8_BAR; PG8_SCHED;
;             PG8_LDA(At, 1, 1); PG8_STAGE(PG8_SB(1, 0), b3, voffB); PG8_STAGE(PG8_SB(1, 1), b3 + hB, voffB); PG8_STAGE(PG8_SA(1, 0), a3, voffA);
;             PG8_WAIT_V(8); PG8_WAIT_L(0); PG8_BAR; PG8_MMA(1, 0, At, B0); PG8_MMA(1, 1, At, B1); PG8_BAR; PG8_SCHED;
	s_setprio 1
	s_waitcnt lgkmcnt(0)
	v_mfma_f32_16x16x32_bf16 v[60:63], v[132:135], v[198:201], v[60:63]
	v_mfma_f32_16x16x32_bf16 v[60:63], v[136:139], v[208:211], v[60:63]
	v_mfma_f32_16x16x32_bf16 v[56:59], v[144:147], v[208:211], v[56:59]
	v_mfma_f32_16x16x32_bf16 v[56:59], v[140:143], v[198:201], v[56:59]
	v_mfma_f32_16x16x32_bf16 v[40:43], v[140:143], v[214:217], v[40:43]
	v_mfma_f32_16x16x32_bf16 v[40:43], v[144:147], v[230:233], v[40:43]
	v_mfma_f32_16x16x32_bf16 v[44:47], v[136:139], v[230:233], v[44:47]
	v_mfma_f32_16x16x32_bf16 v[44:47], v[132:135], v[214:217], v[44:47]
	v_mfma_f32_16x16x32_bf16 v[28:31], v[132:135], v[234:237], v[28:31]
	v_mfma_f32_16x16x32_bf16 v[28:31], v[136:139], v[238:241], v[28:31]
	v_mfma_f32_16x16x32_bf16 v[24:27], v[144:147], v[238:241], v[24:27]
	v_mfma_f32_16x16x32_bf16 v[24:27], v[140:143], v[234:237], v[24:27]
	v_mfma_f32_16x16x32_bf16 v[8:11], v[140:143], v[242:245], v[8:11]
	v_mfma_f32_16x16x32_bf16 v[8:11], v[144:147], v[246:249], v[8:11]
	v_mfma_f32_16x16x32_bf16 v[12:15], v[136:139], v[246:249], v[12:15]
	v_mfma_f32_16x16x32_bf16 v[12:15], v[132:135], v[242:245], v[12:15]
	s_setprio 0
	s_setprio 1
	v_mfma_f32_16x16x32_bf16 v[52:55], v[148:151], v[198:201], v[52:55]
	v_mfma_f32_16x16x32_bf16 v[52:55], v[186:189], v[208:211], v[52:55]
	v_mfma_f32_16x16x32_bf16 v[48:51], v[194:197], v[208:211], v[48:51]
	v_mfma_f32_16x16x32_bf16 v[48:51], v[190:193], v[198:201], v[48:51]
	v_mfma_f32_16x16x32_bf16 v[32:35], v[190:193], v[214:217], v[32:35]
	v_mfma_f32_16x16x32_bf16 v[32:35], v[194:197], v[230:233], v[32:35]
	v_mfma_f32_16x16x32_bf16 v[36:39], v[186:189], v[230:233], v[36:39]
	v_mfma_f32_16x16x32_bf16 v[36:39], v[148:151], v[214:217], v[36:39]
	v_mfma_f32_16x16x32_bf16 v[20:23], v[148:151], v[234:237], v[20:23]
	v_mfma_f32_16x16x32_bf16 v[20:23], v[186:189], v[238:241], v[20:23]
	v_mfma_f32_16x16x32_bf16 v[16:19], v[194:197], v[238:241], v[16:19]
	v_mfma_f32_16x16x32_bf16 v[16:19], v[190:193], v[234:237], v[16:19]
	v_mfma_f32_16x16x32_bf16 v[0:3], v[190:193], v[242:245], v[0:3]
	v_mfma_f32_16x16x32_bf16 v[0:3], v[194:197], v[246:249], v[0:3]
	v_mfma_f32_16x16x32_bf16 v[4:7], v[186:189], v[246:249], v[4:7]
	v_mfma_f32_16x16x32_bf16 v[4:7], v[148:151], v[242:245], v[4:7]
	s_setprio 0
	s_barrier
	s_add_i32 s77, 0, 0x18000
	s_add_i32 s78, 0, 0x1c000
	v_add_u32_e32 v144, s77, v179
	v_add_u32_e32 v178, s78, v179
	ds_read_b128 v[132:135], v144
	ds_read_b128 v[136:139], v144 offset:1024
	ds_read_b128 v[140:143], v144 offset:2048
	ds_read_b128 v[144:147], v144 offset:3072
	ds_read_b128 v[148:151], v178
	ds_read_b128 v[186:189], v178 offset:1024
	ds_read_b128 v[190:193], v178 offset:2048
	ds_read_b128 v[194:197], v178 offset:3072
	s_add_u32 s48, s48, 0x40000
	s_addc_u32 s49, s49, 0
	s_mov_b32 m0, s8
	v_lshl_add_u64 v[204:205], s[48:49], 0, v[152:153]
	ds_read_b128 v[198:201], v181 offset:32768
	ds_read_b128 v[208:211], v181 offset:33792
	ds_read_b128 v[214:217], v181 offset:34816
	ds_read_b128 v[230:233], v181 offset:35840
	ds_read_b128 v[234:237], v181 offset:36864
	ds_read_b128 v[238:241], v181 offset:37888
	ds_read_b128 v[242:245], v181 offset:38912
	ds_read_b128 v[246:249], v181 offset:39936
	global_load_lds_dwordx4 v[204:205], off
	v_lshl_add_u64 v[204:205], s[48:49], 0, v[154:155]
	s_mov_b32 m0, s9
	s_nop 0
	global_load_lds_dwordx4 v[204:205], off
	s_waitcnt vmcnt(8)
	s_waitcnt lgkmcnt(0)
	s_barrier
	s_setprio 1
	s_waitcnt lgkmcnt(0)
	v_mfma_f32_16x16x32_bf16 v[124:127], v[132:135], v[198:201], v[124:127]
	v_mfma_f32_16x16x32_bf16 v[124:127], v[136:139], v[208:211], v[124:127]
	v_mfma_f32_16x16x32_bf16 v[120:123], v[144:147], v[208:211], v[120:123]
	v_mfma_f32_16x16x32_bf16 v[120:123], v[140:143], v[198:201], v[120:123]
	v_mfma_f32_16x16x32_bf16 v[104:107], v[140:143], v[214:217], v[104:107]
	v_mfma_f32_16x16x32_bf16 v[104:107], v[144:147], v[230:233], v[104:107]
	v_mfma_f32_16x16x32_bf16 v[108:111], v[136:139], v[230:233], v[108:111]
	v_mfma_f32_16x16x32_bf16 v[108:111], v[132:135], v[214:217], v[108:111]
	v_mfma_f32_16x16x32_bf16 v[92:95], v[132:135], v[234:237], v[92:95]
	v_mfma_f32_16x16x32_bf16 v[92:95], v[136:139], v[238:241], v[92:95]
	v_mfma_f32_16x16x32_bf16 v[88:91], v[144:147], v[238:241], v[88:91]
	v_mfma_f32_16x16x32_bf16 v[88:91], v[140:143], v[234:237], v[88:91]
	v_mfma_f32_16x16x32_bf16 v[72:75], v[140:143], v[242:245], v[72:75]
	v_mfma_f32_16x16x32_bf16 v[72:75], v[144:147], v[246:249], v[72:75]
	v_mfma_f32_16x16x32_bf16 v[76:79], v[136:139], v[246:249], v[76:79]
	v_mfma_f32_16x16x32_bf16 v[76:79], v[132:135], v[242:245], v[76:79]
	s_setprio 0
	s_setprio 1
	v_mfma_f32_16x16x32_bf16 v[116:119], v[148:151], v[198:201], v[116:119]
	v_mfma_f32_16x16x32_bf16 v[116:119], v[186:189], v[208:211], v[116:119]
	v_mfma_f32_16x16x32_bf16 v[112:115], v[194:197], v[208:211], v[112:115]
	v_mfma_f32_16x16x32_bf16 v[112:115], v[190:193], v[198:201], v[112:115]
	v_mfma_f32_16x16x32_bf16 v[96:99], v[190:193], v[214:217], v[96:99]
	v_mfma_f32_16x16x32_bf16 v[96:99], v[194:197], v[230:233], v[96:99]
	v_mfma_f32_16x16x32_bf16 v[100:103], v[186:189], v[230:233], v[100:103]
	v_mfma_f32_16x16x32_bf16 v[100:103], v[148:151], v[214:217], v[100:103]
	v_mfma_f32_16x16x32_bf16 v[84:87], v[148:151], v[234:237], v[84:87]
	v_mfma_f32_16x16x32_bf16 v[84:87], v[186:189], v[238:241], v[84:87]
	v_mfma_f32_16x16x32_bf16 v[80:83], v[194:197], v[238:241], v[80:83]
	v_mfma_f32_16x16x32_bf16 v[80:83], v[190:193], v[234:237], v[80:83]
	v_mfma_f32_16x16x32_bf16 v[64:67], v[190:193], v[242:245], v[64:67]
	v_mfma_f32_16x16x32_bf16 v[64:67], v[194:197], v[246:249], v[64:67]
	v_mfma_f32_16x16x32_bf16 v[68:71], v[186:189], v[246:249], v[68:71]
	v_mfma_f32_16x16x32_bf16 v[68:71], v[148:151], v[242:245], v[68:71]
	s_setprio 0
	s_barrier
; #define PG8_STAGE(bufoff, gbase, voff) do { _Pragma("unroll") for (int _i = 0; _i < 2; ++_i) \
;         __builtin_amdgcn_global_load_lds((const unsigned*)((const char*)(gbase) + (voff)[_i]), (LAS unsigned*)(lds + (bufoff) + ldsw + _i * 8192), 16, 0, 0); } while (0)
; #define PG8_LDA(dst, b, h) do { _Pragma("unroll") for (int m = 0; m < 4; ++m) _Pragma("unroll") for (int k = 0; k < 2; ++k) dst[m][k] = *(const LAS bf16x8*)(lds + PG8_SA(b, h) + aoff + m * 2048 + k * 1024); } while (0)
; #define PG8_LDB(dst, b, h) do { _Pragma("unroll") for (int n = 0; n < 2; ++n) _Pragma("unroll") for (int k = 0; k < 2; ++k) dst[n][k] = *(const LAS bf16x8*)(lds + PG8_SB(b, h) + boff + n * 2048 + k * 1024); } while (0)
; #define PG8_WAIT_V(n) asm volatile("s_waitcnt vmcnt(" #n ")" ::: "memory")
;     ...
;             PG8_LDA(At, 1, 1); PG8_STAGE(PG8_SB(1, 0), b3, voffB); PG8_STAGE(PG8_SB(1, 1), b3 + hB, voffB); PG8_STAGE(PG8_SA(1, 0), a3, voffA);
;             PG8_WAIT_V(8); PG8_WAIT_L(0); PG8_BAR; PG8_MMA(1, 0, At, B0); PG8_MMA(1, 1, At, B1); PG8_BAR; PG8_SCHED;
;             } else {
;             PG8_LDB(B0, 0, 0); PG8_SCHED; PG8_LDA(At, 0, 0); PG8_STAGE(PG8_SA(1, 1), a1 + hA, voffA);
;             PG8_WAIT_L(8); PG8_BAR; PG8_WAIT_L(0); PG8_MMA(0, 0, At, B0); PG8_BAR; PG8_SCHED;
;             PG8_LDB(B1, 0, 1); PG8_STAGE(PG8_SB(0, 0), b2, voffB);
;             PG8_BAR; PG8_WAIT_L(0); PG8_MMA(0, 1, At, B1); PG8_BAR;
;             PG8_LDA(At, 0, 1); PG8_STAGE(PG8_SA(0, 0), a2, voffA);
;             PG8_BAR; PG8_WAIT_L(0); PG8_MMA(1, 0, At, B0); PG8_BAR; PG8_SCHED;
;             PG8_STAGE(PG8_SB(0, 1), b2 + hB, voffB);
;             PG8_WAIT_V(6); PG8_BAR; PG8_MMA(1, 1, At, B1); PG8_BAR;
;             PG8_LDB(B0, 1, 0); PG8_SCHED; PG8_LDA(At, 1, 0); PG8_STAGE(PG8_SA(0, 1), a2 + hA, voffA);
;             PG8_WAIT_L(8); PG8_BAR; PG8_WAIT_L(0); PG8_MMA(0, 0, At, B0); PG8_BAR; PG8_SCHED;
;             PG8_LDB(B1, 1, 1); PG8_STAGE(PG8_SB(1, 0), b3, voffB);
;             PG8_BAR; PG8_WAIT_L(0); PG8_MMA(0, 1, At, B1); PG8_BAR;
;             PG8_LDA(At, 1, 1); PG8_STAGE(PG8_SA(1, 0), a3, voffA);
;             PG8_BAR; PG8_WAIT_L(0); PG8_MMA(1, 0, At, B0); PG8_BAR; PG8_SCHED;
;             PG8_STAGE(PG8_SB(1, 1), b3 + hB, voffB);
;             PG8_WAIT_V(6); PG8_BAR; PG8_MMA(1, 1, At, B1); PG8_BAR;
;             }
;         }
;         if constexpr (ALIGN_EPI) { if (wr == 0) PG8_BAR; }
	s_add_i32 s48, s77, s5
	v_lshl_add_u64 v[182:183], v[182:183], 0, s[38:39]
	s_mov_b32 m0, s48
	ds_read_b128 v[198:201], v181 offset:49152
	ds_read_b128 v[208:211], v181 offset:50176
	ds_read_b128 v[214:217], v181 offset:51200
	ds_read_b128 v[230:233], v181 offset:52224
	ds_read_b128 v[234:237], v181 offset:53248
	ds_read_b128 v[238:241], v181 offset:54272
	ds_read_b128 v[242:245], v181 offset:55296
	ds_read_b128 v[246:249], v181 offset:56320
	global_load_lds_dwordx4 v[182:183], off
	s_add_i32 m0, s48, 0x2000
	s_add_u32 s44, s44, 0x40080
	v_lshl_add_u64 v[182:183], v[202:203], 0, s[38:39]
	s_addc_u32 s45, s45, 0
	s_add_i32 s48, s78, s5
	global_load_lds_dwordx4 v[182:183], off
	v_lshl_add_u64 v[182:183], s[44:45], 0, v[156:157]
	s_mov_b32 m0, s48
	s_nop 0
	global_load_lds_dwordx4 v[182:183], off
	v_lshl_add_u64 v[182:183], s[44:45], 0, v[168:169]
	s_add_i32 m0, s48, 0x2000
	s_nop 0
	global_load_lds_dwordx4 v[182:183], off
	v_lshl_add_u64 v[182:183], s[42:43], 0, v[152:153]
	s_mov_b32 m0, s50
	s_nop 0
	global_load_lds_dwordx4 v[182:183], off
	v_lshl_add_u64 v[182:183], s[42:43], 0, v[154:155]
	s_mov_b32 m0, s51
	s_nop 0
	global_load_lds_dwordx4 v[182:183], off
	s_waitcnt vmcnt(8)
	s_waitcnt lgkmcnt(0)
	s_barrier
	s_setprio 1
	s_waitcnt lgkmcnt(0)
	v_mfma_f32_16x16x32_bf16 v[60:63], v[132:135], v[198:201], v[60:63]
	v_mfma_f32_16x16x32_bf16 v[60:63], v[136:139], v[208:211], v[60:63]
	v_mfma_f32_16x16x32_bf16 v[56:59], v[144:147], v[208:211], v[56:59]
	v_mfma_f32_16x16x32_bf16 v[56:59], v[140:143], v[198:201], v[56:59]
	v_mfma_f32_16x16x32_bf16 v[40:43], v[140:143], v[214:217], v[40:43]
	v_mfma_f32_16x16x32_bf16 v[40:43], v[144:147], v[230:233], v[40:43]
	v_mfma_f32_16x16x32_bf16 v[44:47], v[136:139], v[230:233], v[44:47]
	v_mfma_f32_16x16x32_bf16 v[44:47], v[132:135], v[214:217], v[44:47]
	v_mfma_f32_16x16x32_bf16 v[28:31], v[132:135], v[234:237], v[28:31]
	v_mfma_f32_16x16x32_bf16 v[28:31], v[136:139], v[238:241], v[28:31]
	v_mfma_f32_16x16x32_bf16 v[24:27], v[144:147], v[238:241], v[24:27]
	v_mfma_f32_16x16x32_bf16 v[24:27], v[140:143], v[234:237], v[24:27]
	v_mfma_f32_16x16x32_bf16 v[8:11], v[140:143], v[242:245], v[8:11]
	v_mfma_f32_16x16x32_bf16 v[8:11], v[144:147], v[246:249], v[8:11]
	v_mfma_f32_16x16x32_bf16 v[12:15], v[136:139], v[246:249], v[12:15]
	v_mfma_f32_16x16x32_bf16 v[12:15], v[132:135], v[242:245], v[12:15]
	s_setprio 0
	s_setprio 1
	v_mfma_f32_16x16x32_bf16 v[52:55], v[148:151], v[198:201], v[52:55]
	v_mfma_f32_16x16x32_bf16 v[52:55], v[186:189], v[208:211], v[52:55]
	v_mfma_f32_16x16x32_bf16 v[48:51], v[194:197], v[208:211], v[48:51]
	v_mfma_f32_16x16x32_bf16 v[48:51], v[190:193], v[198:201], v[48:51]
	v_mfma_f32_16x16x32_bf16 v[32:35], v[190:193], v[214:217], v[32:35]
	v_mfma_f32_16x16x32_bf16 v[32:35], v[194:197], v[230:233], v[32:35]
	v_mfma_f32_16x16x32_bf16 v[36:39], v[186:189], v[230:233], v[36:39]
	v_mfma_f32_16x16x32_bf16 v[36:39], v[148:151], v[214:217], v[36:39]
	v_mfma_f32_16x16x32_bf16 v[20:23], v[148:151], v[234:237], v[20:23]
	v_mfma_f32_16x16x32_bf16 v[20:23], v[186:189], v[238:241], v[20:23]
	v_mfma_f32_16x16x32_bf16 v[16:19], v[194:197], v[238:241], v[16:19]
	v_mfma_f32_16x16x32_bf16 v[16:19], v[190:193], v[234:237], v[16:19]
	v_mfma_f32_16x16x32_bf16 v[0:3], v[190:193], v[242:245], v[0:3]
	v_mfma_f32_16x16x32_bf16 v[0:3], v[194:197], v[246:249], v[0:3]
	v_mfma_f32_16x16x32_bf16 v[4:7], v[186:189], v[246:249], v[4:7]
	v_mfma_f32_16x16x32_bf16 v[4:7], v[148:151], v[242:245], v[4:7]
	s_setprio 0
	s_barrier
	s_add_i32 s76, s76, 2
	s_add_u32 s34, s34, 0x100
	s_addc_u32 s35, s35, 0
	s_cmp_gt_u32 s76, 13
	s_cbranch_scc0 .LBB0_406
	s_and_b64 vcc, exec, s[14:15]
	s_cbranch_vccz .LBB0_409
	s_barrier
